# v2 + removed the redundant s_waitcnt lgkmcnt(0) after the barrier at the head of each GEMM MFMA segment (already waited before the barrier)
# speedup vs baseline: 1.0217x; 1.0217x over previous
.LBB0_102:
	ds_read_b128 v[104:107], v165
	ds_read_b128 v[108:111], v165 offset:1024
	ds_read_b128 v[136:139], v165 offset:2048
	ds_read_b128 v[158:161], v165 offset:3072
	ds_read_b128 v[168:171], v166
	ds_read_b128 v[172:175], v166 offset:1024
	ds_read_b128 v[176:179], v166 offset:2048
	ds_read_b128 v[180:183], v166 offset:3072
	s_add_u32 s2, s36, 0xfff80080
	s_addc_u32 s3, s37, -1
	s_cmp_eq_u32 s56, 28
	s_cselect_b32 s39, s7, s3
	s_cselect_b32 s38, s27, s2
	s_cselect_b32 s3, s23, s55
	s_cselect_b32 s2, s35, s54
	v_lshl_add_u64 v[218:219], s[36:37], 0, v[150:151]
	s_add_i32 m0, s25, 0xc000
	ds_read_b128 v[186:189], v167
	ds_read_b128 v[190:193], v167 offset:1024
	ds_read_b128 v[194:197], v167 offset:2048
	ds_read_b128 v[198:201], v167 offset:3072
	ds_read_b128 v[202:205], v167 offset:4096
	ds_read_b128 v[206:209], v167 offset:5120
	ds_read_b128 v[210:213], v167 offset:6144
	ds_read_b128 v[214:217], v167 offset:7168
	global_load_lds_dwordx4 v[218:219], off
	v_lshl_add_u64 v[218:219], s[36:37], 0, v[152:153]
	s_add_i32 m0, s25, 0xe000
	s_nop 0
	global_load_lds_dwordx4 v[218:219], off
	s_waitcnt vmcnt(8)
	s_waitcnt lgkmcnt(0)
	s_barrier
	s_setprio 1
	v_mfma_f32_16x16x32_bf16 v[132:135], v[104:107], v[186:189], v[132:135]
	v_mfma_f32_16x16x32_bf16 v[128:131], v[136:139], v[186:189], v[128:131]
	v_mfma_f32_16x16x32_bf16 v[124:127], v[104:107], v[194:197], v[124:127]
	v_mfma_f32_16x16x32_bf16 v[120:123], v[136:139], v[194:197], v[120:123]
	v_mfma_f32_16x16x32_bf16 v[116:119], v[104:107], v[202:205], v[116:119]
	v_mfma_f32_16x16x32_bf16 v[112:115], v[136:139], v[202:205], v[112:115]
	v_mfma_f32_16x16x32_bf16 v[100:103], v[104:107], v[210:213], v[100:103]
	v_mfma_f32_16x16x32_bf16 v[96:99], v[136:139], v[210:213], v[96:99]
	v_mfma_f32_16x16x32_bf16 v[132:135], v[108:111], v[190:193], v[132:135]
	v_mfma_f32_16x16x32_bf16 v[128:131], v[158:161], v[190:193], v[128:131]
	v_mfma_f32_16x16x32_bf16 v[124:127], v[108:111], v[198:201], v[124:127]
	v_mfma_f32_16x16x32_bf16 v[120:123], v[158:161], v[198:201], v[120:123]
	v_mfma_f32_16x16x32_bf16 v[116:119], v[108:111], v[206:209], v[116:119]
	v_mfma_f32_16x16x32_bf16 v[112:115], v[158:161], v[206:209], v[112:115]
	v_mfma_f32_16x16x32_bf16 v[100:103], v[108:111], v[214:217], v[100:103]
	v_mfma_f32_16x16x32_bf16 v[96:99], v[158:161], v[214:217], v[96:99]
	s_setprio 0
	s_setprio 1
	v_mfma_f32_16x16x32_bf16 v[60:63], v[168:171], v[186:189], v[60:63]
	v_mfma_f32_16x16x32_bf16 v[56:59], v[176:179], v[186:189], v[56:59]
	v_mfma_f32_16x16x32_bf16 v[52:55], v[168:171], v[194:197], v[52:55]
	v_mfma_f32_16x16x32_bf16 v[48:51], v[176:179], v[194:197], v[48:51]
	v_mfma_f32_16x16x32_bf16 v[44:47], v[168:171], v[202:205], v[44:47]
	v_mfma_f32_16x16x32_bf16 v[40:43], v[176:179], v[202:205], v[40:43]
	v_mfma_f32_16x16x32_bf16 v[36:39], v[168:171], v[210:213], v[36:39]
	v_mfma_f32_16x16x32_bf16 v[32:35], v[176:179], v[210:213], v[32:35]
	v_mfma_f32_16x16x32_bf16 v[60:63], v[172:175], v[190:193], v[60:63]
	v_mfma_f32_16x16x32_bf16 v[56:59], v[180:183], v[190:193], v[56:59]
	v_mfma_f32_16x16x32_bf16 v[52:55], v[172:175], v[198:201], v[52:55]
	v_mfma_f32_16x16x32_bf16 v[48:51], v[180:183], v[198:201], v[48:51]
	v_mfma_f32_16x16x32_bf16 v[44:47], v[172:175], v[206:209], v[44:47]
	v_mfma_f32_16x16x32_bf16 v[40:43], v[180:183], v[206:209], v[40:43]
	v_mfma_f32_16x16x32_bf16 v[36:39], v[172:175], v[214:217], v[36:39]
	v_mfma_f32_16x16x32_bf16 v[32:35], v[180:183], v[214:217], v[32:35]
	s_setprio 0
	s_barrier
	s_add_i32 s57, s51, s19
	v_lshl_add_u64 v[218:219], s[2:3], 0, v[142:143]
	s_mov_b32 m0, s57
	ds_read_b128 v[186:189], v167 offset:16384
	ds_read_b128 v[190:193], v167 offset:17408
	ds_read_b128 v[194:197], v167 offset:18432
	ds_read_b128 v[198:201], v167 offset:19456
	ds_read_b128 v[202:205], v167 offset:20480
	ds_read_b128 v[206:209], v167 offset:21504
	ds_read_b128 v[210:213], v167 offset:22528
	ds_read_b128 v[214:217], v167 offset:23552
	global_load_lds_dwordx4 v[218:219], off
	s_add_i32 m0, s57, 0x2000
	s_add_u32 s62, s2, 0x80000
	v_lshl_add_u64 v[220:221], s[2:3], 0, v[146:147]
	s_addc_u32 s63, s3, 0
	s_add_i32 s57, s52, s19
	global_load_lds_dwordx4 v[220:221], off
	v_lshl_add_u64 v[222:223], s[62:63], 0, v[142:143]
	s_mov_b32 m0, s57
	v_lshl_add_u64 v[224:225], s[38:39], 0, v[144:145]
	global_load_lds_dwordx4 v[222:223], off
	v_lshl_add_u64 v[222:223], s[62:63], 0, v[146:147]
	s_add_i32 m0, s57, 0x2000
	s_nop 0
	global_load_lds_dwordx4 v[222:223], off
	v_lshl_add_u64 v[222:223], s[38:39], 0, v[140:141]
	s_mov_b32 m0, s25
	s_nop 0
	global_load_lds_dwordx4 v[222:223], off
	s_mov_b32 m0, s40
	s_nop 0
	global_load_lds_dwordx4 v[224:225], off
	s_waitcnt vmcnt(8)
	s_waitcnt lgkmcnt(0)
	s_barrier
	s_setprio 1
	v_mfma_f32_16x16x32_bf16 v[92:95], v[104:107], v[186:189], v[92:95]
	v_mfma_f32_16x16x32_bf16 v[88:91], v[136:139], v[186:189], v[88:91]
	v_mfma_f32_16x16x32_bf16 v[84:87], v[104:107], v[194:197], v[84:87]
	v_mfma_f32_16x16x32_bf16 v[80:83], v[136:139], v[194:197], v[80:83]
	v_mfma_f32_16x16x32_bf16 v[76:79], v[104:107], v[202:205], v[76:79]
	v_mfma_f32_16x16x32_bf16 v[72:75], v[136:139], v[202:205], v[72:75]
	v_mfma_f32_16x16x32_bf16 v[68:71], v[104:107], v[210:213], v[68:71]
	v_mfma_f32_16x16x32_bf16 v[64:67], v[136:139], v[210:213], v[64:67]
	v_mfma_f32_16x16x32_bf16 v[92:95], v[108:111], v[190:193], v[92:95]
	v_mfma_f32_16x16x32_bf16 v[88:91], v[158:161], v[190:193], v[88:91]
	v_mfma_f32_16x16x32_bf16 v[84:87], v[108:111], v[198:201], v[84:87]
	v_mfma_f32_16x16x32_bf16 v[80:83], v[158:161], v[198:201], v[80:83]
	v_mfma_f32_16x16x32_bf16 v[76:79], v[108:111], v[206:209], v[76:79]
	v_mfma_f32_16x16x32_bf16 v[72:75], v[158:161], v[206:209], v[72:75]
	v_mfma_f32_16x16x32_bf16 v[68:71], v[108:111], v[214:217], v[68:71]
	v_mfma_f32_16x16x32_bf16 v[64:67], v[158:161], v[214:217], v[64:67]
	s_setprio 0
	s_setprio 1
	v_mfma_f32_16x16x32_bf16 v[28:31], v[168:171], v[186:189], v[28:31]
	v_mfma_f32_16x16x32_bf16 v[24:27], v[176:179], v[186:189], v[24:27]
	v_mfma_f32_16x16x32_bf16 v[20:23], v[168:171], v[194:197], v[20:23]
	v_mfma_f32_16x16x32_bf16 v[16:19], v[176:179], v[194:197], v[16:19]
	v_mfma_f32_16x16x32_bf16 v[12:15], v[168:171], v[202:205], v[12:15]
	v_mfma_f32_16x16x32_bf16 v[8:11], v[176:179], v[202:205], v[8:11]
	v_mfma_f32_16x16x32_bf16 v[4:7], v[168:171], v[210:213], v[4:7]
	v_mfma_f32_16x16x32_bf16 v[0:3], v[176:179], v[210:213], v[0:3]
	v_mfma_f32_16x16x32_bf16 v[28:31], v[172:175], v[190:193], v[28:31]
	v_mfma_f32_16x16x32_bf16 v[24:27], v[180:183], v[190:193], v[24:27]
	v_mfma_f32_16x16x32_bf16 v[20:23], v[172:175], v[198:201], v[20:23]
	v_mfma_f32_16x16x32_bf16 v[16:19], v[180:183], v[198:201], v[16:19]
	v_mfma_f32_16x16x32_bf16 v[12:15], v[172:175], v[206:209], v[12:15]
	v_mfma_f32_16x16x32_bf16 v[8:11], v[180:183], v[206:209], v[8:11]
	v_mfma_f32_16x16x32_bf16 v[4:7], v[172:175], v[214:217], v[4:7]
	v_mfma_f32_16x16x32_bf16 v[0:3], v[180:183], v[214:217], v[0:3]
	s_setprio 0
	s_barrier
	s_add_i32 s57, 0, 0x18000
	v_add_u32_e32 v148, s57, v164
	s_add_i32 s61, 0, 0x1c000
	ds_read_b128 v[104:107], v148
	ds_read_b128 v[108:111], v148 offset:1024
	ds_read_b128 v[136:139], v148 offset:2048
	ds_read_b128 v[158:161], v148 offset:3072
	v_add_u32_e32 v148, s61, v164
	ds_read_b128 v[168:171], v148
	ds_read_b128 v[172:175], v148 offset:1024
	ds_read_b128 v[176:179], v148 offset:2048
	ds_read_b128 v[180:183], v148 offset:3072
	s_add_u32 s38, s38, 0x80000
	s_addc_u32 s39, s39, 0
	s_mov_b32 m0, s41
	v_lshl_add_u64 v[226:227], s[38:39], 0, v[140:141]
	ds_read_b128 v[186:189], v167 offset:32768
	ds_read_b128 v[190:193], v167 offset:33792
	ds_read_b128 v[194:197], v167 offset:34816
	ds_read_b128 v[198:201], v167 offset:35840
	ds_read_b128 v[202:205], v167 offset:36864
	ds_read_b128 v[206:209], v167 offset:37888
	ds_read_b128 v[210:213], v167 offset:38912
	ds_read_b128 v[214:217], v167 offset:39936
	global_load_lds_dwordx4 v[226:227], off
	v_lshl_add_u64 v[226:227], s[38:39], 0, v[144:145]
	s_mov_b32 m0, s42
	s_nop 0
	global_load_lds_dwordx4 v[226:227], off
	s_waitcnt vmcnt(8)
	s_waitcnt lgkmcnt(0)
	s_barrier
	s_setprio 1
	v_mfma_f32_16x16x32_bf16 v[132:135], v[104:107], v[186:189], v[132:135]
	v_mfma_f32_16x16x32_bf16 v[128:131], v[136:139], v[186:189], v[128:131]
	v_mfma_f32_16x16x32_bf16 v[124:127], v[104:107], v[194:197], v[124:127]
	v_mfma_f32_16x16x32_bf16 v[120:123], v[136:139], v[194:197], v[120:123]
	v_mfma_f32_16x16x32_bf16 v[116:119], v[104:107], v[202:205], v[116:119]
	v_mfma_f32_16x16x32_bf16 v[112:115], v[136:139], v[202:205], v[112:115]
	v_mfma_f32_16x16x32_bf16 v[100:103], v[104:107], v[210:213], v[100:103]
	v_mfma_f32_16x16x32_bf16 v[96:99], v[136:139], v[210:213], v[96:99]
	v_mfma_f32_16x16x32_bf16 v[132:135], v[108:111], v[190:193], v[132:135]
	v_mfma_f32_16x16x32_bf16 v[128:131], v[158:161], v[190:193], v[128:131]
	v_mfma_f32_16x16x32_bf16 v[124:127], v[108:111], v[198:201], v[124:127]
	v_mfma_f32_16x16x32_bf16 v[120:123], v[158:161], v[198:201], v[120:123]
	v_mfma_f32_16x16x32_bf16 v[116:119], v[108:111], v[206:209], v[116:119]
	v_mfma_f32_16x16x32_bf16 v[112:115], v[158:161], v[206:209], v[112:115]
	v_mfma_f32_16x16x32_bf16 v[100:103], v[108:111], v[214:217], v[100:103]
	v_mfma_f32_16x16x32_bf16 v[96:99], v[158:161], v[214:217], v[96:99]
	s_setprio 0
	s_setprio 1
	v_mfma_f32_16x16x32_bf16 v[60:63], v[168:171], v[186:189], v[60:63]
	v_mfma_f32_16x16x32_bf16 v[56:59], v[176:179], v[186:189], v[56:59]
	v_mfma_f32_16x16x32_bf16 v[52:55], v[168:171], v[194:197], v[52:55]
	v_mfma_f32_16x16x32_bf16 v[48:51], v[176:179], v[194:197], v[48:51]
	v_mfma_f32_16x16x32_bf16 v[44:47], v[168:171], v[202:205], v[44:47]
	v_mfma_f32_16x16x32_bf16 v[40:43], v[176:179], v[202:205], v[40:43]
	v_mfma_f32_16x16x32_bf16 v[36:39], v[168:171], v[210:213], v[36:39]
	v_mfma_f32_16x16x32_bf16 v[32:35], v[176:179], v[210:213], v[32:35]
	v_mfma_f32_16x16x32_bf16 v[60:63], v[172:175], v[190:193], v[60:63]
	v_mfma_f32_16x16x32_bf16 v[56:59], v[180:183], v[190:193], v[56:59]
	v_mfma_f32_16x16x32_bf16 v[52:55], v[172:175], v[198:201], v[52:55]
	v_mfma_f32_16x16x32_bf16 v[48:51], v[180:183], v[198:201], v[48:51]
	v_mfma_f32_16x16x32_bf16 v[44:47], v[172:175], v[206:209], v[44:47]
	v_mfma_f32_16x16x32_bf16 v[40:43], v[180:183], v[206:209], v[40:43]
	v_mfma_f32_16x16x32_bf16 v[36:39], v[172:175], v[214:217], v[36:39]
	v_mfma_f32_16x16x32_bf16 v[32:35], v[180:183], v[214:217], v[32:35]
	s_setprio 0
	s_barrier
	s_add_i32 s38, s57, s19
	v_lshl_add_u64 v[218:219], v[218:219], 0, s[12:13]
	s_mov_b32 m0, s38
	ds_read_b128 v[186:189], v167 offset:49152
	ds_read_b128 v[190:193], v167 offset:50176
	ds_read_b128 v[194:197], v167 offset:51200
	ds_read_b128 v[198:201], v167 offset:52224
	ds_read_b128 v[202:205], v167 offset:53248
	ds_read_b128 v[206:209], v167 offset:54272
	ds_read_b128 v[210:213], v167 offset:55296
	ds_read_b128 v[214:217], v167 offset:56320
	global_load_lds_dwordx4 v[218:219], off
	s_add_i32 m0, s38, 0x2000
	s_add_u32 s2, s2, 0x80080
	v_lshl_add_u64 v[218:219], v[220:221], 0, s[12:13]
	s_addc_u32 s3, s3, 0
	s_add_i32 s38, s61, s19
	global_load_lds_dwordx4 v[218:219], off
	v_lshl_add_u64 v[218:219], s[2:3], 0, v[142:143]
	s_mov_b32 m0, s38
	s_nop 0
	global_load_lds_dwordx4 v[218:219], off
	v_lshl_add_u64 v[218:219], s[2:3], 0, v[146:147]
	s_add_i32 m0, s38, 0x2000
	s_nop 0
	global_load_lds_dwordx4 v[218:219], off
	v_lshl_add_u64 v[218:219], v[222:223], 0, s[12:13]
	s_mov_b32 m0, s46
	s_nop 0
	global_load_lds_dwordx4 v[218:219], off
	v_lshl_add_u64 v[218:219], v[224:225], 0, s[12:13]
	s_mov_b32 m0, s47
	s_nop 0
	global_load_lds_dwordx4 v[218:219], off
	s_waitcnt vmcnt(8)
	s_waitcnt lgkmcnt(0)
	s_barrier
	s_setprio 1
	v_mfma_f32_16x16x32_bf16 v[92:95], v[104:107], v[186:189], v[92:95]
	v_mfma_f32_16x16x32_bf16 v[88:91], v[136:139], v[186:189], v[88:91]
	v_mfma_f32_16x16x32_bf16 v[84:87], v[104:107], v[194:197], v[84:87]
	v_mfma_f32_16x16x32_bf16 v[80:83], v[136:139], v[194:197], v[80:83]
	v_mfma_f32_16x16x32_bf16 v[76:79], v[104:107], v[202:205], v[76:79]
	v_mfma_f32_16x16x32_bf16 v[72:75], v[136:139], v[202:205], v[72:75]
	v_mfma_f32_16x16x32_bf16 v[68:71], v[104:107], v[210:213], v[68:71]
	v_mfma_f32_16x16x32_bf16 v[64:67], v[136:139], v[210:213], v[64:67]
	v_mfma_f32_16x16x32_bf16 v[92:95], v[108:111], v[190:193], v[92:95]
	v_mfma_f32_16x16x32_bf16 v[88:91], v[158:161], v[190:193], v[88:91]
	v_mfma_f32_16x16x32_bf16 v[84:87], v[108:111], v[198:201], v[84:87]
	v_mfma_f32_16x16x32_bf16 v[80:83], v[158:161], v[198:201], v[80:83]
	v_mfma_f32_16x16x32_bf16 v[76:79], v[108:111], v[206:209], v[76:79]
	v_mfma_f32_16x16x32_bf16 v[72:75], v[158:161], v[206:209], v[72:75]
	v_mfma_f32_16x16x32_bf16 v[68:71], v[108:111], v[214:217], v[68:71]
	v_mfma_f32_16x16x32_bf16 v[64:67], v[158:161], v[214:217], v[64:67]
	s_setprio 0
	s_setprio 1
	v_mfma_f32_16x16x32_bf16 v[28:31], v[168:171], v[186:189], v[28:31]
	v_mfma_f32_16x16x32_bf16 v[24:27], v[176:179], v[186:189], v[24:27]
	v_mfma_f32_16x16x32_bf16 v[20:23], v[168:171], v[194:197], v[20:23]
	v_mfma_f32_16x16x32_bf16 v[16:19], v[176:179], v[194:197], v[16:19]
	v_mfma_f32_16x16x32_bf16 v[12:15], v[168:171], v[202:205], v[12:15]
	v_mfma_f32_16x16x32_bf16 v[8:11], v[176:179], v[202:205], v[8:11]
	v_mfma_f32_16x16x32_bf16 v[4:7], v[168:171], v[210:213], v[4:7]
	v_mfma_f32_16x16x32_bf16 v[0:3], v[176:179], v[210:213], v[0:3]
	v_mfma_f32_16x16x32_bf16 v[28:31], v[172:175], v[190:193], v[28:31]
	v_mfma_f32_16x16x32_bf16 v[24:27], v[180:183], v[190:193], v[24:27]
	v_mfma_f32_16x16x32_bf16 v[20:23], v[172:175], v[198:201], v[20:23]
	v_mfma_f32_16x16x32_bf16 v[16:19], v[180:183], v[198:201], v[16:19]
	v_mfma_f32_16x16x32_bf16 v[12:15], v[172:175], v[206:209], v[12:15]
	v_mfma_f32_16x16x32_bf16 v[8:11], v[180:183], v[206:209], v[8:11]
	v_mfma_f32_16x16x32_bf16 v[4:7], v[172:175], v[214:217], v[4:7]
	v_mfma_f32_16x16x32_bf16 v[0:3], v[180:183], v[214:217], v[0:3]
	s_setprio 0
	s_barrier
	s_add_i32 s56, s56, 2
	s_add_u32 s36, s36, 0x100
	s_addc_u32 s37, s37, 0
	s_add_u32 s54, s54, 0x100
	s_addc_u32 s55, s55, 0
	s_cmp_gt_u32 s56, 29
	s_cbranch_scc0 .LBB0_102
	s_and_b64 vcc, exec, s[20:21]
	s_cbranch_vccz .LBB0_105
	s_barrier

.LBB0_315:
	s_add_u32 s50, s40, s44
	s_addc_u32 s51, s41, s45
	s_add_u32 s48, s50, 0x100
	s_addc_u32 s49, s51, 0
	s_and_b64 s[46:47], s[42:43], exec
	s_cselect_b32 s47, s31, s49
	s_cselect_b32 s46, s30, s48
	s_add_u32 s44, s38, s44
	s_addc_u32 s45, s39, s45
	s_add_u32 s44, s44, 0x100
	s_addc_u32 s45, s45, 0
	s_and_b64 s[42:43], s[42:43], exec
	s_cselect_b32 s49, s27, s45
	s_cselect_b32 s48, s29, s44
	s_add_u32 s52, s50, 0x80080
	ds_read_b128 v[104:107], v193
	ds_read_b128 v[108:111], v193 offset:1024
	ds_read_b128 v[112:115], v193 offset:2048
	ds_read_b128 v[154:157], v193 offset:3072
	ds_read_b128 v[158:161], v194
	ds_read_b128 v[162:165], v194 offset:1024
	ds_read_b128 v[166:169], v194 offset:2048
	ds_read_b128 v[170:173], v194 offset:3072
	s_addc_u32 s53, s51, 0
	s_add_i32 s79, s64, s3
	s_add_i32 m0, s23, 0xc000
	s_add_i32 s80, s23, 0xe000
	s_add_i32 s76, s79, 0x2000
	s_add_u32 s50, s48, 0x10000
	s_addc_u32 s51, s49, 0
	s_add_i32 s78, s65, s3
	s_add_i32 s77, s78, 0x2000
	s_add_i32 s73, 0, 0x18000
	s_add_i32 s72, 0, 0x1c000
	s_add_u32 s44, s46, 0x80000
	s_addc_u32 s45, s47, 0
	s_add_i32 s71, s73, s3
	s_add_i32 s69, s71, 0x2000
	s_add_u32 s42, s48, 0x10080
	s_addc_u32 s43, s49, 0
	s_add_i32 s70, s72, s3
	s_add_i32 s68, s70, 0x2000
	v_lshl_add_u64 v[182:183], s[52:53], 0, v[140:141]
	ds_read_b128 v[174:177], v195
	ds_read_b128 v[178:181], v195 offset:1024
	ds_read_b128 v[186:189], v195 offset:2048
	ds_read_b128 v[196:199], v195 offset:3072
	ds_read_b128 v[200:203], v195 offset:4096
	ds_read_b128 v[204:207], v195 offset:5120
	ds_read_b128 v[208:211], v195 offset:6144
	ds_read_b128 v[212:215], v195 offset:7168
	global_load_lds_dwordx4 v[182:183], off
	v_lshl_add_u64 v[182:183], s[52:53], 0, v[144:145]
	s_mov_b32 m0, s80
	s_nop 0
	global_load_lds_dwordx4 v[182:183], off
	s_waitcnt vmcnt(8)
	s_waitcnt lgkmcnt(0)
	s_barrier
	s_setprio 1
	v_mfma_f32_16x16x32_bf16 v[136:139], v[104:107], v[174:177], v[136:139]
	v_mfma_f32_16x16x32_bf16 v[60:63], v[112:115], v[174:177], v[60:63]
	v_mfma_f32_16x16x32_bf16 v[128:131], v[104:107], v[186:189], v[128:131]
	v_mfma_f32_16x16x32_bf16 v[52:55], v[112:115], v[186:189], v[52:55]
	v_mfma_f32_16x16x32_bf16 v[120:123], v[104:107], v[200:203], v[120:123]
	v_mfma_f32_16x16x32_bf16 v[44:47], v[112:115], v[200:203], v[44:47]
	v_mfma_f32_16x16x32_bf16 v[100:103], v[104:107], v[208:211], v[100:103]
	v_mfma_f32_16x16x32_bf16 v[36:39], v[112:115], v[208:211], v[36:39]
	v_mfma_f32_16x16x32_bf16 v[136:139], v[108:111], v[178:181], v[136:139]
	v_mfma_f32_16x16x32_bf16 v[60:63], v[154:157], v[178:181], v[60:63]
	v_mfma_f32_16x16x32_bf16 v[128:131], v[108:111], v[196:199], v[128:131]
	v_mfma_f32_16x16x32_bf16 v[52:55], v[154:157], v[196:199], v[52:55]
	v_mfma_f32_16x16x32_bf16 v[120:123], v[108:111], v[204:207], v[120:123]
	v_mfma_f32_16x16x32_bf16 v[44:47], v[154:157], v[204:207], v[44:47]
	v_mfma_f32_16x16x32_bf16 v[100:103], v[108:111], v[212:215], v[100:103]
	v_mfma_f32_16x16x32_bf16 v[36:39], v[154:157], v[212:215], v[36:39]
	s_setprio 0
	s_setprio 1
	v_mfma_f32_16x16x32_bf16 v[132:135], v[158:161], v[174:177], v[132:135]
	v_mfma_f32_16x16x32_bf16 v[56:59], v[166:169], v[174:177], v[56:59]
	v_mfma_f32_16x16x32_bf16 v[124:127], v[158:161], v[186:189], v[124:127]
	v_mfma_f32_16x16x32_bf16 v[48:51], v[166:169], v[186:189], v[48:51]
	v_mfma_f32_16x16x32_bf16 v[116:119], v[158:161], v[200:203], v[116:119]
	v_mfma_f32_16x16x32_bf16 v[40:43], v[166:169], v[200:203], v[40:43]
	v_mfma_f32_16x16x32_bf16 v[96:99], v[158:161], v[208:211], v[96:99]
	v_mfma_f32_16x16x32_bf16 v[32:35], v[166:169], v[208:211], v[32:35]
	v_mfma_f32_16x16x32_bf16 v[132:135], v[162:165], v[178:181], v[132:135]
	v_mfma_f32_16x16x32_bf16 v[56:59], v[170:173], v[178:181], v[56:59]
	v_mfma_f32_16x16x32_bf16 v[124:127], v[162:165], v[196:199], v[124:127]
	v_mfma_f32_16x16x32_bf16 v[48:51], v[170:173], v[196:199], v[48:51]
	v_mfma_f32_16x16x32_bf16 v[116:119], v[162:165], v[204:207], v[116:119]
	v_mfma_f32_16x16x32_bf16 v[40:43], v[170:173], v[204:207], v[40:43]
	v_mfma_f32_16x16x32_bf16 v[96:99], v[162:165], v[212:215], v[96:99]
	v_mfma_f32_16x16x32_bf16 v[32:35], v[170:173], v[212:215], v[32:35]
	s_setprio 0
	s_barrier
	s_mov_b32 m0, s79
	v_lshl_add_u64 v[182:183], s[48:49], 0, v[142:143]
	ds_read_b128 v[174:177], v195 offset:16384
	ds_read_b128 v[178:181], v195 offset:17408
	ds_read_b128 v[186:189], v195 offset:18432
	ds_read_b128 v[196:199], v195 offset:19456
	ds_read_b128 v[200:203], v195 offset:20480
	ds_read_b128 v[204:207], v195 offset:21504
	ds_read_b128 v[208:211], v195 offset:22528
	ds_read_b128 v[212:215], v195 offset:23552
	global_load_lds_dwordx4 v[182:183], off
	v_lshl_add_u64 v[216:217], s[48:49], 0, v[146:147]
	s_mov_b32 m0, s76
	v_lshl_add_u64 v[218:219], s[50:51], 0, v[142:143]
	global_load_lds_dwordx4 v[216:217], off
	s_mov_b32 m0, s78
	v_lshl_add_u64 v[220:221], s[46:47], 0, v[144:145]
	global_load_lds_dwordx4 v[218:219], off
	v_lshl_add_u64 v[218:219], s[50:51], 0, v[146:147]
	s_mov_b32 m0, s77
	s_nop 0
	global_load_lds_dwordx4 v[218:219], off
	v_lshl_add_u64 v[218:219], s[46:47], 0, v[140:141]
	s_mov_b32 m0, s23
	s_nop 0
	global_load_lds_dwordx4 v[218:219], off
	s_mov_b32 m0, s25
	s_nop 0
	global_load_lds_dwordx4 v[220:221], off
	s_waitcnt vmcnt(8)
	s_waitcnt lgkmcnt(0)
	s_barrier
	s_setprio 1
	v_mfma_f32_16x16x32_bf16 v[92:95], v[104:107], v[174:177], v[92:95]
	v_mfma_f32_16x16x32_bf16 v[28:31], v[112:115], v[174:177], v[28:31]
	v_mfma_f32_16x16x32_bf16 v[84:87], v[104:107], v[186:189], v[84:87]
	v_mfma_f32_16x16x32_bf16 v[20:23], v[112:115], v[186:189], v[20:23]
	v_mfma_f32_16x16x32_bf16 v[76:79], v[104:107], v[200:203], v[76:79]
	v_mfma_f32_16x16x32_bf16 v[12:15], v[112:115], v[200:203], v[12:15]
	v_mfma_f32_16x16x32_bf16 v[68:71], v[104:107], v[208:211], v[68:71]
	v_mfma_f32_16x16x32_bf16 v[4:7], v[112:115], v[208:211], v[4:7]
	v_mfma_f32_16x16x32_bf16 v[92:95], v[108:111], v[178:181], v[92:95]
	v_mfma_f32_16x16x32_bf16 v[28:31], v[154:157], v[178:181], v[28:31]
	v_mfma_f32_16x16x32_bf16 v[84:87], v[108:111], v[196:199], v[84:87]
	v_mfma_f32_16x16x32_bf16 v[20:23], v[154:157], v[196:199], v[20:23]
	v_mfma_f32_16x16x32_bf16 v[76:79], v[108:111], v[204:207], v[76:79]
	v_mfma_f32_16x16x32_bf16 v[12:15], v[154:157], v[204:207], v[12:15]
	v_mfma_f32_16x16x32_bf16 v[68:71], v[108:111], v[212:215], v[68:71]
	v_mfma_f32_16x16x32_bf16 v[4:7], v[154:157], v[212:215], v[4:7]
	s_setprio 0
	s_setprio 1
	v_mfma_f32_16x16x32_bf16 v[88:91], v[158:161], v[174:177], v[88:91]
	v_mfma_f32_16x16x32_bf16 v[24:27], v[166:169], v[174:177], v[24:27]
	v_mfma_f32_16x16x32_bf16 v[80:83], v[158:161], v[186:189], v[80:83]
	v_mfma_f32_16x16x32_bf16 v[16:19], v[166:169], v[186:189], v[16:19]
	v_mfma_f32_16x16x32_bf16 v[72:75], v[158:161], v[200:203], v[72:75]
	v_mfma_f32_16x16x32_bf16 v[8:11], v[166:169], v[200:203], v[8:11]
	v_mfma_f32_16x16x32_bf16 v[64:67], v[158:161], v[208:211], v[64:67]
	v_mfma_f32_16x16x32_bf16 v[0:3], v[166:169], v[208:211], v[0:3]
	v_mfma_f32_16x16x32_bf16 v[88:91], v[162:165], v[178:181], v[88:91]
	v_mfma_f32_16x16x32_bf16 v[24:27], v[170:173], v[178:181], v[24:27]
	v_mfma_f32_16x16x32_bf16 v[80:83], v[162:165], v[196:199], v[80:83]
	v_mfma_f32_16x16x32_bf16 v[16:19], v[170:173], v[196:199], v[16:19]
	v_mfma_f32_16x16x32_bf16 v[72:75], v[162:165], v[204:207], v[72:75]
	v_mfma_f32_16x16x32_bf16 v[8:11], v[170:173], v[204:207], v[8:11]
	v_mfma_f32_16x16x32_bf16 v[64:67], v[162:165], v[212:215], v[64:67]
	v_mfma_f32_16x16x32_bf16 v[0:3], v[170:173], v[212:215], v[0:3]
	s_setprio 0
	s_barrier
	v_add_u32_e32 v148, s73, v192
	ds_read_b128 v[104:107], v148
	ds_read_b128 v[108:111], v148 offset:1024
	ds_read_b128 v[112:115], v148 offset:2048
	ds_read_b128 v[154:157], v148 offset:3072
	v_add_u32_e32 v148, s72, v192
	ds_read_b128 v[158:161], v148
	ds_read_b128 v[162:165], v148 offset:1024
	ds_read_b128 v[166:169], v148 offset:2048
	ds_read_b128 v[170:173], v148 offset:3072
	s_mov_b32 m0, s33
	v_lshl_add_u64 v[222:223], s[44:45], 0, v[140:141]
	ds_read_b128 v[174:177], v195 offset:32768
	ds_read_b128 v[178:181], v195 offset:33792
	ds_read_b128 v[186:189], v195 offset:34816
	ds_read_b128 v[196:199], v195 offset:35840
	ds_read_b128 v[200:203], v195 offset:36864
	ds_read_b128 v[204:207], v195 offset:37888
	ds_read_b128 v[208:211], v195 offset:38912
	ds_read_b128 v[212:215], v195 offset:39936
	global_load_lds_dwordx4 v[222:223], off
	v_lshl_add_u64 v[222:223], s[44:45], 0, v[144:145]
	s_mov_b32 m0, s37
	s_nop 0
	global_load_lds_dwordx4 v[222:223], off
	s_waitcnt vmcnt(8)
	s_waitcnt lgkmcnt(0)
	s_barrier
	s_setprio 1
	v_mfma_f32_16x16x32_bf16 v[136:139], v[104:107], v[174:177], v[136:139]
	v_mfma_f32_16x16x32_bf16 v[60:63], v[112:115], v[174:177], v[60:63]
	v_mfma_f32_16x16x32_bf16 v[128:131], v[104:107], v[186:189], v[128:131]
	v_mfma_f32_16x16x32_bf16 v[52:55], v[112:115], v[186:189], v[52:55]
	v_mfma_f32_16x16x32_bf16 v[120:123], v[104:107], v[200:203], v[120:123]
	v_mfma_f32_16x16x32_bf16 v[44:47], v[112:115], v[200:203], v[44:47]
	v_mfma_f32_16x16x32_bf16 v[100:103], v[104:107], v[208:211], v[100:103]
	v_mfma_f32_16x16x32_bf16 v[36:39], v[112:115], v[208:211], v[36:39]
	v_mfma_f32_16x16x32_bf16 v[136:139], v[108:111], v[178:181], v[136:139]
	v_mfma_f32_16x16x32_bf16 v[60:63], v[154:157], v[178:181], v[60:63]
	v_mfma_f32_16x16x32_bf16 v[128:131], v[108:111], v[196:199], v[128:131]
	v_mfma_f32_16x16x32_bf16 v[52:55], v[154:157], v[196:199], v[52:55]
	v_mfma_f32_16x16x32_bf16 v[120:123], v[108:111], v[204:207], v[120:123]
	v_mfma_f32_16x16x32_bf16 v[44:47], v[154:157], v[204:207], v[44:47]
	v_mfma_f32_16x16x32_bf16 v[100:103], v[108:111], v[212:215], v[100:103]
	v_mfma_f32_16x16x32_bf16 v[36:39], v[154:157], v[212:215], v[36:39]
	s_setprio 0
	s_setprio 1
	v_mfma_f32_16x16x32_bf16 v[132:135], v[158:161], v[174:177], v[132:135]
	v_mfma_f32_16x16x32_bf16 v[56:59], v[166:169], v[174:177], v[56:59]
	v_mfma_f32_16x16x32_bf16 v[124:127], v[158:161], v[186:189], v[124:127]
	v_mfma_f32_16x16x32_bf16 v[48:51], v[166:169], v[186:189], v[48:51]
	v_mfma_f32_16x16x32_bf16 v[116:119], v[158:161], v[200:203], v[116:119]
	v_mfma_f32_16x16x32_bf16 v[40:43], v[166:169], v[200:203], v[40:43]
	v_mfma_f32_16x16x32_bf16 v[96:99], v[158:161], v[208:211], v[96:99]
	v_mfma_f32_16x16x32_bf16 v[32:35], v[166:169], v[208:211], v[32:35]
	v_mfma_f32_16x16x32_bf16 v[132:135], v[162:165], v[178:181], v[132:135]
	v_mfma_f32_16x16x32_bf16 v[56:59], v[170:173], v[178:181], v[56:59]
	v_mfma_f32_16x16x32_bf16 v[124:127], v[162:165], v[196:199], v[124:127]
	v_mfma_f32_16x16x32_bf16 v[48:51], v[170:173], v[196:199], v[48:51]
	v_mfma_f32_16x16x32_bf16 v[116:119], v[162:165], v[204:207], v[116:119]
	v_mfma_f32_16x16x32_bf16 v[40:43], v[170:173], v[204:207], v[40:43]
	v_mfma_f32_16x16x32_bf16 v[96:99], v[162:165], v[212:215], v[96:99]
	v_mfma_f32_16x16x32_bf16 v[32:35], v[170:173], v[212:215], v[32:35]
	s_setprio 0
	s_barrier
	s_mov_b32 m0, s71
	v_lshl_add_u64 v[182:183], v[182:183], 0, s[18:19]
	ds_read_b128 v[174:177], v195 offset:49152
	ds_read_b128 v[178:181], v195 offset:50176
	ds_read_b128 v[186:189], v195 offset:51200
	ds_read_b128 v[196:199], v195 offset:52224
	ds_read_b128 v[200:203], v195 offset:53248
	ds_read_b128 v[204:207], v195 offset:54272
	ds_read_b128 v[208:211], v195 offset:55296
	ds_read_b128 v[212:215], v195 offset:56320
	global_load_lds_dwordx4 v[182:183], off
	v_lshl_add_u64 v[182:183], v[216:217], 0, s[18:19]
	s_mov_b32 m0, s69
	s_nop 0
	global_load_lds_dwordx4 v[182:183], off
	v_lshl_add_u64 v[182:183], s[42:43], 0, v[142:143]
	s_mov_b32 m0, s70
	s_nop 0
	global_load_lds_dwordx4 v[182:183], off
	v_lshl_add_u64 v[182:183], s[42:43], 0, v[146:147]
	s_mov_b32 m0, s68
	s_nop 0
	global_load_lds_dwordx4 v[182:183], off
	v_lshl_add_u64 v[182:183], v[218:219], 0, s[18:19]
	s_mov_b32 m0, s57
	s_nop 0
	global_load_lds_dwordx4 v[182:183], off
	v_lshl_add_u64 v[182:183], v[220:221], 0, s[18:19]
	s_mov_b32 m0, s61
	s_nop 0
	global_load_lds_dwordx4 v[182:183], off
	s_waitcnt vmcnt(8)
	s_waitcnt lgkmcnt(0)
	s_barrier
	s_setprio 1
	v_mfma_f32_16x16x32_bf16 v[92:95], v[104:107], v[174:177], v[92:95]
	v_mfma_f32_16x16x32_bf16 v[28:31], v[112:115], v[174:177], v[28:31]
	v_mfma_f32_16x16x32_bf16 v[84:87], v[104:107], v[186:189], v[84:87]
	v_mfma_f32_16x16x32_bf16 v[20:23], v[112:115], v[186:189], v[20:23]
	v_mfma_f32_16x16x32_bf16 v[76:79], v[104:107], v[200:203], v[76:79]
	v_mfma_f32_16x16x32_bf16 v[12:15], v[112:115], v[200:203], v[12:15]
	v_mfma_f32_16x16x32_bf16 v[68:71], v[104:107], v[208:211], v[68:71]
	v_mfma_f32_16x16x32_bf16 v[4:7], v[112:115], v[208:211], v[4:7]
	v_mfma_f32_16x16x32_bf16 v[92:95], v[108:111], v[178:181], v[92:95]
	v_mfma_f32_16x16x32_bf16 v[28:31], v[154:157], v[178:181], v[28:31]
	v_mfma_f32_16x16x32_bf16 v[84:87], v[108:111], v[196:199], v[84:87]
	v_mfma_f32_16x16x32_bf16 v[20:23], v[154:157], v[196:199], v[20:23]
	v_mfma_f32_16x16x32_bf16 v[76:79], v[108:111], v[204:207], v[76:79]
	v_mfma_f32_16x16x32_bf16 v[12:15], v[154:157], v[204:207], v[12:15]
	v_mfma_f32_16x16x32_bf16 v[68:71], v[108:111], v[212:215], v[68:71]
	v_mfma_f32_16x16x32_bf16 v[4:7], v[154:157], v[212:215], v[4:7]
	s_setprio 0
	s_setprio 1
	v_mfma_f32_16x16x32_bf16 v[88:91], v[158:161], v[174:177], v[88:91]
	v_mfma_f32_16x16x32_bf16 v[24:27], v[166:169], v[174:177], v[24:27]
	v_mfma_f32_16x16x32_bf16 v[80:83], v[158:161], v[186:189], v[80:83]
	v_mfma_f32_16x16x32_bf16 v[16:19], v[166:169], v[186:189], v[16:19]
	v_mfma_f32_16x16x32_bf16 v[72:75], v[158:161], v[200:203], v[72:75]
	v_mfma_f32_16x16x32_bf16 v[8:11], v[166:169], v[200:203], v[8:11]
	v_mfma_f32_16x16x32_bf16 v[64:67], v[158:161], v[208:211], v[64:67]
	v_mfma_f32_16x16x32_bf16 v[0:3], v[166:169], v[208:211], v[0:3]
	v_mfma_f32_16x16x32_bf16 v[88:91], v[162:165], v[178:181], v[88:91]
	v_mfma_f32_16x16x32_bf16 v[24:27], v[170:173], v[178:181], v[24:27]
	v_mfma_f32_16x16x32_bf16 v[80:83], v[162:165], v[196:199], v[80:83]
	v_mfma_f32_16x16x32_bf16 v[16:19], v[170:173], v[196:199], v[16:19]
	v_mfma_f32_16x16x32_bf16 v[72:75], v[162:165], v[204:207], v[72:75]
	v_mfma_f32_16x16x32_bf16 v[8:11], v[170:173], v[204:207], v[8:11]
	v_mfma_f32_16x16x32_bf16 v[64:67], v[162:165], v[212:215], v[64:67]
	v_mfma_f32_16x16x32_bf16 v[0:3], v[170:173], v[212:215], v[0:3]
	s_setprio 0
	s_barrier
	s_andn2_b64 vcc, exec, s[6:7]
	s_mov_b64 s[42:43], -1
	s_mov_b64 s[6:7], 0
	s_mov_b64 s[44:45], 0x100
	s_cbranch_vccz .LBB0_315
	s_and_b64 vcc, exec, s[20:21]
	s_cbranch_vccz .LBB0_318
	s_barrier

.LBB0_516:
	ds_read_b128 v[120:123], v215
	ds_read_b128 v[132:135], v215 offset:1024
	ds_read_b128 v[136:139], v215 offset:2048
	ds_read_b128 v[140:143], v215 offset:3072
	ds_read_b128 v[144:147], v216
	ds_read_b128 v[148:151], v216 offset:1024
	ds_read_b128 v[152:155], v216 offset:2048
	ds_read_b128 v[156:159], v216 offset:3072
	s_add_u32 s34, s8, 0xfff80080
	s_addc_u32 s35, s9, -1
	s_cmp_eq_u32 s54, 28
	s_cselect_b32 s37, s7, s35
	s_cselect_b32 s36, s23, s34
	s_cselect_b32 s35, s21, s53
	s_cselect_b32 s34, s31, s52
	v_lshl_add_u64 v[220:221], s[8:9], 0, v[196:197]
	s_add_i32 m0, s33, 0xc000
	ds_read_b128 v[160:163], v217
	ds_read_b128 v[164:167], v217 offset:1024
	ds_read_b128 v[168:171], v217 offset:2048
	ds_read_b128 v[172:175], v217 offset:3072
	ds_read_b128 v[176:179], v217 offset:4096
	ds_read_b128 v[180:183], v217 offset:5120
	ds_read_b128 v[204:207], v217 offset:6144
	ds_read_b128 v[208:211], v217 offset:7168
	global_load_lds_dwordx4 v[220:221], off
	v_lshl_add_u64 v[220:221], s[8:9], 0, v[198:199]
	s_add_i32 m0, s33, 0xe000
	s_nop 0
	global_load_lds_dwordx4 v[220:221], off
	s_waitcnt vmcnt(8)
	s_waitcnt lgkmcnt(0)
	s_barrier
	s_setprio 1
	v_mfma_f32_16x16x32_bf16 v[128:131], v[120:123], v[160:163], v[128:131]
	v_mfma_f32_16x16x32_bf16 v[124:127], v[136:139], v[160:163], v[124:127]
	v_mfma_f32_16x16x32_bf16 v[108:111], v[120:123], v[168:171], v[108:111]
	v_mfma_f32_16x16x32_bf16 v[104:107], v[136:139], v[168:171], v[104:107]
	v_mfma_f32_16x16x32_bf16 v[92:95], v[120:123], v[176:179], v[92:95]
	v_mfma_f32_16x16x32_bf16 v[88:91], v[136:139], v[176:179], v[88:91]
	v_mfma_f32_16x16x32_bf16 v[76:79], v[120:123], v[204:207], v[76:79]
	v_mfma_f32_16x16x32_bf16 v[72:75], v[136:139], v[204:207], v[72:75]
	v_mfma_f32_16x16x32_bf16 v[128:131], v[132:135], v[164:167], v[128:131]
	v_mfma_f32_16x16x32_bf16 v[124:127], v[140:143], v[164:167], v[124:127]
	v_mfma_f32_16x16x32_bf16 v[108:111], v[132:135], v[172:175], v[108:111]
	v_mfma_f32_16x16x32_bf16 v[104:107], v[140:143], v[172:175], v[104:107]
	v_mfma_f32_16x16x32_bf16 v[92:95], v[132:135], v[180:183], v[92:95]
	v_mfma_f32_16x16x32_bf16 v[88:91], v[140:143], v[180:183], v[88:91]
	v_mfma_f32_16x16x32_bf16 v[76:79], v[132:135], v[208:211], v[76:79]
	v_mfma_f32_16x16x32_bf16 v[72:75], v[140:143], v[208:211], v[72:75]
	s_setprio 0
	s_setprio 1
	v_mfma_f32_16x16x32_bf16 v[116:119], v[144:147], v[160:163], v[116:119]
	v_mfma_f32_16x16x32_bf16 v[112:115], v[152:155], v[160:163], v[112:115]
	v_mfma_f32_16x16x32_bf16 v[100:103], v[144:147], v[168:171], v[100:103]
	v_mfma_f32_16x16x32_bf16 v[96:99], v[152:155], v[168:171], v[96:99]
	v_mfma_f32_16x16x32_bf16 v[84:87], v[144:147], v[176:179], v[84:87]
	v_mfma_f32_16x16x32_bf16 v[80:83], v[152:155], v[176:179], v[80:83]
	v_mfma_f32_16x16x32_bf16 v[68:71], v[144:147], v[204:207], v[68:71]
	v_mfma_f32_16x16x32_bf16 v[64:67], v[152:155], v[204:207], v[64:67]
	v_mfma_f32_16x16x32_bf16 v[116:119], v[148:151], v[164:167], v[116:119]
	v_mfma_f32_16x16x32_bf16 v[112:115], v[156:159], v[164:167], v[112:115]
	v_mfma_f32_16x16x32_bf16 v[100:103], v[148:151], v[172:175], v[100:103]
	v_mfma_f32_16x16x32_bf16 v[96:99], v[156:159], v[172:175], v[96:99]
	v_mfma_f32_16x16x32_bf16 v[84:87], v[148:151], v[180:183], v[84:87]
	v_mfma_f32_16x16x32_bf16 v[80:83], v[156:159], v[180:183], v[80:83]
	v_mfma_f32_16x16x32_bf16 v[68:71], v[148:151], v[208:211], v[68:71]
	v_mfma_f32_16x16x32_bf16 v[64:67], v[156:159], v[208:211], v[64:67]
	s_setprio 0
	s_barrier
	s_add_i32 s55, s50, s25
	v_lshl_add_u64 v[220:221], s[34:35], 0, v[188:189]
	s_mov_b32 m0, s55
	ds_read_b128 v[160:163], v217 offset:16384
	ds_read_b128 v[164:167], v217 offset:17408
	ds_read_b128 v[168:171], v217 offset:18432
	ds_read_b128 v[172:175], v217 offset:19456
	ds_read_b128 v[176:179], v217 offset:20480
	ds_read_b128 v[180:183], v217 offset:21504
	ds_read_b128 v[204:207], v217 offset:22528
	ds_read_b128 v[208:211], v217 offset:23552
	global_load_lds_dwordx4 v[220:221], off
	s_add_i32 m0, s55, 0x2000
	s_add_u32 s56, s34, 0x80000
	v_lshl_add_u64 v[222:223], s[34:35], 0, v[192:193]
	s_addc_u32 s57, s35, 0
	s_add_i32 s55, s51, s25
	global_load_lds_dwordx4 v[222:223], off
	v_lshl_add_u64 v[224:225], s[56:57], 0, v[188:189]
	s_mov_b32 m0, s55
	v_lshl_add_u64 v[226:227], s[36:37], 0, v[190:191]
	global_load_lds_dwordx4 v[224:225], off
	v_lshl_add_u64 v[224:225], s[56:57], 0, v[192:193]
	s_add_i32 m0, s55, 0x2000
	s_nop 0
	global_load_lds_dwordx4 v[224:225], off
	v_lshl_add_u64 v[224:225], s[36:37], 0, v[186:187]
	s_mov_b32 m0, s33
	s_nop 0
	global_load_lds_dwordx4 v[224:225], off
	s_mov_b32 m0, s38
	s_nop 0
	global_load_lds_dwordx4 v[226:227], off
	s_waitcnt vmcnt(8)
	s_waitcnt lgkmcnt(0)
	s_barrier
	s_setprio 1
	v_mfma_f32_16x16x32_bf16 v[60:63], v[120:123], v[160:163], v[60:63]
	v_mfma_f32_16x16x32_bf16 v[56:59], v[136:139], v[160:163], v[56:59]
	v_mfma_f32_16x16x32_bf16 v[44:47], v[120:123], v[168:171], v[44:47]
	v_mfma_f32_16x16x32_bf16 v[40:43], v[136:139], v[168:171], v[40:43]
	v_mfma_f32_16x16x32_bf16 v[28:31], v[120:123], v[176:179], v[28:31]
	v_mfma_f32_16x16x32_bf16 v[24:27], v[136:139], v[176:179], v[24:27]
	v_mfma_f32_16x16x32_bf16 v[12:15], v[120:123], v[204:207], v[12:15]
	v_mfma_f32_16x16x32_bf16 v[8:11], v[136:139], v[204:207], v[8:11]
	v_mfma_f32_16x16x32_bf16 v[60:63], v[132:135], v[164:167], v[60:63]
	v_mfma_f32_16x16x32_bf16 v[56:59], v[140:143], v[164:167], v[56:59]
	v_mfma_f32_16x16x32_bf16 v[44:47], v[132:135], v[172:175], v[44:47]
	v_mfma_f32_16x16x32_bf16 v[40:43], v[140:143], v[172:175], v[40:43]
	v_mfma_f32_16x16x32_bf16 v[28:31], v[132:135], v[180:183], v[28:31]
	v_mfma_f32_16x16x32_bf16 v[24:27], v[140:143], v[180:183], v[24:27]
	v_mfma_f32_16x16x32_bf16 v[12:15], v[132:135], v[208:211], v[12:15]
	v_mfma_f32_16x16x32_bf16 v[8:11], v[140:143], v[208:211], v[8:11]
	s_setprio 0
	s_setprio 1
	v_mfma_f32_16x16x32_bf16 v[52:55], v[144:147], v[160:163], v[52:55]
	v_mfma_f32_16x16x32_bf16 v[48:51], v[152:155], v[160:163], v[48:51]
	v_mfma_f32_16x16x32_bf16 v[36:39], v[144:147], v[168:171], v[36:39]
	v_mfma_f32_16x16x32_bf16 v[32:35], v[152:155], v[168:171], v[32:35]
	v_mfma_f32_16x16x32_bf16 v[20:23], v[144:147], v[176:179], v[20:23]
	v_mfma_f32_16x16x32_bf16 v[16:19], v[152:155], v[176:179], v[16:19]
	v_mfma_f32_16x16x32_bf16 v[4:7], v[144:147], v[204:207], v[4:7]
	v_mfma_f32_16x16x32_bf16 v[0:3], v[152:155], v[204:207], v[0:3]
	v_mfma_f32_16x16x32_bf16 v[52:55], v[148:151], v[164:167], v[52:55]
	v_mfma_f32_16x16x32_bf16 v[48:51], v[156:159], v[164:167], v[48:51]
	v_mfma_f32_16x16x32_bf16 v[36:39], v[148:151], v[172:175], v[36:39]
	v_mfma_f32_16x16x32_bf16 v[32:35], v[156:159], v[172:175], v[32:35]
	v_mfma_f32_16x16x32_bf16 v[20:23], v[148:151], v[180:183], v[20:23]
	v_mfma_f32_16x16x32_bf16 v[16:19], v[156:159], v[180:183], v[16:19]
	v_mfma_f32_16x16x32_bf16 v[4:7], v[148:151], v[208:211], v[4:7]
	v_mfma_f32_16x16x32_bf16 v[0:3], v[156:159], v[208:211], v[0:3]
	s_setprio 0
	s_barrier
	s_add_i32 s55, 0, 0x18000
	s_add_i32 s56, 0, 0x1c000
	v_add_u32_e32 v140, s55, v214
	v_add_u32_e32 v156, s56, v214
	ds_read_b128 v[120:123], v140
	ds_read_b128 v[132:135], v140 offset:1024
	ds_read_b128 v[136:139], v140 offset:2048
	ds_read_b128 v[140:143], v140 offset:3072
	ds_read_b128 v[144:147], v156
	ds_read_b128 v[148:151], v156 offset:1024
	ds_read_b128 v[152:155], v156 offset:2048
	ds_read_b128 v[156:159], v156 offset:3072
	s_add_u32 s36, s36, 0x80000
	s_addc_u32 s37, s37, 0
	s_mov_b32 m0, s39
	v_lshl_add_u64 v[228:229], s[36:37], 0, v[186:187]
	ds_read_b128 v[160:163], v217 offset:32768
	ds_read_b128 v[164:167], v217 offset:33792
	ds_read_b128 v[168:171], v217 offset:34816
	ds_read_b128 v[172:175], v217 offset:35840
	ds_read_b128 v[176:179], v217 offset:36864
	ds_read_b128 v[180:183], v217 offset:37888
	ds_read_b128 v[204:207], v217 offset:38912
	ds_read_b128 v[208:211], v217 offset:39936
	global_load_lds_dwordx4 v[228:229], off
	v_lshl_add_u64 v[228:229], s[36:37], 0, v[190:191]
	s_mov_b32 m0, s40
	s_nop 0
	global_load_lds_dwordx4 v[228:229], off
	s_waitcnt vmcnt(8)
	s_waitcnt lgkmcnt(0)
	s_barrier
	s_setprio 1
	v_mfma_f32_16x16x32_bf16 v[128:131], v[120:123], v[160:163], v[128:131]
	v_mfma_f32_16x16x32_bf16 v[124:127], v[136:139], v[160:163], v[124:127]
	v_mfma_f32_16x16x32_bf16 v[108:111], v[120:123], v[168:171], v[108:111]
	v_mfma_f32_16x16x32_bf16 v[104:107], v[136:139], v[168:171], v[104:107]
	v_mfma_f32_16x16x32_bf16 v[92:95], v[120:123], v[176:179], v[92:95]
	v_mfma_f32_16x16x32_bf16 v[88:91], v[136:139], v[176:179], v[88:91]
	v_mfma_f32_16x16x32_bf16 v[76:79], v[120:123], v[204:207], v[76:79]
	v_mfma_f32_16x16x32_bf16 v[72:75], v[136:139], v[204:207], v[72:75]
	v_mfma_f32_16x16x32_bf16 v[128:131], v[132:135], v[164:167], v[128:131]
	v_mfma_f32_16x16x32_bf16 v[124:127], v[140:143], v[164:167], v[124:127]
	v_mfma_f32_16x16x32_bf16 v[108:111], v[132:135], v[172:175], v[108:111]
	v_mfma_f32_16x16x32_bf16 v[104:107], v[140:143], v[172:175], v[104:107]
	v_mfma_f32_16x16x32_bf16 v[92:95], v[132:135], v[180:183], v[92:95]
	v_mfma_f32_16x16x32_bf16 v[88:91], v[140:143], v[180:183], v[88:91]
	v_mfma_f32_16x16x32_bf16 v[76:79], v[132:135], v[208:211], v[76:79]
	v_mfma_f32_16x16x32_bf16 v[72:75], v[140:143], v[208:211], v[72:75]
	s_setprio 0
	s_setprio 1
	v_mfma_f32_16x16x32_bf16 v[116:119], v[144:147], v[160:163], v[116:119]
	v_mfma_f32_16x16x32_bf16 v[112:115], v[152:155], v[160:163], v[112:115]
	v_mfma_f32_16x16x32_bf16 v[100:103], v[144:147], v[168:171], v[100:103]
	v_mfma_f32_16x16x32_bf16 v[96:99], v[152:155], v[168:171], v[96:99]
	v_mfma_f32_16x16x32_bf16 v[84:87], v[144:147], v[176:179], v[84:87]
	v_mfma_f32_16x16x32_bf16 v[80:83], v[152:155], v[176:179], v[80:83]
	v_mfma_f32_16x16x32_bf16 v[68:71], v[144:147], v[204:207], v[68:71]
	v_mfma_f32_16x16x32_bf16 v[64:67], v[152:155], v[204:207], v[64:67]
	v_mfma_f32_16x16x32_bf16 v[116:119], v[148:151], v[164:167], v[116:119]
	v_mfma_f32_16x16x32_bf16 v[112:115], v[156:159], v[164:167], v[112:115]
	v_mfma_f32_16x16x32_bf16 v[100:103], v[148:151], v[172:175], v[100:103]
	v_mfma_f32_16x16x32_bf16 v[96:99], v[156:159], v[172:175], v[96:99]
	v_mfma_f32_16x16x32_bf16 v[84:87], v[148:151], v[180:183], v[84:87]
	v_mfma_f32_16x16x32_bf16 v[80:83], v[156:159], v[180:183], v[80:83]
	v_mfma_f32_16x16x32_bf16 v[68:71], v[148:151], v[208:211], v[68:71]
	v_mfma_f32_16x16x32_bf16 v[64:67], v[156:159], v[208:211], v[64:67]
	s_setprio 0
	s_barrier
	s_add_i32 s36, s55, s25
	v_lshl_add_u64 v[220:221], v[220:221], 0, s[12:13]
	s_mov_b32 m0, s36
	ds_read_b128 v[160:163], v217 offset:49152
	ds_read_b128 v[164:167], v217 offset:50176
	ds_read_b128 v[168:171], v217 offset:51200
	ds_read_b128 v[172:175], v217 offset:52224
	ds_read_b128 v[176:179], v217 offset:53248
	ds_read_b128 v[180:183], v217 offset:54272
	ds_read_b128 v[204:207], v217 offset:55296
	ds_read_b128 v[208:211], v217 offset:56320
	global_load_lds_dwordx4 v[220:221], off
	s_add_i32 m0, s36, 0x2000
	s_add_u32 s34, s34, 0x80080
	v_lshl_add_u64 v[220:221], v[222:223], 0, s[12:13]
	s_addc_u32 s35, s35, 0
	s_add_i32 s36, s56, s25
	global_load_lds_dwordx4 v[220:221], off
	v_lshl_add_u64 v[220:221], s[34:35], 0, v[188:189]
	s_mov_b32 m0, s36
	s_nop 0
	global_load_lds_dwordx4 v[220:221], off
	v_lshl_add_u64 v[220:221], s[34:35], 0, v[192:193]
	s_add_i32 m0, s36, 0x2000
	s_nop 0
	global_load_lds_dwordx4 v[220:221], off
	v_lshl_add_u64 v[220:221], v[224:225], 0, s[12:13]
	s_mov_b32 m0, s45
	s_nop 0
	global_load_lds_dwordx4 v[220:221], off
	v_lshl_add_u64 v[220:221], v[226:227], 0, s[12:13]
	s_mov_b32 m0, s46
	s_nop 0
	global_load_lds_dwordx4 v[220:221], off
	s_waitcnt vmcnt(8)
	s_waitcnt lgkmcnt(0)
	s_barrier
	s_setprio 1
	v_mfma_f32_16x16x32_bf16 v[60:63], v[120:123], v[160:163], v[60:63]
	v_mfma_f32_16x16x32_bf16 v[56:59], v[136:139], v[160:163], v[56:59]
	v_mfma_f32_16x16x32_bf16 v[44:47], v[120:123], v[168:171], v[44:47]
	v_mfma_f32_16x16x32_bf16 v[40:43], v[136:139], v[168:171], v[40:43]
	v_mfma_f32_16x16x32_bf16 v[28:31], v[120:123], v[176:179], v[28:31]
	v_mfma_f32_16x16x32_bf16 v[24:27], v[136:139], v[176:179], v[24:27]
	v_mfma_f32_16x16x32_bf16 v[12:15], v[120:123], v[204:207], v[12:15]
	v_mfma_f32_16x16x32_bf16 v[8:11], v[136:139], v[204:207], v[8:11]
	v_mfma_f32_16x16x32_bf16 v[60:63], v[132:135], v[164:167], v[60:63]
	v_mfma_f32_16x16x32_bf16 v[56:59], v[140:143], v[164:167], v[56:59]
	v_mfma_f32_16x16x32_bf16 v[44:47], v[132:135], v[172:175], v[44:47]
	v_mfma_f32_16x16x32_bf16 v[40:43], v[140:143], v[172:175], v[40:43]
	v_mfma_f32_16x16x32_bf16 v[28:31], v[132:135], v[180:183], v[28:31]
	v_mfma_f32_16x16x32_bf16 v[24:27], v[140:143], v[180:183], v[24:27]
	v_mfma_f32_16x16x32_bf16 v[12:15], v[132:135], v[208:211], v[12:15]
	v_mfma_f32_16x16x32_bf16 v[8:11], v[140:143], v[208:211], v[8:11]
	s_setprio 0
	s_setprio 1
	v_mfma_f32_16x16x32_bf16 v[52:55], v[144:147], v[160:163], v[52:55]
	v_mfma_f32_16x16x32_bf16 v[48:51], v[152:155], v[160:163], v[48:51]
	v_mfma_f32_16x16x32_bf16 v[36:39], v[144:147], v[168:171], v[36:39]
	v_mfma_f32_16x16x32_bf16 v[32:35], v[152:155], v[168:171], v[32:35]
	v_mfma_f32_16x16x32_bf16 v[20:23], v[144:147], v[176:179], v[20:23]
	v_mfma_f32_16x16x32_bf16 v[16:19], v[152:155], v[176:179], v[16:19]
	v_mfma_f32_16x16x32_bf16 v[4:7], v[144:147], v[204:207], v[4:7]
	v_mfma_f32_16x16x32_bf16 v[0:3], v[152:155], v[204:207], v[0:3]
	v_mfma_f32_16x16x32_bf16 v[52:55], v[148:151], v[164:167], v[52:55]
	v_mfma_f32_16x16x32_bf16 v[48:51], v[156:159], v[164:167], v[48:51]
	v_mfma_f32_16x16x32_bf16 v[36:39], v[148:151], v[172:175], v[36:39]
	v_mfma_f32_16x16x32_bf16 v[32:35], v[156:159], v[172:175], v[32:35]
	v_mfma_f32_16x16x32_bf16 v[20:23], v[148:151], v[180:183], v[20:23]
	v_mfma_f32_16x16x32_bf16 v[16:19], v[156:159], v[180:183], v[16:19]
	v_mfma_f32_16x16x32_bf16 v[4:7], v[148:151], v[208:211], v[4:7]
	v_mfma_f32_16x16x32_bf16 v[0:3], v[156:159], v[208:211], v[0:3]
	s_setprio 0
	s_barrier
	s_add_i32 s54, s54, 2
	s_add_u32 s8, s8, 0x100
	s_addc_u32 s9, s9, 0
	s_add_u32 s52, s52, 0x100
	s_addc_u32 s53, s53, 0
	s_cmp_gt_u32 s54, 29
	s_cbranch_scc0 .LBB0_516
	s_and_b64 vcc, exec, s[14:15]
	s_cbranch_vccz .LBB0_519
	s_barrier

.LBB0_632:
	ds_read_b128 v[128:131], v175
	ds_read_b128 v[132:135], v175 offset:1024
	ds_read_b128 v[136:139], v175 offset:2048
	ds_read_b128 v[140:143], v175 offset:3072
	ds_read_b128 v[144:147], v176
	ds_read_b128 v[148:151], v176 offset:1024
	ds_read_b128 v[186:189], v176 offset:2048
	ds_read_b128 v[190:193], v176 offset:3072
	s_add_u32 s22, s6, 0xfff80080
	s_addc_u32 s23, s7, -1
	s_cmp_eq_u32 s50, 28
	s_cselect_b32 s27, s17, s23
	s_cselect_b32 s26, s46, s22
	s_cselect_b32 s23, s15, s49
	s_cselect_b32 s22, s47, s48
	v_lshl_add_u64 v[170:171], s[6:7], 0, v[162:163]
	s_add_i32 m0, s30, 0xc000
	ds_read_b128 v[194:197], v177
	ds_read_b128 v[198:201], v177 offset:1024
	ds_read_b128 v[202:205], v177 offset:2048
	ds_read_b128 v[206:209], v177 offset:3072
	ds_read_b128 v[210:213], v177 offset:4096
	ds_read_b128 v[214:217], v177 offset:5120
	ds_read_b128 v[218:221], v177 offset:6144
	ds_read_b128 v[222:225], v177 offset:7168
	global_load_lds_dwordx4 v[170:171], off
	v_lshl_add_u64 v[170:171], s[6:7], 0, v[164:165]
	s_add_i32 m0, s30, 0xe000
	s_nop 0
	global_load_lds_dwordx4 v[170:171], off
	s_waitcnt vmcnt(8)
	s_waitcnt lgkmcnt(0)
	s_barrier
	s_setprio 1
	v_mfma_f32_16x16x32_bf16 v[124:127], v[128:131], v[194:197], v[124:127]
	v_mfma_f32_16x16x32_bf16 v[116:119], v[136:139], v[194:197], v[116:119]
	v_mfma_f32_16x16x32_bf16 v[108:111], v[128:131], v[202:205], v[108:111]
	v_mfma_f32_16x16x32_bf16 v[100:103], v[136:139], v[202:205], v[100:103]
	v_mfma_f32_16x16x32_bf16 v[92:95], v[128:131], v[210:213], v[92:95]
	v_mfma_f32_16x16x32_bf16 v[84:87], v[136:139], v[210:213], v[84:87]
	v_mfma_f32_16x16x32_bf16 v[76:79], v[128:131], v[218:221], v[76:79]
	v_mfma_f32_16x16x32_bf16 v[68:71], v[136:139], v[218:221], v[68:71]
	v_mfma_f32_16x16x32_bf16 v[124:127], v[132:135], v[198:201], v[124:127]
	v_mfma_f32_16x16x32_bf16 v[116:119], v[140:143], v[198:201], v[116:119]
	v_mfma_f32_16x16x32_bf16 v[108:111], v[132:135], v[206:209], v[108:111]
	v_mfma_f32_16x16x32_bf16 v[100:103], v[140:143], v[206:209], v[100:103]
	v_mfma_f32_16x16x32_bf16 v[92:95], v[132:135], v[214:217], v[92:95]
	v_mfma_f32_16x16x32_bf16 v[84:87], v[140:143], v[214:217], v[84:87]
	v_mfma_f32_16x16x32_bf16 v[76:79], v[132:135], v[222:225], v[76:79]
	v_mfma_f32_16x16x32_bf16 v[68:71], v[140:143], v[222:225], v[68:71]
	s_setprio 0
	s_setprio 1
	v_mfma_f32_16x16x32_bf16 v[120:123], v[144:147], v[194:197], v[120:123]
	v_mfma_f32_16x16x32_bf16 v[112:115], v[186:189], v[194:197], v[112:115]
	v_mfma_f32_16x16x32_bf16 v[104:107], v[144:147], v[202:205], v[104:107]
	v_mfma_f32_16x16x32_bf16 v[96:99], v[186:189], v[202:205], v[96:99]
	v_mfma_f32_16x16x32_bf16 v[88:91], v[144:147], v[210:213], v[88:91]
	v_mfma_f32_16x16x32_bf16 v[80:83], v[186:189], v[210:213], v[80:83]
	v_mfma_f32_16x16x32_bf16 v[72:75], v[144:147], v[218:221], v[72:75]
	v_mfma_f32_16x16x32_bf16 v[64:67], v[186:189], v[218:221], v[64:67]
	v_mfma_f32_16x16x32_bf16 v[120:123], v[148:151], v[198:201], v[120:123]
	v_mfma_f32_16x16x32_bf16 v[112:115], v[190:193], v[198:201], v[112:115]
	v_mfma_f32_16x16x32_bf16 v[104:107], v[148:151], v[206:209], v[104:107]
	v_mfma_f32_16x16x32_bf16 v[96:99], v[190:193], v[206:209], v[96:99]
	v_mfma_f32_16x16x32_bf16 v[88:91], v[148:151], v[214:217], v[88:91]
	v_mfma_f32_16x16x32_bf16 v[80:83], v[190:193], v[214:217], v[80:83]
	v_mfma_f32_16x16x32_bf16 v[72:75], v[148:151], v[222:225], v[72:75]
	v_mfma_f32_16x16x32_bf16 v[64:67], v[190:193], v[222:225], v[64:67]
	s_setprio 0
	s_barrier
	s_add_i32 s51, s42, s25
	v_lshl_add_u64 v[170:171], s[22:23], 0, v[156:157]
	s_mov_b32 m0, s51
	ds_read_b128 v[194:197], v177 offset:16384
	ds_read_b128 v[198:201], v177 offset:17408
	ds_read_b128 v[202:205], v177 offset:18432
	ds_read_b128 v[206:209], v177 offset:19456
	ds_read_b128 v[210:213], v177 offset:20480
	ds_read_b128 v[214:217], v177 offset:21504
	ds_read_b128 v[218:221], v177 offset:22528
	ds_read_b128 v[222:225], v177 offset:23552
	global_load_lds_dwordx4 v[170:171], off
	s_add_i32 m0, s51, 0x2000
	s_add_u32 s52, s22, 0x80000
	v_lshl_add_u64 v[182:183], s[22:23], 0, v[152:153]
	s_addc_u32 s53, s23, 0
	s_add_i32 s51, s43, s25
	global_load_lds_dwordx4 v[182:183], off
	v_lshl_add_u64 v[226:227], s[52:53], 0, v[156:157]
	s_mov_b32 m0, s51
	v_lshl_add_u64 v[228:229], s[26:27], 0, v[154:155]
	global_load_lds_dwordx4 v[226:227], off
	v_lshl_add_u64 v[226:227], s[52:53], 0, v[152:153]
	s_add_i32 m0, s51, 0x2000
	s_nop 0
	global_load_lds_dwordx4 v[226:227], off
	v_lshl_add_u64 v[226:227], s[26:27], 0, v[158:159]
	s_mov_b32 m0, s30
	s_nop 0
	global_load_lds_dwordx4 v[226:227], off
	s_mov_b32 m0, s31
	s_nop 0
	global_load_lds_dwordx4 v[228:229], off
	s_waitcnt vmcnt(8)
	s_waitcnt lgkmcnt(0)
	s_barrier
	s_setprio 1
	v_mfma_f32_16x16x32_bf16 v[60:63], v[128:131], v[194:197], v[60:63]
	v_mfma_f32_16x16x32_bf16 v[52:55], v[136:139], v[194:197], v[52:55]
	v_mfma_f32_16x16x32_bf16 v[44:47], v[128:131], v[202:205], v[44:47]
	v_mfma_f32_16x16x32_bf16 v[36:39], v[136:139], v[202:205], v[36:39]
	v_mfma_f32_16x16x32_bf16 v[28:31], v[128:131], v[210:213], v[28:31]
	v_mfma_f32_16x16x32_bf16 v[20:23], v[136:139], v[210:213], v[20:23]
	v_mfma_f32_16x16x32_bf16 v[12:15], v[128:131], v[218:221], v[12:15]
	v_mfma_f32_16x16x32_bf16 v[4:7], v[136:139], v[218:221], v[4:7]
	v_mfma_f32_16x16x32_bf16 v[60:63], v[132:135], v[198:201], v[60:63]
	v_mfma_f32_16x16x32_bf16 v[52:55], v[140:143], v[198:201], v[52:55]
	v_mfma_f32_16x16x32_bf16 v[44:47], v[132:135], v[206:209], v[44:47]
	v_mfma_f32_16x16x32_bf16 v[36:39], v[140:143], v[206:209], v[36:39]
	v_mfma_f32_16x16x32_bf16 v[28:31], v[132:135], v[214:217], v[28:31]
	v_mfma_f32_16x16x32_bf16 v[20:23], v[140:143], v[214:217], v[20:23]
	v_mfma_f32_16x16x32_bf16 v[12:15], v[132:135], v[222:225], v[12:15]
	v_mfma_f32_16x16x32_bf16 v[4:7], v[140:143], v[222:225], v[4:7]
	s_setprio 0
	s_setprio 1
	v_mfma_f32_16x16x32_bf16 v[56:59], v[144:147], v[194:197], v[56:59]
	v_mfma_f32_16x16x32_bf16 v[48:51], v[186:189], v[194:197], v[48:51]
	v_mfma_f32_16x16x32_bf16 v[40:43], v[144:147], v[202:205], v[40:43]
	v_mfma_f32_16x16x32_bf16 v[32:35], v[186:189], v[202:205], v[32:35]
	v_mfma_f32_16x16x32_bf16 v[24:27], v[144:147], v[210:213], v[24:27]
	v_mfma_f32_16x16x32_bf16 v[16:19], v[186:189], v[210:213], v[16:19]
	v_mfma_f32_16x16x32_bf16 v[8:11], v[144:147], v[218:221], v[8:11]
	v_mfma_f32_16x16x32_bf16 v[0:3], v[186:189], v[218:221], v[0:3]
	v_mfma_f32_16x16x32_bf16 v[56:59], v[148:151], v[198:201], v[56:59]
	v_mfma_f32_16x16x32_bf16 v[48:51], v[190:193], v[198:201], v[48:51]
	v_mfma_f32_16x16x32_bf16 v[40:43], v[148:151], v[206:209], v[40:43]
	v_mfma_f32_16x16x32_bf16 v[32:35], v[190:193], v[206:209], v[32:35]
	v_mfma_f32_16x16x32_bf16 v[24:27], v[148:151], v[214:217], v[24:27]
	v_mfma_f32_16x16x32_bf16 v[16:19], v[190:193], v[214:217], v[16:19]
	v_mfma_f32_16x16x32_bf16 v[8:11], v[148:151], v[222:225], v[8:11]
	v_mfma_f32_16x16x32_bf16 v[0:3], v[190:193], v[222:225], v[0:3]
	s_setprio 0
	s_barrier
	s_add_i32 s51, 0, 0x18000
	s_add_i32 s52, 0, 0x1c000
	v_add_u32_e32 v140, s51, v174
	v_add_u32_e32 v160, s52, v174
	ds_read_b128 v[128:131], v140
	ds_read_b128 v[132:135], v140 offset:1024
	ds_read_b128 v[136:139], v140 offset:2048
	ds_read_b128 v[140:143], v140 offset:3072
	ds_read_b128 v[144:147], v160
	ds_read_b128 v[148:151], v160 offset:1024
	ds_read_b128 v[186:189], v160 offset:2048
	ds_read_b128 v[190:193], v160 offset:3072
	s_add_u32 s26, s26, 0x80000
	s_addc_u32 s27, s27, 0
	s_mov_b32 m0, s33
	v_lshl_add_u64 v[230:231], s[26:27], 0, v[158:159]
	ds_read_b128 v[194:197], v177 offset:32768
	ds_read_b128 v[198:201], v177 offset:33792
	ds_read_b128 v[202:205], v177 offset:34816
	ds_read_b128 v[206:209], v177 offset:35840
	ds_read_b128 v[210:213], v177 offset:36864
	ds_read_b128 v[214:217], v177 offset:37888
	ds_read_b128 v[218:221], v177 offset:38912
	ds_read_b128 v[222:225], v177 offset:39936
	global_load_lds_dwordx4 v[230:231], off
	v_lshl_add_u64 v[230:231], s[26:27], 0, v[154:155]
	s_mov_b32 m0, s34
	s_nop 0
	global_load_lds_dwordx4 v[230:231], off
	s_waitcnt vmcnt(8)
	s_waitcnt lgkmcnt(0)
	s_barrier
	s_setprio 1
	v_mfma_f32_16x16x32_bf16 v[124:127], v[128:131], v[194:197], v[124:127]
	v_mfma_f32_16x16x32_bf16 v[116:119], v[136:139], v[194:197], v[116:119]
	v_mfma_f32_16x16x32_bf16 v[108:111], v[128:131], v[202:205], v[108:111]
	v_mfma_f32_16x16x32_bf16 v[100:103], v[136:139], v[202:205], v[100:103]
	v_mfma_f32_16x16x32_bf16 v[92:95], v[128:131], v[210:213], v[92:95]
	v_mfma_f32_16x16x32_bf16 v[84:87], v[136:139], v[210:213], v[84:87]
	v_mfma_f32_16x16x32_bf16 v[76:79], v[128:131], v[218:221], v[76:79]
	v_mfma_f32_16x16x32_bf16 v[68:71], v[136:139], v[218:221], v[68:71]
	v_mfma_f32_16x16x32_bf16 v[124:127], v[132:135], v[198:201], v[124:127]
	v_mfma_f32_16x16x32_bf16 v[116:119], v[140:143], v[198:201], v[116:119]
	v_mfma_f32_16x16x32_bf16 v[108:111], v[132:135], v[206:209], v[108:111]
	v_mfma_f32_16x16x32_bf16 v[100:103], v[140:143], v[206:209], v[100:103]
	v_mfma_f32_16x16x32_bf16 v[92:95], v[132:135], v[214:217], v[92:95]
	v_mfma_f32_16x16x32_bf16 v[84:87], v[140:143], v[214:217], v[84:87]
	v_mfma_f32_16x16x32_bf16 v[76:79], v[132:135], v[222:225], v[76:79]
	v_mfma_f32_16x16x32_bf16 v[68:71], v[140:143], v[222:225], v[68:71]
	s_setprio 0
	s_setprio 1
	v_mfma_f32_16x16x32_bf16 v[120:123], v[144:147], v[194:197], v[120:123]
	v_mfma_f32_16x16x32_bf16 v[112:115], v[186:189], v[194:197], v[112:115]
	v_mfma_f32_16x16x32_bf16 v[104:107], v[144:147], v[202:205], v[104:107]
	v_mfma_f32_16x16x32_bf16 v[96:99], v[186:189], v[202:205], v[96:99]
	v_mfma_f32_16x16x32_bf16 v[88:91], v[144:147], v[210:213], v[88:91]
	v_mfma_f32_16x16x32_bf16 v[80:83], v[186:189], v[210:213], v[80:83]
	v_mfma_f32_16x16x32_bf16 v[72:75], v[144:147], v[218:221], v[72:75]
	v_mfma_f32_16x16x32_bf16 v[64:67], v[186:189], v[218:221], v[64:67]
	v_mfma_f32_16x16x32_bf16 v[120:123], v[148:151], v[198:201], v[120:123]
	v_mfma_f32_16x16x32_bf16 v[112:115], v[190:193], v[198:201], v[112:115]
	v_mfma_f32_16x16x32_bf16 v[104:107], v[148:151], v[206:209], v[104:107]
	v_mfma_f32_16x16x32_bf16 v[96:99], v[190:193], v[206:209], v[96:99]
	v_mfma_f32_16x16x32_bf16 v[88:91], v[148:151], v[214:217], v[88:91]
	v_mfma_f32_16x16x32_bf16 v[80:83], v[190:193], v[214:217], v[80:83]
	v_mfma_f32_16x16x32_bf16 v[72:75], v[148:151], v[222:225], v[72:75]
	v_mfma_f32_16x16x32_bf16 v[64:67], v[190:193], v[222:225], v[64:67]
	s_setprio 0
	s_barrier
	s_add_i32 s26, s51, s25
	v_lshl_add_u64 v[170:171], v[170:171], 0, s[10:11]
	s_mov_b32 m0, s26
	ds_read_b128 v[194:197], v177 offset:49152
	ds_read_b128 v[198:201], v177 offset:50176
	ds_read_b128 v[202:205], v177 offset:51200
	ds_read_b128 v[206:209], v177 offset:52224
	ds_read_b128 v[210:213], v177 offset:53248
	ds_read_b128 v[214:217], v177 offset:54272
	ds_read_b128 v[218:221], v177 offset:55296
	ds_read_b128 v[222:225], v177 offset:56320
	global_load_lds_dwordx4 v[170:171], off
	s_add_i32 m0, s26, 0x2000
	s_add_u32 s22, s22, 0x80080
	v_lshl_add_u64 v[170:171], v[182:183], 0, s[10:11]
	s_addc_u32 s23, s23, 0
	s_add_i32 s26, s52, s25
	global_load_lds_dwordx4 v[170:171], off
	v_lshl_add_u64 v[170:171], s[22:23], 0, v[156:157]
	s_mov_b32 m0, s26
	s_nop 0
	global_load_lds_dwordx4 v[170:171], off
	v_lshl_add_u64 v[170:171], s[22:23], 0, v[152:153]
	s_add_i32 m0, s26, 0x2000
	s_nop 0
	global_load_lds_dwordx4 v[170:171], off
	v_lshl_add_u64 v[170:171], v[226:227], 0, s[10:11]
	s_mov_b32 m0, s38
	s_nop 0
	global_load_lds_dwordx4 v[170:171], off
	v_lshl_add_u64 v[170:171], v[228:229], 0, s[10:11]
	s_mov_b32 m0, s39
	s_nop 0
	global_load_lds_dwordx4 v[170:171], off
	s_waitcnt vmcnt(8)
	s_waitcnt lgkmcnt(0)
	s_barrier
	s_setprio 1
	v_mfma_f32_16x16x32_bf16 v[60:63], v[128:131], v[194:197], v[60:63]
	v_mfma_f32_16x16x32_bf16 v[52:55], v[136:139], v[194:197], v[52:55]
	v_mfma_f32_16x16x32_bf16 v[44:47], v[128:131], v[202:205], v[44:47]
	v_mfma_f32_16x16x32_bf16 v[36:39], v[136:139], v[202:205], v[36:39]
	v_mfma_f32_16x16x32_bf16 v[28:31], v[128:131], v[210:213], v[28:31]
	v_mfma_f32_16x16x32_bf16 v[20:23], v[136:139], v[210:213], v[20:23]
	v_mfma_f32_16x16x32_bf16 v[12:15], v[128:131], v[218:221], v[12:15]
	v_mfma_f32_16x16x32_bf16 v[4:7], v[136:139], v[218:221], v[4:7]
	v_mfma_f32_16x16x32_bf16 v[60:63], v[132:135], v[198:201], v[60:63]
	v_mfma_f32_16x16x32_bf16 v[52:55], v[140:143], v[198:201], v[52:55]
	v_mfma_f32_16x16x32_bf16 v[44:47], v[132:135], v[206:209], v[44:47]
	v_mfma_f32_16x16x32_bf16 v[36:39], v[140:143], v[206:209], v[36:39]
	v_mfma_f32_16x16x32_bf16 v[28:31], v[132:135], v[214:217], v[28:31]
	v_mfma_f32_16x16x32_bf16 v[20:23], v[140:143], v[214:217], v[20:23]
	v_mfma_f32_16x16x32_bf16 v[12:15], v[132:135], v[222:225], v[12:15]
	v_mfma_f32_16x16x32_bf16 v[4:7], v[140:143], v[222:225], v[4:7]
	s_setprio 0
	s_setprio 1
	v_mfma_f32_16x16x32_bf16 v[56:59], v[144:147], v[194:197], v[56:59]
	v_mfma_f32_16x16x32_bf16 v[48:51], v[186:189], v[194:197], v[48:51]
	v_mfma_f32_16x16x32_bf16 v[40:43], v[144:147], v[202:205], v[40:43]
	v_mfma_f32_16x16x32_bf16 v[32:35], v[186:189], v[202:205], v[32:35]
	v_mfma_f32_16x16x32_bf16 v[24:27], v[144:147], v[210:213], v[24:27]
	v_mfma_f32_16x16x32_bf16 v[16:19], v[186:189], v[210:213], v[16:19]
	v_mfma_f32_16x16x32_bf16 v[8:11], v[144:147], v[218:221], v[8:11]
	v_mfma_f32_16x16x32_bf16 v[0:3], v[186:189], v[218:221], v[0:3]
	v_mfma_f32_16x16x32_bf16 v[56:59], v[148:151], v[198:201], v[56:59]
	v_mfma_f32_16x16x32_bf16 v[48:51], v[190:193], v[198:201], v[48:51]
	v_mfma_f32_16x16x32_bf16 v[40:43], v[148:151], v[206:209], v[40:43]
	v_mfma_f32_16x16x32_bf16 v[32:35], v[190:193], v[206:209], v[32:35]
	v_mfma_f32_16x16x32_bf16 v[24:27], v[148:151], v[214:217], v[24:27]
	v_mfma_f32_16x16x32_bf16 v[16:19], v[190:193], v[214:217], v[16:19]
	v_mfma_f32_16x16x32_bf16 v[8:11], v[148:151], v[222:225], v[8:11]
	v_mfma_f32_16x16x32_bf16 v[0:3], v[190:193], v[222:225], v[0:3]
	s_setprio 0
	s_barrier
	s_add_i32 s50, s50, 2
	s_add_u32 s6, s6, 0x100
	s_addc_u32 s7, s7, 0
	s_add_u32 s48, s48, 0x100
	s_addc_u32 s49, s49, 0
	s_cmp_gt_u32 s50, 29
	s_cbranch_scc0 .LBB0_632
	s_and_b64 vcc, exec, s[12:13]
	s_cbranch_vccz .LBB0_635
	s_barrier

.LBB0_714:
	ds_read_b128 v[128:131], v177
	ds_read_b128 v[132:135], v177 offset:1024
	ds_read_b128 v[136:139], v177 offset:2048
	ds_read_b128 v[140:143], v177 offset:3072
	ds_read_b128 v[144:147], v178
	ds_read_b128 v[148:151], v178 offset:1024
	ds_read_b128 v[170:173], v178 offset:2048
	ds_read_b128 v[186:189], v178 offset:3072
	s_add_u32 s0, s16, 0x100
	s_addc_u32 s1, s17, 0
	s_cmpk_eq_i32 s46, 0x54
	s_cselect_b32 s21, s13, s1
	s_cselect_b32 s20, s12, s0
	s_cselect_b32 s19, s15, s45
	s_cselect_b32 s18, s14, s44
	v_lshl_add_u64 v[182:183], s[16:17], 0, v[162:163]
	s_add_i32 m0, s23, 0xc000
	ds_read_b128 v[190:193], v179
	ds_read_b128 v[194:197], v179 offset:1024
	ds_read_b128 v[198:201], v179 offset:2048
	ds_read_b128 v[202:205], v179 offset:3072
	ds_read_b128 v[206:209], v179 offset:4096
	ds_read_b128 v[210:213], v179 offset:5120
	ds_read_b128 v[214:217], v179 offset:6144
	ds_read_b128 v[218:221], v179 offset:7168
	global_load_lds_dwordx4 v[182:183], off
	v_lshl_add_u64 v[182:183], s[16:17], 0, v[164:165]
	s_add_i32 m0, s23, 0xe000
	s_nop 0
	global_load_lds_dwordx4 v[182:183], off
	s_waitcnt vmcnt(8)
	s_waitcnt lgkmcnt(0)
	s_barrier
	s_setprio 1
	v_mfma_f32_16x16x32_bf16 v[124:127], v[128:131], v[190:193], v[124:127]
	v_mfma_f32_16x16x32_bf16 v[120:123], v[136:139], v[190:193], v[120:123]
	v_mfma_f32_16x16x32_bf16 v[108:111], v[128:131], v[198:201], v[108:111]
	v_mfma_f32_16x16x32_bf16 v[104:107], v[136:139], v[198:201], v[104:107]
	v_mfma_f32_16x16x32_bf16 v[92:95], v[128:131], v[206:209], v[92:95]
	v_mfma_f32_16x16x32_bf16 v[88:91], v[136:139], v[206:209], v[88:91]
	v_mfma_f32_16x16x32_bf16 v[76:79], v[128:131], v[214:217], v[76:79]
	v_mfma_f32_16x16x32_bf16 v[72:75], v[136:139], v[214:217], v[72:75]
	v_mfma_f32_16x16x32_bf16 v[124:127], v[132:135], v[194:197], v[124:127]
	v_mfma_f32_16x16x32_bf16 v[120:123], v[140:143], v[194:197], v[120:123]
	v_mfma_f32_16x16x32_bf16 v[108:111], v[132:135], v[202:205], v[108:111]
	v_mfma_f32_16x16x32_bf16 v[104:107], v[140:143], v[202:205], v[104:107]
	v_mfma_f32_16x16x32_bf16 v[92:95], v[132:135], v[210:213], v[92:95]
	v_mfma_f32_16x16x32_bf16 v[88:91], v[140:143], v[210:213], v[88:91]
	v_mfma_f32_16x16x32_bf16 v[76:79], v[132:135], v[218:221], v[76:79]
	v_mfma_f32_16x16x32_bf16 v[72:75], v[140:143], v[218:221], v[72:75]
	s_setprio 0
	s_setprio 1
	v_mfma_f32_16x16x32_bf16 v[116:119], v[144:147], v[190:193], v[116:119]
	v_mfma_f32_16x16x32_bf16 v[112:115], v[170:173], v[190:193], v[112:115]
	v_mfma_f32_16x16x32_bf16 v[100:103], v[144:147], v[198:201], v[100:103]
	v_mfma_f32_16x16x32_bf16 v[96:99], v[170:173], v[198:201], v[96:99]
	v_mfma_f32_16x16x32_bf16 v[84:87], v[144:147], v[206:209], v[84:87]
	v_mfma_f32_16x16x32_bf16 v[80:83], v[170:173], v[206:209], v[80:83]
	v_mfma_f32_16x16x32_bf16 v[68:71], v[144:147], v[214:217], v[68:71]
	v_mfma_f32_16x16x32_bf16 v[64:67], v[170:173], v[214:217], v[64:67]
	v_mfma_f32_16x16x32_bf16 v[116:119], v[148:151], v[194:197], v[116:119]
	v_mfma_f32_16x16x32_bf16 v[112:115], v[186:189], v[194:197], v[112:115]
	v_mfma_f32_16x16x32_bf16 v[100:103], v[148:151], v[202:205], v[100:103]
	v_mfma_f32_16x16x32_bf16 v[96:99], v[186:189], v[202:205], v[96:99]
	v_mfma_f32_16x16x32_bf16 v[84:87], v[148:151], v[210:213], v[84:87]
	v_mfma_f32_16x16x32_bf16 v[80:83], v[186:189], v[210:213], v[80:83]
	v_mfma_f32_16x16x32_bf16 v[68:71], v[148:151], v[218:221], v[68:71]
	v_mfma_f32_16x16x32_bf16 v[64:67], v[186:189], v[218:221], v[64:67]
	s_setprio 0
	s_barrier
	s_add_i32 s16, s38, s22
	v_lshl_add_u64 v[182:183], s[18:19], 0, v[154:155]
	s_mov_b32 m0, s16
	ds_read_b128 v[190:193], v179 offset:16384
	ds_read_b128 v[194:197], v179 offset:17408
	ds_read_b128 v[198:201], v179 offset:18432
	ds_read_b128 v[202:205], v179 offset:19456
	ds_read_b128 v[206:209], v179 offset:20480
	ds_read_b128 v[210:213], v179 offset:21504
	ds_read_b128 v[214:217], v179 offset:22528
	ds_read_b128 v[218:221], v179 offset:23552
	global_load_lds_dwordx4 v[182:183], off
	s_add_i32 m0, s16, 0x2000
	s_add_u32 s16, s18, 0x160000
	v_lshl_add_u64 v[222:223], s[18:19], 0, v[158:159]
	s_addc_u32 s17, s19, 0
	s_add_i32 s47, s39, s22
	global_load_lds_dwordx4 v[222:223], off
	v_lshl_add_u64 v[224:225], s[16:17], 0, v[154:155]
	s_mov_b32 m0, s47
	v_lshl_add_u64 v[226:227], s[20:21], 0, v[156:157]
	global_load_lds_dwordx4 v[224:225], off
	v_lshl_add_u64 v[224:225], s[16:17], 0, v[158:159]
	s_add_i32 m0, s47, 0x2000
	s_nop 0
	global_load_lds_dwordx4 v[224:225], off
	v_lshl_add_u64 v[224:225], s[20:21], 0, v[152:153]
	s_mov_b32 m0, s23
	s_nop 0
	global_load_lds_dwordx4 v[224:225], off
	s_mov_b32 m0, s25
	s_nop 0
	global_load_lds_dwordx4 v[226:227], off
	s_waitcnt vmcnt(8)
	s_waitcnt lgkmcnt(0)
	s_barrier
	s_setprio 1
	v_mfma_f32_16x16x32_bf16 v[60:63], v[128:131], v[190:193], v[60:63]
	v_mfma_f32_16x16x32_bf16 v[56:59], v[136:139], v[190:193], v[56:59]
	v_mfma_f32_16x16x32_bf16 v[44:47], v[128:131], v[198:201], v[44:47]
	v_mfma_f32_16x16x32_bf16 v[40:43], v[136:139], v[198:201], v[40:43]
	v_mfma_f32_16x16x32_bf16 v[28:31], v[128:131], v[206:209], v[28:31]
	v_mfma_f32_16x16x32_bf16 v[24:27], v[136:139], v[206:209], v[24:27]
	v_mfma_f32_16x16x32_bf16 v[12:15], v[128:131], v[214:217], v[12:15]
	v_mfma_f32_16x16x32_bf16 v[8:11], v[136:139], v[214:217], v[8:11]
	v_mfma_f32_16x16x32_bf16 v[60:63], v[132:135], v[194:197], v[60:63]
	v_mfma_f32_16x16x32_bf16 v[56:59], v[140:143], v[194:197], v[56:59]
	v_mfma_f32_16x16x32_bf16 v[44:47], v[132:135], v[202:205], v[44:47]
	v_mfma_f32_16x16x32_bf16 v[40:43], v[140:143], v[202:205], v[40:43]
	v_mfma_f32_16x16x32_bf16 v[28:31], v[132:135], v[210:213], v[28:31]
	v_mfma_f32_16x16x32_bf16 v[24:27], v[140:143], v[210:213], v[24:27]
	v_mfma_f32_16x16x32_bf16 v[12:15], v[132:135], v[218:221], v[12:15]
	v_mfma_f32_16x16x32_bf16 v[8:11], v[140:143], v[218:221], v[8:11]
	s_setprio 0
	s_setprio 1
	v_mfma_f32_16x16x32_bf16 v[52:55], v[144:147], v[190:193], v[52:55]
	v_mfma_f32_16x16x32_bf16 v[48:51], v[170:173], v[190:193], v[48:51]
	v_mfma_f32_16x16x32_bf16 v[36:39], v[144:147], v[198:201], v[36:39]
	v_mfma_f32_16x16x32_bf16 v[32:35], v[170:173], v[198:201], v[32:35]
	v_mfma_f32_16x16x32_bf16 v[20:23], v[144:147], v[206:209], v[20:23]
	v_mfma_f32_16x16x32_bf16 v[16:19], v[170:173], v[206:209], v[16:19]
	v_mfma_f32_16x16x32_bf16 v[4:7], v[144:147], v[214:217], v[4:7]
	v_mfma_f32_16x16x32_bf16 v[0:3], v[170:173], v[214:217], v[0:3]
	v_mfma_f32_16x16x32_bf16 v[52:55], v[148:151], v[194:197], v[52:55]
	v_mfma_f32_16x16x32_bf16 v[48:51], v[186:189], v[194:197], v[48:51]
	v_mfma_f32_16x16x32_bf16 v[36:39], v[148:151], v[202:205], v[36:39]
	v_mfma_f32_16x16x32_bf16 v[32:35], v[186:189], v[202:205], v[32:35]
	v_mfma_f32_16x16x32_bf16 v[20:23], v[148:151], v[210:213], v[20:23]
	v_mfma_f32_16x16x32_bf16 v[16:19], v[186:189], v[210:213], v[16:19]
	v_mfma_f32_16x16x32_bf16 v[4:7], v[148:151], v[218:221], v[4:7]
	v_mfma_f32_16x16x32_bf16 v[0:3], v[186:189], v[218:221], v[0:3]
	s_setprio 0
	s_barrier
	s_add_i32 s47, 0, 0x18000
	s_add_i32 s48, 0, 0x1c000
	v_add_u32_e32 v140, s47, v176
	v_add_u32_e32 v160, s48, v176
	ds_read_b128 v[128:131], v140
	ds_read_b128 v[132:135], v140 offset:1024
	ds_read_b128 v[136:139], v140 offset:2048
	ds_read_b128 v[140:143], v140 offset:3072
	ds_read_b128 v[144:147], v160
	ds_read_b128 v[148:151], v160 offset:1024
	ds_read_b128 v[170:173], v160 offset:2048
	ds_read_b128 v[186:189], v160 offset:3072
	s_add_u32 s16, s20, 0x160000
	s_addc_u32 s17, s21, 0
	s_mov_b32 m0, s26
	v_lshl_add_u64 v[228:229], s[16:17], 0, v[152:153]
	ds_read_b128 v[190:193], v179 offset:32768
	ds_read_b128 v[194:197], v179 offset:33792
	ds_read_b128 v[198:201], v179 offset:34816
	ds_read_b128 v[202:205], v179 offset:35840
	ds_read_b128 v[206:209], v179 offset:36864
	ds_read_b128 v[210:213], v179 offset:37888
	ds_read_b128 v[214:217], v179 offset:38912
	ds_read_b128 v[218:221], v179 offset:39936
	global_load_lds_dwordx4 v[228:229], off
	v_lshl_add_u64 v[228:229], s[16:17], 0, v[156:157]
	s_mov_b32 m0, s27
	s_nop 0
	global_load_lds_dwordx4 v[228:229], off
	s_waitcnt vmcnt(8)
	s_waitcnt lgkmcnt(0)
	s_barrier
	s_setprio 1
	v_mfma_f32_16x16x32_bf16 v[124:127], v[128:131], v[190:193], v[124:127]
	v_mfma_f32_16x16x32_bf16 v[120:123], v[136:139], v[190:193], v[120:123]
	v_mfma_f32_16x16x32_bf16 v[108:111], v[128:131], v[198:201], v[108:111]
	v_mfma_f32_16x16x32_bf16 v[104:107], v[136:139], v[198:201], v[104:107]
	v_mfma_f32_16x16x32_bf16 v[92:95], v[128:131], v[206:209], v[92:95]
	v_mfma_f32_16x16x32_bf16 v[88:91], v[136:139], v[206:209], v[88:91]
	v_mfma_f32_16x16x32_bf16 v[76:79], v[128:131], v[214:217], v[76:79]
	v_mfma_f32_16x16x32_bf16 v[72:75], v[136:139], v[214:217], v[72:75]
	v_mfma_f32_16x16x32_bf16 v[124:127], v[132:135], v[194:197], v[124:127]
	v_mfma_f32_16x16x32_bf16 v[120:123], v[140:143], v[194:197], v[120:123]
	v_mfma_f32_16x16x32_bf16 v[108:111], v[132:135], v[202:205], v[108:111]
	v_mfma_f32_16x16x32_bf16 v[104:107], v[140:143], v[202:205], v[104:107]
	v_mfma_f32_16x16x32_bf16 v[92:95], v[132:135], v[210:213], v[92:95]
	v_mfma_f32_16x16x32_bf16 v[88:91], v[140:143], v[210:213], v[88:91]
	v_mfma_f32_16x16x32_bf16 v[76:79], v[132:135], v[218:221], v[76:79]
	v_mfma_f32_16x16x32_bf16 v[72:75], v[140:143], v[218:221], v[72:75]
	s_setprio 0
	s_setprio 1
	v_mfma_f32_16x16x32_bf16 v[116:119], v[144:147], v[190:193], v[116:119]
	v_mfma_f32_16x16x32_bf16 v[112:115], v[170:173], v[190:193], v[112:115]
	v_mfma_f32_16x16x32_bf16 v[100:103], v[144:147], v[198:201], v[100:103]
	v_mfma_f32_16x16x32_bf16 v[96:99], v[170:173], v[198:201], v[96:99]
	v_mfma_f32_16x16x32_bf16 v[84:87], v[144:147], v[206:209], v[84:87]
	v_mfma_f32_16x16x32_bf16 v[80:83], v[170:173], v[206:209], v[80:83]
	v_mfma_f32_16x16x32_bf16 v[68:71], v[144:147], v[214:217], v[68:71]
	v_mfma_f32_16x16x32_bf16 v[64:67], v[170:173], v[214:217], v[64:67]
	v_mfma_f32_16x16x32_bf16 v[116:119], v[148:151], v[194:197], v[116:119]
	v_mfma_f32_16x16x32_bf16 v[112:115], v[186:189], v[194:197], v[112:115]
	v_mfma_f32_16x16x32_bf16 v[100:103], v[148:151], v[202:205], v[100:103]
	v_mfma_f32_16x16x32_bf16 v[96:99], v[186:189], v[202:205], v[96:99]
	v_mfma_f32_16x16x32_bf16 v[84:87], v[148:151], v[210:213], v[84:87]
	v_mfma_f32_16x16x32_bf16 v[80:83], v[186:189], v[210:213], v[80:83]
	v_mfma_f32_16x16x32_bf16 v[68:71], v[148:151], v[218:221], v[68:71]
	v_mfma_f32_16x16x32_bf16 v[64:67], v[186:189], v[218:221], v[64:67]
	s_setprio 0
	s_barrier
	s_add_i32 s16, s47, s22
	v_lshl_add_u64 v[182:183], v[182:183], 0, s[8:9]
	s_mov_b32 m0, s16
	ds_read_b128 v[190:193], v179 offset:49152
	ds_read_b128 v[194:197], v179 offset:50176
	ds_read_b128 v[198:201], v179 offset:51200
	ds_read_b128 v[202:205], v179 offset:52224
	ds_read_b128 v[206:209], v179 offset:53248
	ds_read_b128 v[210:213], v179 offset:54272
	ds_read_b128 v[214:217], v179 offset:55296
	ds_read_b128 v[218:221], v179 offset:56320
	global_load_lds_dwordx4 v[182:183], off
	s_add_i32 m0, s16, 0x2000
	s_add_u32 s16, s18, 0x160080
	v_lshl_add_u64 v[182:183], v[222:223], 0, s[8:9]
	s_addc_u32 s17, s19, 0
	s_add_i32 s18, s48, s22
	global_load_lds_dwordx4 v[182:183], off
	v_lshl_add_u64 v[182:183], s[16:17], 0, v[154:155]
	s_mov_b32 m0, s18
	s_nop 0
	global_load_lds_dwordx4 v[182:183], off
	v_lshl_add_u64 v[182:183], s[16:17], 0, v[158:159]
	s_add_i32 m0, s18, 0x2000
	s_nop 0
	global_load_lds_dwordx4 v[182:183], off
	v_lshl_add_u64 v[182:183], v[224:225], 0, s[8:9]
	s_mov_b32 m0, s33
	s_nop 0
	global_load_lds_dwordx4 v[182:183], off
	v_lshl_add_u64 v[182:183], v[226:227], 0, s[8:9]
	s_mov_b32 m0, s34
	s_nop 0
	global_load_lds_dwordx4 v[182:183], off
	s_waitcnt vmcnt(8)
	s_waitcnt lgkmcnt(0)
	s_barrier
	s_setprio 1
	v_mfma_f32_16x16x32_bf16 v[60:63], v[128:131], v[190:193], v[60:63]
	v_mfma_f32_16x16x32_bf16 v[56:59], v[136:139], v[190:193], v[56:59]
	v_mfma_f32_16x16x32_bf16 v[44:47], v[128:131], v[198:201], v[44:47]
	v_mfma_f32_16x16x32_bf16 v[40:43], v[136:139], v[198:201], v[40:43]
	v_mfma_f32_16x16x32_bf16 v[28:31], v[128:131], v[206:209], v[28:31]
	v_mfma_f32_16x16x32_bf16 v[24:27], v[136:139], v[206:209], v[24:27]
	v_mfma_f32_16x16x32_bf16 v[12:15], v[128:131], v[214:217], v[12:15]
	v_mfma_f32_16x16x32_bf16 v[8:11], v[136:139], v[214:217], v[8:11]
	v_mfma_f32_16x16x32_bf16 v[60:63], v[132:135], v[194:197], v[60:63]
	v_mfma_f32_16x16x32_bf16 v[56:59], v[140:143], v[194:197], v[56:59]
	v_mfma_f32_16x16x32_bf16 v[44:47], v[132:135], v[202:205], v[44:47]
	v_mfma_f32_16x16x32_bf16 v[40:43], v[140:143], v[202:205], v[40:43]
	v_mfma_f32_16x16x32_bf16 v[28:31], v[132:135], v[210:213], v[28:31]
	v_mfma_f32_16x16x32_bf16 v[24:27], v[140:143], v[210:213], v[24:27]
	v_mfma_f32_16x16x32_bf16 v[12:15], v[132:135], v[218:221], v[12:15]
	v_mfma_f32_16x16x32_bf16 v[8:11], v[140:143], v[218:221], v[8:11]
	s_setprio 0
	s_setprio 1
	v_mfma_f32_16x16x32_bf16 v[52:55], v[144:147], v[190:193], v[52:55]
	v_mfma_f32_16x16x32_bf16 v[48:51], v[170:173], v[190:193], v[48:51]
	v_mfma_f32_16x16x32_bf16 v[36:39], v[144:147], v[198:201], v[36:39]
	v_mfma_f32_16x16x32_bf16 v[32:35], v[170:173], v[198:201], v[32:35]
	v_mfma_f32_16x16x32_bf16 v[20:23], v[144:147], v[206:209], v[20:23]
	v_mfma_f32_16x16x32_bf16 v[16:19], v[170:173], v[206:209], v[16:19]
	v_mfma_f32_16x16x32_bf16 v[4:7], v[144:147], v[214:217], v[4:7]
	v_mfma_f32_16x16x32_bf16 v[0:3], v[170:173], v[214:217], v[0:3]
	v_mfma_f32_16x16x32_bf16 v[52:55], v[148:151], v[194:197], v[52:55]
	v_mfma_f32_16x16x32_bf16 v[48:51], v[186:189], v[194:197], v[48:51]
	v_mfma_f32_16x16x32_bf16 v[36:39], v[148:151], v[202:205], v[36:39]
	v_mfma_f32_16x16x32_bf16 v[32:35], v[186:189], v[202:205], v[32:35]
	v_mfma_f32_16x16x32_bf16 v[20:23], v[148:151], v[210:213], v[20:23]
	v_mfma_f32_16x16x32_bf16 v[16:19], v[186:189], v[210:213], v[16:19]
	v_mfma_f32_16x16x32_bf16 v[4:7], v[148:151], v[218:221], v[4:7]
	v_mfma_f32_16x16x32_bf16 v[0:3], v[186:189], v[218:221], v[0:3]
	s_setprio 0
	s_barrier
	s_add_i32 s46, s46, 2
	s_add_u32 s44, s44, 0x100
	s_addc_u32 s45, s45, 0
	s_cmpk_gt_u32 s46, 0x55
	s_mov_b64 s[16:17], s[0:1]
	s_cbranch_scc0 .LBB0_714
	s_and_b64 vcc, exec, s[10:11]
	s_cbranch_vccz .LBB0_717
	s_barrier

.LBB0_800:
	ds_read_b128 v[158:161], v152
	ds_read_b128 v[162:165], v152 offset:1024
	ds_read_b128 v[166:169], v152 offset:2048
	ds_read_b128 v[170:173], v152 offset:3072
	ds_read_b128 v[174:177], v153
	ds_read_b128 v[178:181], v153 offset:1024
	ds_read_b128 v[186:189], v153 offset:2048
	ds_read_b128 v[190:193], v153 offset:3072
	s_add_u32 s28, s26, 0xfff80080
	s_addc_u32 s29, s27, -1
	s_cmp_eq_u32 s53, 28
	s_cselect_b32 s31, s1, s29
	s_cselect_b32 s30, s17, s28
	s_cselect_b32 s29, s15, s52
	s_cselect_b32 s28, s50, s51
	v_lshl_add_u64 v[146:147], s[26:27], 0, v[138:139]
	s_add_i32 m0, s23, 0xc000
	ds_read_b128 v[194:197], v154
	ds_read_b128 v[198:201], v154 offset:1024
	ds_read_b128 v[202:205], v154 offset:2048
	ds_read_b128 v[206:209], v154 offset:3072
	ds_read_b128 v[210:213], v154 offset:4096
	ds_read_b128 v[214:217], v154 offset:5120
	ds_read_b128 v[218:221], v154 offset:6144
	ds_read_b128 v[222:225], v154 offset:7168
	global_load_lds_dwordx4 v[146:147], off
	v_lshl_add_u64 v[146:147], s[26:27], 0, v[140:141]
	s_add_i32 m0, s23, 0xe000
	s_nop 0
	global_load_lds_dwordx4 v[146:147], off
	s_waitcnt vmcnt(8)
	s_waitcnt lgkmcnt(0)
	s_barrier
	s_setprio 1
	v_mfma_f32_16x16x32_bf16 v[124:127], v[158:161], v[194:197], v[124:127]
	v_mfma_f32_16x16x32_bf16 v[120:123], v[166:169], v[194:197], v[120:123]
	v_mfma_f32_16x16x32_bf16 v[108:111], v[158:161], v[202:205], v[108:111]
	v_mfma_f32_16x16x32_bf16 v[104:107], v[166:169], v[202:205], v[104:107]
	v_mfma_f32_16x16x32_bf16 v[92:95], v[158:161], v[210:213], v[92:95]
	v_mfma_f32_16x16x32_bf16 v[88:91], v[166:169], v[210:213], v[88:91]
	v_mfma_f32_16x16x32_bf16 v[76:79], v[158:161], v[218:221], v[76:79]
	v_mfma_f32_16x16x32_bf16 v[72:75], v[166:169], v[218:221], v[72:75]
	v_mfma_f32_16x16x32_bf16 v[124:127], v[162:165], v[198:201], v[124:127]
	v_mfma_f32_16x16x32_bf16 v[120:123], v[170:173], v[198:201], v[120:123]
	v_mfma_f32_16x16x32_bf16 v[108:111], v[162:165], v[206:209], v[108:111]
	v_mfma_f32_16x16x32_bf16 v[104:107], v[170:173], v[206:209], v[104:107]
	v_mfma_f32_16x16x32_bf16 v[92:95], v[162:165], v[214:217], v[92:95]
	v_mfma_f32_16x16x32_bf16 v[88:91], v[170:173], v[214:217], v[88:91]
	v_mfma_f32_16x16x32_bf16 v[76:79], v[162:165], v[222:225], v[76:79]
	v_mfma_f32_16x16x32_bf16 v[72:75], v[170:173], v[222:225], v[72:75]
	s_setprio 0
	s_setprio 1
	v_mfma_f32_16x16x32_bf16 v[116:119], v[174:177], v[194:197], v[116:119]
	v_mfma_f32_16x16x32_bf16 v[112:115], v[186:189], v[194:197], v[112:115]
	v_mfma_f32_16x16x32_bf16 v[100:103], v[174:177], v[202:205], v[100:103]
	v_mfma_f32_16x16x32_bf16 v[96:99], v[186:189], v[202:205], v[96:99]
	v_mfma_f32_16x16x32_bf16 v[84:87], v[174:177], v[210:213], v[84:87]
	v_mfma_f32_16x16x32_bf16 v[80:83], v[186:189], v[210:213], v[80:83]
	v_mfma_f32_16x16x32_bf16 v[68:71], v[174:177], v[218:221], v[68:71]
	v_mfma_f32_16x16x32_bf16 v[64:67], v[186:189], v[218:221], v[64:67]
	v_mfma_f32_16x16x32_bf16 v[116:119], v[178:181], v[198:201], v[116:119]
	v_mfma_f32_16x16x32_bf16 v[112:115], v[190:193], v[198:201], v[112:115]
	v_mfma_f32_16x16x32_bf16 v[100:103], v[178:181], v[206:209], v[100:103]
	v_mfma_f32_16x16x32_bf16 v[96:99], v[190:193], v[206:209], v[96:99]
	v_mfma_f32_16x16x32_bf16 v[84:87], v[178:181], v[214:217], v[84:87]
	v_mfma_f32_16x16x32_bf16 v[80:83], v[190:193], v[214:217], v[80:83]
	v_mfma_f32_16x16x32_bf16 v[68:71], v[178:181], v[222:225], v[68:71]
	v_mfma_f32_16x16x32_bf16 v[64:67], v[190:193], v[222:225], v[64:67]
	s_setprio 0
	s_barrier
	s_add_i32 s54, s46, s33
	v_lshl_add_u64 v[146:147], s[28:29], 0, v[130:131]
	s_mov_b32 m0, s54
	ds_read_b128 v[194:197], v154 offset:16384
	ds_read_b128 v[198:201], v154 offset:17408
	ds_read_b128 v[202:205], v154 offset:18432
	ds_read_b128 v[206:209], v154 offset:19456
	ds_read_b128 v[210:213], v154 offset:20480
	ds_read_b128 v[214:217], v154 offset:21504
	ds_read_b128 v[218:221], v154 offset:22528
	ds_read_b128 v[222:225], v154 offset:23552
	global_load_lds_dwordx4 v[146:147], off
	s_add_i32 m0, s54, 0x2000
	s_add_u32 s54, s28, 0x80000
	v_lshl_add_u64 v[182:183], s[28:29], 0, v[134:135]
	s_addc_u32 s55, s29, 0
	s_add_i32 s56, s47, s33
	global_load_lds_dwordx4 v[182:183], off
	v_lshl_add_u64 v[226:227], s[54:55], 0, v[130:131]
	s_mov_b32 m0, s56
	v_lshl_add_u64 v[228:229], s[30:31], 0, v[132:133]
	global_load_lds_dwordx4 v[226:227], off
	v_lshl_add_u64 v[226:227], s[54:55], 0, v[134:135]
	s_add_i32 m0, s56, 0x2000
	s_nop 0
	global_load_lds_dwordx4 v[226:227], off
	v_lshl_add_u64 v[226:227], s[30:31], 0, v[128:129]
	s_mov_b32 m0, s23
	s_nop 0
	global_load_lds_dwordx4 v[226:227], off
	s_mov_b32 m0, s34
	s_nop 0
	global_load_lds_dwordx4 v[228:229], off
	s_waitcnt vmcnt(8)
	s_waitcnt lgkmcnt(0)
	s_barrier
	s_setprio 1
	v_mfma_f32_16x16x32_bf16 v[60:63], v[158:161], v[194:197], v[60:63]
	v_mfma_f32_16x16x32_bf16 v[56:59], v[166:169], v[194:197], v[56:59]
	v_mfma_f32_16x16x32_bf16 v[44:47], v[158:161], v[202:205], v[44:47]
	v_mfma_f32_16x16x32_bf16 v[40:43], v[166:169], v[202:205], v[40:43]
	v_mfma_f32_16x16x32_bf16 v[28:31], v[158:161], v[210:213], v[28:31]
	v_mfma_f32_16x16x32_bf16 v[24:27], v[166:169], v[210:213], v[24:27]
	v_mfma_f32_16x16x32_bf16 v[12:15], v[158:161], v[218:221], v[12:15]
	v_mfma_f32_16x16x32_bf16 v[8:11], v[166:169], v[218:221], v[8:11]
	v_mfma_f32_16x16x32_bf16 v[60:63], v[162:165], v[198:201], v[60:63]
	v_mfma_f32_16x16x32_bf16 v[56:59], v[170:173], v[198:201], v[56:59]
	v_mfma_f32_16x16x32_bf16 v[44:47], v[162:165], v[206:209], v[44:47]
	v_mfma_f32_16x16x32_bf16 v[40:43], v[170:173], v[206:209], v[40:43]
	v_mfma_f32_16x16x32_bf16 v[28:31], v[162:165], v[214:217], v[28:31]
	v_mfma_f32_16x16x32_bf16 v[24:27], v[170:173], v[214:217], v[24:27]
	v_mfma_f32_16x16x32_bf16 v[12:15], v[162:165], v[222:225], v[12:15]
	v_mfma_f32_16x16x32_bf16 v[8:11], v[170:173], v[222:225], v[8:11]
	s_setprio 0
	s_setprio 1
	v_mfma_f32_16x16x32_bf16 v[52:55], v[174:177], v[194:197], v[52:55]
	v_mfma_f32_16x16x32_bf16 v[48:51], v[186:189], v[194:197], v[48:51]
	v_mfma_f32_16x16x32_bf16 v[36:39], v[174:177], v[202:205], v[36:39]
	v_mfma_f32_16x16x32_bf16 v[32:35], v[186:189], v[202:205], v[32:35]
	v_mfma_f32_16x16x32_bf16 v[20:23], v[174:177], v[210:213], v[20:23]
	v_mfma_f32_16x16x32_bf16 v[16:19], v[186:189], v[210:213], v[16:19]
	v_mfma_f32_16x16x32_bf16 v[4:7], v[174:177], v[218:221], v[4:7]
	v_mfma_f32_16x16x32_bf16 v[0:3], v[186:189], v[218:221], v[0:3]
	v_mfma_f32_16x16x32_bf16 v[52:55], v[178:181], v[198:201], v[52:55]
	v_mfma_f32_16x16x32_bf16 v[48:51], v[190:193], v[198:201], v[48:51]
	v_mfma_f32_16x16x32_bf16 v[36:39], v[178:181], v[206:209], v[36:39]
	v_mfma_f32_16x16x32_bf16 v[32:35], v[190:193], v[206:209], v[32:35]
	v_mfma_f32_16x16x32_bf16 v[20:23], v[178:181], v[214:217], v[20:23]
	v_mfma_f32_16x16x32_bf16 v[16:19], v[190:193], v[214:217], v[16:19]
	v_mfma_f32_16x16x32_bf16 v[4:7], v[178:181], v[222:225], v[4:7]
	v_mfma_f32_16x16x32_bf16 v[0:3], v[190:193], v[222:225], v[0:3]
	s_setprio 0
	s_barrier
	s_add_i32 s54, 0, 0x18000
	v_add_u32_e32 v136, s54, v151
	s_add_i32 s55, 0, 0x1c000
	ds_read_b128 v[158:161], v136
	ds_read_b128 v[162:165], v136 offset:1024
	ds_read_b128 v[166:169], v136 offset:2048
	ds_read_b128 v[170:173], v136 offset:3072
	v_add_u32_e32 v136, s55, v151
	ds_read_b128 v[174:177], v136
	ds_read_b128 v[178:181], v136 offset:1024
	ds_read_b128 v[186:189], v136 offset:2048
	ds_read_b128 v[190:193], v136 offset:3072
	s_add_u32 s30, s30, 0x80000
	s_addc_u32 s31, s31, 0
	s_mov_b32 m0, s35
	v_lshl_add_u64 v[230:231], s[30:31], 0, v[128:129]
	ds_read_b128 v[194:197], v154 offset:32768
	ds_read_b128 v[198:201], v154 offset:33792
	ds_read_b128 v[202:205], v154 offset:34816
	ds_read_b128 v[206:209], v154 offset:35840
	ds_read_b128 v[210:213], v154 offset:36864
	ds_read_b128 v[214:217], v154 offset:37888
	ds_read_b128 v[218:221], v154 offset:38912
	ds_read_b128 v[222:225], v154 offset:39936
	global_load_lds_dwordx4 v[230:231], off
	v_lshl_add_u64 v[230:231], s[30:31], 0, v[132:133]
	s_mov_b32 m0, s36
	s_nop 0
	global_load_lds_dwordx4 v[230:231], off
	s_waitcnt vmcnt(8)
	s_waitcnt lgkmcnt(0)
	s_barrier
	s_setprio 1
	v_mfma_f32_16x16x32_bf16 v[124:127], v[158:161], v[194:197], v[124:127]
	v_mfma_f32_16x16x32_bf16 v[120:123], v[166:169], v[194:197], v[120:123]
	v_mfma_f32_16x16x32_bf16 v[108:111], v[158:161], v[202:205], v[108:111]
	v_mfma_f32_16x16x32_bf16 v[104:107], v[166:169], v[202:205], v[104:107]
	v_mfma_f32_16x16x32_bf16 v[92:95], v[158:161], v[210:213], v[92:95]
	v_mfma_f32_16x16x32_bf16 v[88:91], v[166:169], v[210:213], v[88:91]
	v_mfma_f32_16x16x32_bf16 v[76:79], v[158:161], v[218:221], v[76:79]
	v_mfma_f32_16x16x32_bf16 v[72:75], v[166:169], v[218:221], v[72:75]
	v_mfma_f32_16x16x32_bf16 v[124:127], v[162:165], v[198:201], v[124:127]
	v_mfma_f32_16x16x32_bf16 v[120:123], v[170:173], v[198:201], v[120:123]
	v_mfma_f32_16x16x32_bf16 v[108:111], v[162:165], v[206:209], v[108:111]
	v_mfma_f32_16x16x32_bf16 v[104:107], v[170:173], v[206:209], v[104:107]
	v_mfma_f32_16x16x32_bf16 v[92:95], v[162:165], v[214:217], v[92:95]
	v_mfma_f32_16x16x32_bf16 v[88:91], v[170:173], v[214:217], v[88:91]
	v_mfma_f32_16x16x32_bf16 v[76:79], v[162:165], v[222:225], v[76:79]
	v_mfma_f32_16x16x32_bf16 v[72:75], v[170:173], v[222:225], v[72:75]
	s_setprio 0
	s_setprio 1
	v_mfma_f32_16x16x32_bf16 v[116:119], v[174:177], v[194:197], v[116:119]
	v_mfma_f32_16x16x32_bf16 v[112:115], v[186:189], v[194:197], v[112:115]
	v_mfma_f32_16x16x32_bf16 v[100:103], v[174:177], v[202:205], v[100:103]
	v_mfma_f32_16x16x32_bf16 v[96:99], v[186:189], v[202:205], v[96:99]
	v_mfma_f32_16x16x32_bf16 v[84:87], v[174:177], v[210:213], v[84:87]
	v_mfma_f32_16x16x32_bf16 v[80:83], v[186:189], v[210:213], v[80:83]
	v_mfma_f32_16x16x32_bf16 v[68:71], v[174:177], v[218:221], v[68:71]
	v_mfma_f32_16x16x32_bf16 v[64:67], v[186:189], v[218:221], v[64:67]
	v_mfma_f32_16x16x32_bf16 v[116:119], v[178:181], v[198:201], v[116:119]
	v_mfma_f32_16x16x32_bf16 v[112:115], v[190:193], v[198:201], v[112:115]
	v_mfma_f32_16x16x32_bf16 v[100:103], v[178:181], v[206:209], v[100:103]
	v_mfma_f32_16x16x32_bf16 v[96:99], v[190:193], v[206:209], v[96:99]
	v_mfma_f32_16x16x32_bf16 v[84:87], v[178:181], v[214:217], v[84:87]
	v_mfma_f32_16x16x32_bf16 v[80:83], v[190:193], v[214:217], v[80:83]
	v_mfma_f32_16x16x32_bf16 v[68:71], v[178:181], v[222:225], v[68:71]
	v_mfma_f32_16x16x32_bf16 v[64:67], v[190:193], v[222:225], v[64:67]
	s_setprio 0
	s_barrier
	s_add_i32 s30, s54, s33
	v_lshl_add_u64 v[146:147], v[146:147], 0, s[10:11]
	s_mov_b32 m0, s30
	ds_read_b128 v[194:197], v154 offset:49152
	ds_read_b128 v[198:201], v154 offset:50176
	ds_read_b128 v[202:205], v154 offset:51200
	ds_read_b128 v[206:209], v154 offset:52224
	ds_read_b128 v[210:213], v154 offset:53248
	ds_read_b128 v[214:217], v154 offset:54272
	ds_read_b128 v[218:221], v154 offset:55296
	ds_read_b128 v[222:225], v154 offset:56320
	global_load_lds_dwordx4 v[146:147], off
	s_add_i32 m0, s30, 0x2000
	s_add_u32 s28, s28, 0x80080
	v_lshl_add_u64 v[146:147], v[182:183], 0, s[10:11]
	s_addc_u32 s29, s29, 0
	s_add_i32 s30, s55, s33
	global_load_lds_dwordx4 v[146:147], off
	v_lshl_add_u64 v[146:147], s[28:29], 0, v[130:131]
	s_mov_b32 m0, s30
	s_nop 0
	global_load_lds_dwordx4 v[146:147], off
	v_lshl_add_u64 v[146:147], s[28:29], 0, v[134:135]
	s_add_i32 m0, s30, 0x2000
	s_nop 0
	global_load_lds_dwordx4 v[146:147], off
	v_lshl_add_u64 v[146:147], v[226:227], 0, s[10:11]
	s_mov_b32 m0, s41
	s_nop 0
	global_load_lds_dwordx4 v[146:147], off
	v_lshl_add_u64 v[146:147], v[228:229], 0, s[10:11]
	s_mov_b32 m0, s42
	s_nop 0
	global_load_lds_dwordx4 v[146:147], off
	s_waitcnt vmcnt(8)
	s_waitcnt lgkmcnt(0)
	s_barrier
	s_setprio 1
	v_mfma_f32_16x16x32_bf16 v[60:63], v[158:161], v[194:197], v[60:63]
	v_mfma_f32_16x16x32_bf16 v[56:59], v[166:169], v[194:197], v[56:59]
	v_mfma_f32_16x16x32_bf16 v[44:47], v[158:161], v[202:205], v[44:47]
	v_mfma_f32_16x16x32_bf16 v[40:43], v[166:169], v[202:205], v[40:43]
	v_mfma_f32_16x16x32_bf16 v[28:31], v[158:161], v[210:213], v[28:31]
	v_mfma_f32_16x16x32_bf16 v[24:27], v[166:169], v[210:213], v[24:27]
	v_mfma_f32_16x16x32_bf16 v[12:15], v[158:161], v[218:221], v[12:15]
	v_mfma_f32_16x16x32_bf16 v[8:11], v[166:169], v[218:221], v[8:11]
	v_mfma_f32_16x16x32_bf16 v[60:63], v[162:165], v[198:201], v[60:63]
	v_mfma_f32_16x16x32_bf16 v[56:59], v[170:173], v[198:201], v[56:59]
	v_mfma_f32_16x16x32_bf16 v[44:47], v[162:165], v[206:209], v[44:47]
	v_mfma_f32_16x16x32_bf16 v[40:43], v[170:173], v[206:209], v[40:43]
	v_mfma_f32_16x16x32_bf16 v[28:31], v[162:165], v[214:217], v[28:31]
	v_mfma_f32_16x16x32_bf16 v[24:27], v[170:173], v[214:217], v[24:27]
	v_mfma_f32_16x16x32_bf16 v[12:15], v[162:165], v[222:225], v[12:15]
	v_mfma_f32_16x16x32_bf16 v[8:11], v[170:173], v[222:225], v[8:11]
	s_setprio 0
	s_setprio 1
	v_mfma_f32_16x16x32_bf16 v[52:55], v[174:177], v[194:197], v[52:55]
	v_mfma_f32_16x16x32_bf16 v[48:51], v[186:189], v[194:197], v[48:51]
	v_mfma_f32_16x16x32_bf16 v[36:39], v[174:177], v[202:205], v[36:39]
	v_mfma_f32_16x16x32_bf16 v[32:35], v[186:189], v[202:205], v[32:35]
	v_mfma_f32_16x16x32_bf16 v[20:23], v[174:177], v[210:213], v[20:23]
	v_mfma_f32_16x16x32_bf16 v[16:19], v[186:189], v[210:213], v[16:19]
	v_mfma_f32_16x16x32_bf16 v[4:7], v[174:177], v[218:221], v[4:7]
	v_mfma_f32_16x16x32_bf16 v[0:3], v[186:189], v[218:221], v[0:3]
	v_mfma_f32_16x16x32_bf16 v[52:55], v[178:181], v[198:201], v[52:55]
	v_mfma_f32_16x16x32_bf16 v[48:51], v[190:193], v[198:201], v[48:51]
	v_mfma_f32_16x16x32_bf16 v[36:39], v[178:181], v[206:209], v[36:39]
	v_mfma_f32_16x16x32_bf16 v[32:35], v[190:193], v[206:209], v[32:35]
	v_mfma_f32_16x16x32_bf16 v[20:23], v[178:181], v[214:217], v[20:23]
	v_mfma_f32_16x16x32_bf16 v[16:19], v[190:193], v[214:217], v[16:19]
	v_mfma_f32_16x16x32_bf16 v[4:7], v[178:181], v[222:225], v[4:7]
	v_mfma_f32_16x16x32_bf16 v[0:3], v[190:193], v[222:225], v[0:3]
	s_setprio 0
	s_barrier
	s_add_i32 s53, s53, 2
	s_add_u32 s26, s26, 0x100
	s_addc_u32 s27, s27, 0
	s_add_u32 s51, s51, 0x100
	s_addc_u32 s52, s52, 0
	s_cmp_gt_u32 s53, 29
	s_cbranch_scc0 .LBB0_800
	s_and_b64 vcc, exec, s[12:13]
	s_cbranch_vccz .LBB0_803
	s_barrier

.LBB0_896:
	ds_read_b128 v[104:107], v215
	ds_read_b128 v[108:111], v215 offset:1024
	ds_read_b128 v[124:127], v215 offset:2048
	ds_read_b128 v[132:135], v215 offset:3072
	ds_read_b128 v[144:147], v216
	ds_read_b128 v[148:151], v216 offset:1024
	ds_read_b128 v[152:155], v216 offset:2048
	ds_read_b128 v[156:159], v216 offset:3072
	s_add_u32 s0, s6, 0x100
	s_addc_u32 s1, s7, 0
	s_cmp_eq_u32 s37, 4
	s_cselect_b32 s31, s21, s1
	s_cselect_b32 s30, s20, s0
	s_cselect_b32 s29, s19, s36
	s_cselect_b32 s28, s27, s35
	v_lshl_add_u64 v[220:221], s[6:7], 0, v[196:197]
	s_add_i32 m0, s33, 0xc000
	ds_read_b128 v[160:163], v217
	ds_read_b128 v[164:167], v217 offset:1024
	ds_read_b128 v[168:171], v217 offset:2048
	ds_read_b128 v[172:175], v217 offset:3072
	ds_read_b128 v[176:179], v217 offset:4096
	ds_read_b128 v[180:183], v217 offset:5120
	ds_read_b128 v[204:207], v217 offset:6144
	ds_read_b128 v[208:211], v217 offset:7168
	global_load_lds_dwordx4 v[220:221], off
	v_lshl_add_u64 v[220:221], s[6:7], 0, v[198:199]
	s_add_i32 m0, s33, 0xe000
	s_nop 0
	global_load_lds_dwordx4 v[220:221], off
	s_waitcnt vmcnt(8)
	s_waitcnt lgkmcnt(0)
	s_barrier
	s_setprio 1
	v_mfma_f32_16x16x32_bf16 v[140:143], v[104:107], v[160:163], v[140:143]
	v_mfma_f32_16x16x32_bf16 v[136:139], v[124:127], v[160:163], v[136:139]
	v_mfma_f32_16x16x32_bf16 v[116:119], v[104:107], v[168:171], v[116:119]
	v_mfma_f32_16x16x32_bf16 v[112:115], v[124:127], v[168:171], v[112:115]
	v_mfma_f32_16x16x32_bf16 v[92:95], v[104:107], v[176:179], v[92:95]
	v_mfma_f32_16x16x32_bf16 v[88:91], v[124:127], v[176:179], v[88:91]
	v_mfma_f32_16x16x32_bf16 v[76:79], v[104:107], v[204:207], v[76:79]
	v_mfma_f32_16x16x32_bf16 v[72:75], v[124:127], v[204:207], v[72:75]
	v_mfma_f32_16x16x32_bf16 v[140:143], v[108:111], v[164:167], v[140:143]
	v_mfma_f32_16x16x32_bf16 v[136:139], v[132:135], v[164:167], v[136:139]
	v_mfma_f32_16x16x32_bf16 v[116:119], v[108:111], v[172:175], v[116:119]
	v_mfma_f32_16x16x32_bf16 v[112:115], v[132:135], v[172:175], v[112:115]
	v_mfma_f32_16x16x32_bf16 v[92:95], v[108:111], v[180:183], v[92:95]
	v_mfma_f32_16x16x32_bf16 v[88:91], v[132:135], v[180:183], v[88:91]
	v_mfma_f32_16x16x32_bf16 v[76:79], v[108:111], v[208:211], v[76:79]
	v_mfma_f32_16x16x32_bf16 v[72:75], v[132:135], v[208:211], v[72:75]
	s_setprio 0
	s_setprio 1
	v_mfma_f32_16x16x32_bf16 v[128:131], v[144:147], v[160:163], v[128:131]
	v_mfma_f32_16x16x32_bf16 v[120:123], v[152:155], v[160:163], v[120:123]
	v_mfma_f32_16x16x32_bf16 v[100:103], v[144:147], v[168:171], v[100:103]
	v_mfma_f32_16x16x32_bf16 v[96:99], v[152:155], v[168:171], v[96:99]
	v_mfma_f32_16x16x32_bf16 v[84:87], v[144:147], v[176:179], v[84:87]
	v_mfma_f32_16x16x32_bf16 v[80:83], v[152:155], v[176:179], v[80:83]
	v_mfma_f32_16x16x32_bf16 v[68:71], v[144:147], v[204:207], v[68:71]
	v_mfma_f32_16x16x32_bf16 v[64:67], v[152:155], v[204:207], v[64:67]
	v_mfma_f32_16x16x32_bf16 v[128:131], v[148:151], v[164:167], v[128:131]
	v_mfma_f32_16x16x32_bf16 v[120:123], v[156:159], v[164:167], v[120:123]
	v_mfma_f32_16x16x32_bf16 v[100:103], v[148:151], v[172:175], v[100:103]
	v_mfma_f32_16x16x32_bf16 v[96:99], v[156:159], v[172:175], v[96:99]
	v_mfma_f32_16x16x32_bf16 v[84:87], v[148:151], v[180:183], v[84:87]
	v_mfma_f32_16x16x32_bf16 v[80:83], v[156:159], v[180:183], v[80:83]
	v_mfma_f32_16x16x32_bf16 v[68:71], v[148:151], v[208:211], v[68:71]
	v_mfma_f32_16x16x32_bf16 v[64:67], v[156:159], v[208:211], v[64:67]
	s_setprio 0
	s_barrier
	s_add_i32 s6, s52, s25
	v_lshl_add_u64 v[220:221], s[28:29], 0, v[188:189]
	s_mov_b32 m0, s6
	ds_read_b128 v[160:163], v217 offset:16384
	ds_read_b128 v[164:167], v217 offset:17408
	ds_read_b128 v[168:171], v217 offset:18432
	ds_read_b128 v[172:175], v217 offset:19456
	ds_read_b128 v[176:179], v217 offset:20480
	ds_read_b128 v[180:183], v217 offset:21504
	ds_read_b128 v[204:207], v217 offset:22528
	ds_read_b128 v[208:211], v217 offset:23552
	global_load_lds_dwordx4 v[220:221], off
	s_add_i32 m0, s6, 0x2000
	s_add_u32 s6, s28, 0x20000
	v_lshl_add_u64 v[222:223], s[28:29], 0, v[192:193]
	s_addc_u32 s7, s29, 0
	s_add_i32 s38, s53, s25
	global_load_lds_dwordx4 v[222:223], off
	v_lshl_add_u64 v[224:225], s[6:7], 0, v[188:189]
	s_mov_b32 m0, s38
	v_lshl_add_u64 v[226:227], s[30:31], 0, v[190:191]
	global_load_lds_dwordx4 v[224:225], off
	v_lshl_add_u64 v[224:225], s[6:7], 0, v[192:193]
	s_add_i32 m0, s38, 0x2000
	s_nop 0
	global_load_lds_dwordx4 v[224:225], off
	v_lshl_add_u64 v[224:225], s[30:31], 0, v[186:187]
	s_mov_b32 m0, s33
	s_nop 0
	global_load_lds_dwordx4 v[224:225], off
	s_mov_b32 m0, s40
	s_nop 0
	global_load_lds_dwordx4 v[226:227], off
	s_waitcnt vmcnt(8)
	s_waitcnt lgkmcnt(0)
	s_barrier
	s_setprio 1
	v_mfma_f32_16x16x32_bf16 v[60:63], v[104:107], v[160:163], v[60:63]
	v_mfma_f32_16x16x32_bf16 v[56:59], v[124:127], v[160:163], v[56:59]
	v_mfma_f32_16x16x32_bf16 v[44:47], v[104:107], v[168:171], v[44:47]
	v_mfma_f32_16x16x32_bf16 v[40:43], v[124:127], v[168:171], v[40:43]
	v_mfma_f32_16x16x32_bf16 v[28:31], v[104:107], v[176:179], v[28:31]
	v_mfma_f32_16x16x32_bf16 v[24:27], v[124:127], v[176:179], v[24:27]
	v_mfma_f32_16x16x32_bf16 v[12:15], v[104:107], v[204:207], v[12:15]
	v_mfma_f32_16x16x32_bf16 v[8:11], v[124:127], v[204:207], v[8:11]
	v_mfma_f32_16x16x32_bf16 v[60:63], v[108:111], v[164:167], v[60:63]
	v_mfma_f32_16x16x32_bf16 v[56:59], v[132:135], v[164:167], v[56:59]
	v_mfma_f32_16x16x32_bf16 v[44:47], v[108:111], v[172:175], v[44:47]
	v_mfma_f32_16x16x32_bf16 v[40:43], v[132:135], v[172:175], v[40:43]
	v_mfma_f32_16x16x32_bf16 v[28:31], v[108:111], v[180:183], v[28:31]
	v_mfma_f32_16x16x32_bf16 v[24:27], v[132:135], v[180:183], v[24:27]
	v_mfma_f32_16x16x32_bf16 v[12:15], v[108:111], v[208:211], v[12:15]
	v_mfma_f32_16x16x32_bf16 v[8:11], v[132:135], v[208:211], v[8:11]
	s_setprio 0
	s_setprio 1
	v_mfma_f32_16x16x32_bf16 v[52:55], v[144:147], v[160:163], v[52:55]
	v_mfma_f32_16x16x32_bf16 v[48:51], v[152:155], v[160:163], v[48:51]
	v_mfma_f32_16x16x32_bf16 v[36:39], v[144:147], v[168:171], v[36:39]
	v_mfma_f32_16x16x32_bf16 v[32:35], v[152:155], v[168:171], v[32:35]
	v_mfma_f32_16x16x32_bf16 v[20:23], v[144:147], v[176:179], v[20:23]
	v_mfma_f32_16x16x32_bf16 v[16:19], v[152:155], v[176:179], v[16:19]
	v_mfma_f32_16x16x32_bf16 v[4:7], v[144:147], v[204:207], v[4:7]
	v_mfma_f32_16x16x32_bf16 v[0:3], v[152:155], v[204:207], v[0:3]
	v_mfma_f32_16x16x32_bf16 v[52:55], v[148:151], v[164:167], v[52:55]
	v_mfma_f32_16x16x32_bf16 v[48:51], v[156:159], v[164:167], v[48:51]
	v_mfma_f32_16x16x32_bf16 v[36:39], v[148:151], v[172:175], v[36:39]
	v_mfma_f32_16x16x32_bf16 v[32:35], v[156:159], v[172:175], v[32:35]
	v_mfma_f32_16x16x32_bf16 v[20:23], v[148:151], v[180:183], v[20:23]
	v_mfma_f32_16x16x32_bf16 v[16:19], v[156:159], v[180:183], v[16:19]
	v_mfma_f32_16x16x32_bf16 v[4:7], v[148:151], v[208:211], v[4:7]
	v_mfma_f32_16x16x32_bf16 v[0:3], v[156:159], v[208:211], v[0:3]
	s_setprio 0
	s_barrier
	s_add_i32 s38, 0, 0x18000
	s_add_i32 s39, 0, 0x1c000
	v_add_u32_e32 v132, s38, v214
	v_add_u32_e32 v156, s39, v214
	ds_read_b128 v[104:107], v132
	ds_read_b128 v[108:111], v132 offset:1024
	ds_read_b128 v[124:127], v132 offset:2048
	ds_read_b128 v[132:135], v132 offset:3072
	ds_read_b128 v[144:147], v156
	ds_read_b128 v[148:151], v156 offset:1024
	ds_read_b128 v[152:155], v156 offset:2048
	ds_read_b128 v[156:159], v156 offset:3072
	s_add_u32 s6, s30, 0x50000
	s_addc_u32 s7, s31, 0
	s_mov_b32 m0, s41
	v_lshl_add_u64 v[228:229], s[6:7], 0, v[186:187]
	ds_read_b128 v[160:163], v217 offset:32768
	ds_read_b128 v[164:167], v217 offset:33792
	ds_read_b128 v[168:171], v217 offset:34816
	ds_read_b128 v[172:175], v217 offset:35840
	ds_read_b128 v[176:179], v217 offset:36864
	ds_read_b128 v[180:183], v217 offset:37888
	ds_read_b128 v[204:207], v217 offset:38912
	ds_read_b128 v[208:211], v217 offset:39936
	global_load_lds_dwordx4 v[228:229], off
	v_lshl_add_u64 v[228:229], s[6:7], 0, v[190:191]
	s_mov_b32 m0, s42
	s_nop 0
	global_load_lds_dwordx4 v[228:229], off
	s_waitcnt vmcnt(8)
	s_waitcnt lgkmcnt(0)
	s_barrier
	s_setprio 1
	v_mfma_f32_16x16x32_bf16 v[140:143], v[104:107], v[160:163], v[140:143]
	v_mfma_f32_16x16x32_bf16 v[136:139], v[124:127], v[160:163], v[136:139]
	v_mfma_f32_16x16x32_bf16 v[116:119], v[104:107], v[168:171], v[116:119]
	v_mfma_f32_16x16x32_bf16 v[112:115], v[124:127], v[168:171], v[112:115]
	v_mfma_f32_16x16x32_bf16 v[92:95], v[104:107], v[176:179], v[92:95]
	v_mfma_f32_16x16x32_bf16 v[88:91], v[124:127], v[176:179], v[88:91]
	v_mfma_f32_16x16x32_bf16 v[76:79], v[104:107], v[204:207], v[76:79]
	v_mfma_f32_16x16x32_bf16 v[72:75], v[124:127], v[204:207], v[72:75]
	v_mfma_f32_16x16x32_bf16 v[140:143], v[108:111], v[164:167], v[140:143]
	v_mfma_f32_16x16x32_bf16 v[136:139], v[132:135], v[164:167], v[136:139]
	v_mfma_f32_16x16x32_bf16 v[116:119], v[108:111], v[172:175], v[116:119]
	v_mfma_f32_16x16x32_bf16 v[112:115], v[132:135], v[172:175], v[112:115]
	v_mfma_f32_16x16x32_bf16 v[92:95], v[108:111], v[180:183], v[92:95]
	v_mfma_f32_16x16x32_bf16 v[88:91], v[132:135], v[180:183], v[88:91]
	v_mfma_f32_16x16x32_bf16 v[76:79], v[108:111], v[208:211], v[76:79]
	v_mfma_f32_16x16x32_bf16 v[72:75], v[132:135], v[208:211], v[72:75]
	s_setprio 0
	s_setprio 1
	v_mfma_f32_16x16x32_bf16 v[128:131], v[144:147], v[160:163], v[128:131]
	v_mfma_f32_16x16x32_bf16 v[120:123], v[152:155], v[160:163], v[120:123]
	v_mfma_f32_16x16x32_bf16 v[100:103], v[144:147], v[168:171], v[100:103]
	v_mfma_f32_16x16x32_bf16 v[96:99], v[152:155], v[168:171], v[96:99]
	v_mfma_f32_16x16x32_bf16 v[84:87], v[144:147], v[176:179], v[84:87]
	v_mfma_f32_16x16x32_bf16 v[80:83], v[152:155], v[176:179], v[80:83]
	v_mfma_f32_16x16x32_bf16 v[68:71], v[144:147], v[204:207], v[68:71]
	v_mfma_f32_16x16x32_bf16 v[64:67], v[152:155], v[204:207], v[64:67]
	v_mfma_f32_16x16x32_bf16 v[128:131], v[148:151], v[164:167], v[128:131]
	v_mfma_f32_16x16x32_bf16 v[120:123], v[156:159], v[164:167], v[120:123]
	v_mfma_f32_16x16x32_bf16 v[100:103], v[148:151], v[172:175], v[100:103]
	v_mfma_f32_16x16x32_bf16 v[96:99], v[156:159], v[172:175], v[96:99]
	v_mfma_f32_16x16x32_bf16 v[84:87], v[148:151], v[180:183], v[84:87]
	v_mfma_f32_16x16x32_bf16 v[80:83], v[156:159], v[180:183], v[80:83]
	v_mfma_f32_16x16x32_bf16 v[68:71], v[148:151], v[208:211], v[68:71]
	v_mfma_f32_16x16x32_bf16 v[64:67], v[156:159], v[208:211], v[64:67]
	s_setprio 0
	s_barrier
	s_add_i32 s6, s38, s25
	v_lshl_add_u64 v[220:221], v[220:221], 0, s[12:13]
	s_mov_b32 m0, s6
	ds_read_b128 v[160:163], v217 offset:49152
	ds_read_b128 v[164:167], v217 offset:50176
	ds_read_b128 v[168:171], v217 offset:51200
	ds_read_b128 v[172:175], v217 offset:52224
	ds_read_b128 v[176:179], v217 offset:53248
	ds_read_b128 v[180:183], v217 offset:54272
	ds_read_b128 v[204:207], v217 offset:55296
	ds_read_b128 v[208:211], v217 offset:56320
	global_load_lds_dwordx4 v[220:221], off
	s_add_i32 m0, s6, 0x2000
	s_add_u32 s6, s28, 0x20080
	v_lshl_add_u64 v[220:221], v[222:223], 0, s[12:13]
	s_addc_u32 s7, s29, 0
	s_add_i32 s28, s39, s25
	global_load_lds_dwordx4 v[220:221], off
	v_lshl_add_u64 v[220:221], s[6:7], 0, v[188:189]
	s_mov_b32 m0, s28
	s_nop 0
	global_load_lds_dwordx4 v[220:221], off
	v_lshl_add_u64 v[220:221], s[6:7], 0, v[192:193]
	s_add_i32 m0, s28, 0x2000
	s_nop 0
	global_load_lds_dwordx4 v[220:221], off
	v_lshl_add_u64 v[220:221], v[224:225], 0, s[12:13]
	s_mov_b32 m0, s46
	s_nop 0
	global_load_lds_dwordx4 v[220:221], off
	v_lshl_add_u64 v[220:221], v[226:227], 0, s[12:13]
	s_mov_b32 m0, s47
	s_nop 0
	global_load_lds_dwordx4 v[220:221], off
	s_waitcnt vmcnt(8)
	s_waitcnt lgkmcnt(0)
	s_barrier
	s_setprio 1
	v_mfma_f32_16x16x32_bf16 v[60:63], v[104:107], v[160:163], v[60:63]
	v_mfma_f32_16x16x32_bf16 v[56:59], v[124:127], v[160:163], v[56:59]
	v_mfma_f32_16x16x32_bf16 v[44:47], v[104:107], v[168:171], v[44:47]
	v_mfma_f32_16x16x32_bf16 v[40:43], v[124:127], v[168:171], v[40:43]
	v_mfma_f32_16x16x32_bf16 v[28:31], v[104:107], v[176:179], v[28:31]
	v_mfma_f32_16x16x32_bf16 v[24:27], v[124:127], v[176:179], v[24:27]
	v_mfma_f32_16x16x32_bf16 v[12:15], v[104:107], v[204:207], v[12:15]
	v_mfma_f32_16x16x32_bf16 v[8:11], v[124:127], v[204:207], v[8:11]
	v_mfma_f32_16x16x32_bf16 v[60:63], v[108:111], v[164:167], v[60:63]
	v_mfma_f32_16x16x32_bf16 v[56:59], v[132:135], v[164:167], v[56:59]
	v_mfma_f32_16x16x32_bf16 v[44:47], v[108:111], v[172:175], v[44:47]
	v_mfma_f32_16x16x32_bf16 v[40:43], v[132:135], v[172:175], v[40:43]
	v_mfma_f32_16x16x32_bf16 v[28:31], v[108:111], v[180:183], v[28:31]
	v_mfma_f32_16x16x32_bf16 v[24:27], v[132:135], v[180:183], v[24:27]
	v_mfma_f32_16x16x32_bf16 v[12:15], v[108:111], v[208:211], v[12:15]
	v_mfma_f32_16x16x32_bf16 v[8:11], v[132:135], v[208:211], v[8:11]
	s_setprio 0
	s_setprio 1
	v_mfma_f32_16x16x32_bf16 v[52:55], v[144:147], v[160:163], v[52:55]
	v_mfma_f32_16x16x32_bf16 v[48:51], v[152:155], v[160:163], v[48:51]
	v_mfma_f32_16x16x32_bf16 v[36:39], v[144:147], v[168:171], v[36:39]
	v_mfma_f32_16x16x32_bf16 v[32:35], v[152:155], v[168:171], v[32:35]
	v_mfma_f32_16x16x32_bf16 v[20:23], v[144:147], v[176:179], v[20:23]
	v_mfma_f32_16x16x32_bf16 v[16:19], v[152:155], v[176:179], v[16:19]
	v_mfma_f32_16x16x32_bf16 v[4:7], v[144:147], v[204:207], v[4:7]
	v_mfma_f32_16x16x32_bf16 v[0:3], v[152:155], v[204:207], v[0:3]
	v_mfma_f32_16x16x32_bf16 v[52:55], v[148:151], v[164:167], v[52:55]
	v_mfma_f32_16x16x32_bf16 v[48:51], v[156:159], v[164:167], v[48:51]
	v_mfma_f32_16x16x32_bf16 v[36:39], v[148:151], v[172:175], v[36:39]
	v_mfma_f32_16x16x32_bf16 v[32:35], v[156:159], v[172:175], v[32:35]
	v_mfma_f32_16x16x32_bf16 v[20:23], v[148:151], v[180:183], v[20:23]
	v_mfma_f32_16x16x32_bf16 v[16:19], v[156:159], v[180:183], v[16:19]
	v_mfma_f32_16x16x32_bf16 v[4:7], v[148:151], v[208:211], v[4:7]
	v_mfma_f32_16x16x32_bf16 v[0:3], v[156:159], v[208:211], v[0:3]
	s_setprio 0
	s_barrier
	s_add_i32 s37, s37, 2
	s_add_u32 s35, s35, 0x100
	s_addc_u32 s36, s36, 0
	s_cmp_gt_u32 s37, 5
	s_mov_b64 s[6:7], s[0:1]
	s_cbranch_scc0 .LBB0_896
	s_and_b64 vcc, exec, s[14:15]
	s_cbranch_vccz .LBB0_899
	s_barrier

.LBB0_1280:
	ds_read_b128 v[128:131], v177
	ds_read_b128 v[132:135], v177 offset:1024
	ds_read_b128 v[136:139], v177 offset:2048
	ds_read_b128 v[140:143], v177 offset:3072
	ds_read_b128 v[144:147], v178
	ds_read_b128 v[148:151], v178 offset:1024
	ds_read_b128 v[170:173], v178 offset:2048
	ds_read_b128 v[186:189], v178 offset:3072
	s_add_u32 s24, s22, 0xfff80080
	s_addc_u32 s25, s23, -1
	s_cmp_eq_u32 s47, 28
	s_cselect_b32 s27, s1, s25
	s_cselect_b32 s26, s15, s24
	s_cselect_b32 s25, s13, s46
	s_cselect_b32 s24, s44, s45
	v_lshl_add_u64 v[182:183], s[22:23], 0, v[162:163]
	s_add_i32 m0, s21, 0xc000
	ds_read_b128 v[190:193], v179
	ds_read_b128 v[194:197], v179 offset:1024
	ds_read_b128 v[198:201], v179 offset:2048
	ds_read_b128 v[202:205], v179 offset:3072
	ds_read_b128 v[206:209], v179 offset:4096
	ds_read_b128 v[210:213], v179 offset:5120
	ds_read_b128 v[214:217], v179 offset:6144
	ds_read_b128 v[218:221], v179 offset:7168
	global_load_lds_dwordx4 v[182:183], off
	v_lshl_add_u64 v[182:183], s[22:23], 0, v[164:165]
	s_add_i32 m0, s21, 0xe000
	s_nop 0
	global_load_lds_dwordx4 v[182:183], off
	s_waitcnt vmcnt(8)
	s_waitcnt lgkmcnt(0)
	s_barrier
	s_setprio 1
	v_mfma_f32_16x16x32_bf16 v[124:127], v[128:131], v[190:193], v[124:127]
	v_mfma_f32_16x16x32_bf16 v[120:123], v[136:139], v[190:193], v[120:123]
	v_mfma_f32_16x16x32_bf16 v[108:111], v[128:131], v[198:201], v[108:111]
	v_mfma_f32_16x16x32_bf16 v[104:107], v[136:139], v[198:201], v[104:107]
	v_mfma_f32_16x16x32_bf16 v[92:95], v[128:131], v[206:209], v[92:95]
	v_mfma_f32_16x16x32_bf16 v[88:91], v[136:139], v[206:209], v[88:91]
	v_mfma_f32_16x16x32_bf16 v[76:79], v[128:131], v[214:217], v[76:79]
	v_mfma_f32_16x16x32_bf16 v[72:75], v[136:139], v[214:217], v[72:75]
	v_mfma_f32_16x16x32_bf16 v[124:127], v[132:135], v[194:197], v[124:127]
	v_mfma_f32_16x16x32_bf16 v[120:123], v[140:143], v[194:197], v[120:123]
	v_mfma_f32_16x16x32_bf16 v[108:111], v[132:135], v[202:205], v[108:111]
	v_mfma_f32_16x16x32_bf16 v[104:107], v[140:143], v[202:205], v[104:107]
	v_mfma_f32_16x16x32_bf16 v[92:95], v[132:135], v[210:213], v[92:95]
	v_mfma_f32_16x16x32_bf16 v[88:91], v[140:143], v[210:213], v[88:91]
	v_mfma_f32_16x16x32_bf16 v[76:79], v[132:135], v[218:221], v[76:79]
	v_mfma_f32_16x16x32_bf16 v[72:75], v[140:143], v[218:221], v[72:75]
	s_setprio 0
	s_setprio 1
	v_mfma_f32_16x16x32_bf16 v[116:119], v[144:147], v[190:193], v[116:119]
	v_mfma_f32_16x16x32_bf16 v[112:115], v[170:173], v[190:193], v[112:115]
	v_mfma_f32_16x16x32_bf16 v[100:103], v[144:147], v[198:201], v[100:103]
	v_mfma_f32_16x16x32_bf16 v[96:99], v[170:173], v[198:201], v[96:99]
	v_mfma_f32_16x16x32_bf16 v[84:87], v[144:147], v[206:209], v[84:87]
	v_mfma_f32_16x16x32_bf16 v[80:83], v[170:173], v[206:209], v[80:83]
	v_mfma_f32_16x16x32_bf16 v[68:71], v[144:147], v[214:217], v[68:71]
	v_mfma_f32_16x16x32_bf16 v[64:67], v[170:173], v[214:217], v[64:67]
	v_mfma_f32_16x16x32_bf16 v[116:119], v[148:151], v[194:197], v[116:119]
	v_mfma_f32_16x16x32_bf16 v[112:115], v[186:189], v[194:197], v[112:115]
	v_mfma_f32_16x16x32_bf16 v[100:103], v[148:151], v[202:205], v[100:103]
	v_mfma_f32_16x16x32_bf16 v[96:99], v[186:189], v[202:205], v[96:99]
	v_mfma_f32_16x16x32_bf16 v[84:87], v[148:151], v[210:213], v[84:87]
	v_mfma_f32_16x16x32_bf16 v[80:83], v[186:189], v[210:213], v[80:83]
	v_mfma_f32_16x16x32_bf16 v[68:71], v[148:151], v[218:221], v[68:71]
	v_mfma_f32_16x16x32_bf16 v[64:67], v[186:189], v[218:221], v[64:67]
	s_setprio 0
	s_barrier
	s_add_i32 s48, s42, s28
	v_lshl_add_u64 v[182:183], s[24:25], 0, v[154:155]
	s_mov_b32 m0, s48
	ds_read_b128 v[190:193], v179 offset:16384
	ds_read_b128 v[194:197], v179 offset:17408
	ds_read_b128 v[198:201], v179 offset:18432
	ds_read_b128 v[202:205], v179 offset:19456
	ds_read_b128 v[206:209], v179 offset:20480
	ds_read_b128 v[210:213], v179 offset:21504
	ds_read_b128 v[214:217], v179 offset:22528
	ds_read_b128 v[218:221], v179 offset:23552
	global_load_lds_dwordx4 v[182:183], off
	s_add_i32 m0, s48, 0x2000
	s_add_u32 s48, s24, 0x80000
	v_lshl_add_u64 v[222:223], s[24:25], 0, v[158:159]
	s_addc_u32 s49, s25, 0
	s_add_i32 s50, s43, s28
	global_load_lds_dwordx4 v[222:223], off
	v_lshl_add_u64 v[224:225], s[48:49], 0, v[154:155]
	s_mov_b32 m0, s50
	v_lshl_add_u64 v[226:227], s[26:27], 0, v[156:157]
	global_load_lds_dwordx4 v[224:225], off
	v_lshl_add_u64 v[224:225], s[48:49], 0, v[158:159]
	s_add_i32 m0, s50, 0x2000
	s_nop 0
	global_load_lds_dwordx4 v[224:225], off
	v_lshl_add_u64 v[224:225], s[26:27], 0, v[152:153]
	s_mov_b32 m0, s21
	s_nop 0
	global_load_lds_dwordx4 v[224:225], off
	s_mov_b32 m0, s29
	s_nop 0
	global_load_lds_dwordx4 v[226:227], off
	s_waitcnt vmcnt(8)
	s_waitcnt lgkmcnt(0)
	s_barrier
	s_setprio 1
	v_mfma_f32_16x16x32_bf16 v[60:63], v[128:131], v[190:193], v[60:63]
	v_mfma_f32_16x16x32_bf16 v[56:59], v[136:139], v[190:193], v[56:59]
	v_mfma_f32_16x16x32_bf16 v[44:47], v[128:131], v[198:201], v[44:47]
	v_mfma_f32_16x16x32_bf16 v[40:43], v[136:139], v[198:201], v[40:43]
	v_mfma_f32_16x16x32_bf16 v[28:31], v[128:131], v[206:209], v[28:31]
	v_mfma_f32_16x16x32_bf16 v[24:27], v[136:139], v[206:209], v[24:27]
	v_mfma_f32_16x16x32_bf16 v[12:15], v[128:131], v[214:217], v[12:15]
	v_mfma_f32_16x16x32_bf16 v[8:11], v[136:139], v[214:217], v[8:11]
	v_mfma_f32_16x16x32_bf16 v[60:63], v[132:135], v[194:197], v[60:63]
	v_mfma_f32_16x16x32_bf16 v[56:59], v[140:143], v[194:197], v[56:59]
	v_mfma_f32_16x16x32_bf16 v[44:47], v[132:135], v[202:205], v[44:47]
	v_mfma_f32_16x16x32_bf16 v[40:43], v[140:143], v[202:205], v[40:43]
	v_mfma_f32_16x16x32_bf16 v[28:31], v[132:135], v[210:213], v[28:31]
	v_mfma_f32_16x16x32_bf16 v[24:27], v[140:143], v[210:213], v[24:27]
	v_mfma_f32_16x16x32_bf16 v[12:15], v[132:135], v[218:221], v[12:15]
	v_mfma_f32_16x16x32_bf16 v[8:11], v[140:143], v[218:221], v[8:11]
	s_setprio 0
	s_setprio 1
	v_mfma_f32_16x16x32_bf16 v[52:55], v[144:147], v[190:193], v[52:55]
	v_mfma_f32_16x16x32_bf16 v[48:51], v[170:173], v[190:193], v[48:51]
	v_mfma_f32_16x16x32_bf16 v[36:39], v[144:147], v[198:201], v[36:39]
	v_mfma_f32_16x16x32_bf16 v[32:35], v[170:173], v[198:201], v[32:35]
	v_mfma_f32_16x16x32_bf16 v[20:23], v[144:147], v[206:209], v[20:23]
	v_mfma_f32_16x16x32_bf16 v[16:19], v[170:173], v[206:209], v[16:19]
	v_mfma_f32_16x16x32_bf16 v[4:7], v[144:147], v[214:217], v[4:7]
	v_mfma_f32_16x16x32_bf16 v[0:3], v[170:173], v[214:217], v[0:3]
	v_mfma_f32_16x16x32_bf16 v[52:55], v[148:151], v[194:197], v[52:55]
	v_mfma_f32_16x16x32_bf16 v[48:51], v[186:189], v[194:197], v[48:51]
	v_mfma_f32_16x16x32_bf16 v[36:39], v[148:151], v[202:205], v[36:39]
	v_mfma_f32_16x16x32_bf16 v[32:35], v[186:189], v[202:205], v[32:35]
	v_mfma_f32_16x16x32_bf16 v[20:23], v[148:151], v[210:213], v[20:23]
	v_mfma_f32_16x16x32_bf16 v[16:19], v[186:189], v[210:213], v[16:19]
	v_mfma_f32_16x16x32_bf16 v[4:7], v[148:151], v[218:221], v[4:7]
	v_mfma_f32_16x16x32_bf16 v[0:3], v[186:189], v[218:221], v[0:3]
	s_setprio 0
	s_barrier
	s_add_i32 s48, 0, 0x18000
	s_add_i32 s49, 0, 0x1c000
	v_add_u32_e32 v140, s48, v176
	v_add_u32_e32 v160, s49, v176
	ds_read_b128 v[128:131], v140
	ds_read_b128 v[132:135], v140 offset:1024
	ds_read_b128 v[136:139], v140 offset:2048
	ds_read_b128 v[140:143], v140 offset:3072
	ds_read_b128 v[144:147], v160
	ds_read_b128 v[148:151], v160 offset:1024
	ds_read_b128 v[170:173], v160 offset:2048
	ds_read_b128 v[186:189], v160 offset:3072
	s_add_u32 s26, s26, 0x80000
	s_addc_u32 s27, s27, 0
	s_mov_b32 m0, s30
	v_lshl_add_u64 v[228:229], s[26:27], 0, v[152:153]
	ds_read_b128 v[190:193], v179 offset:32768
	ds_read_b128 v[194:197], v179 offset:33792
	ds_read_b128 v[198:201], v179 offset:34816
	ds_read_b128 v[202:205], v179 offset:35840
	ds_read_b128 v[206:209], v179 offset:36864
	ds_read_b128 v[210:213], v179 offset:37888
	ds_read_b128 v[214:217], v179 offset:38912
	ds_read_b128 v[218:221], v179 offset:39936
	global_load_lds_dwordx4 v[228:229], off
	v_lshl_add_u64 v[228:229], s[26:27], 0, v[156:157]
	s_mov_b32 m0, s31
	s_nop 0
	global_load_lds_dwordx4 v[228:229], off
	s_waitcnt vmcnt(8)
	s_waitcnt lgkmcnt(0)
	s_barrier
	s_setprio 1
	v_mfma_f32_16x16x32_bf16 v[124:127], v[128:131], v[190:193], v[124:127]
	v_mfma_f32_16x16x32_bf16 v[120:123], v[136:139], v[190:193], v[120:123]
	v_mfma_f32_16x16x32_bf16 v[108:111], v[128:131], v[198:201], v[108:111]
	v_mfma_f32_16x16x32_bf16 v[104:107], v[136:139], v[198:201], v[104:107]
	v_mfma_f32_16x16x32_bf16 v[92:95], v[128:131], v[206:209], v[92:95]
	v_mfma_f32_16x16x32_bf16 v[88:91], v[136:139], v[206:209], v[88:91]
	v_mfma_f32_16x16x32_bf16 v[76:79], v[128:131], v[214:217], v[76:79]
	v_mfma_f32_16x16x32_bf16 v[72:75], v[136:139], v[214:217], v[72:75]
	v_mfma_f32_16x16x32_bf16 v[124:127], v[132:135], v[194:197], v[124:127]
	v_mfma_f32_16x16x32_bf16 v[120:123], v[140:143], v[194:197], v[120:123]
	v_mfma_f32_16x16x32_bf16 v[108:111], v[132:135], v[202:205], v[108:111]
	v_mfma_f32_16x16x32_bf16 v[104:107], v[140:143], v[202:205], v[104:107]
	v_mfma_f32_16x16x32_bf16 v[92:95], v[132:135], v[210:213], v[92:95]
	v_mfma_f32_16x16x32_bf16 v[88:91], v[140:143], v[210:213], v[88:91]
	v_mfma_f32_16x16x32_bf16 v[76:79], v[132:135], v[218:221], v[76:79]
	v_mfma_f32_16x16x32_bf16 v[72:75], v[140:143], v[218:221], v[72:75]
	s_setprio 0
	s_setprio 1
	v_mfma_f32_16x16x32_bf16 v[116:119], v[144:147], v[190:193], v[116:119]
	v_mfma_f32_16x16x32_bf16 v[112:115], v[170:173], v[190:193], v[112:115]
	v_mfma_f32_16x16x32_bf16 v[100:103], v[144:147], v[198:201], v[100:103]
	v_mfma_f32_16x16x32_bf16 v[96:99], v[170:173], v[198:201], v[96:99]
	v_mfma_f32_16x16x32_bf16 v[84:87], v[144:147], v[206:209], v[84:87]
	v_mfma_f32_16x16x32_bf16 v[80:83], v[170:173], v[206:209], v[80:83]
	v_mfma_f32_16x16x32_bf16 v[68:71], v[144:147], v[214:217], v[68:71]
	v_mfma_f32_16x16x32_bf16 v[64:67], v[170:173], v[214:217], v[64:67]
	v_mfma_f32_16x16x32_bf16 v[116:119], v[148:151], v[194:197], v[116:119]
	v_mfma_f32_16x16x32_bf16 v[112:115], v[186:189], v[194:197], v[112:115]
	v_mfma_f32_16x16x32_bf16 v[100:103], v[148:151], v[202:205], v[100:103]
	v_mfma_f32_16x16x32_bf16 v[96:99], v[186:189], v[202:205], v[96:99]
	v_mfma_f32_16x16x32_bf16 v[84:87], v[148:151], v[210:213], v[84:87]
	v_mfma_f32_16x16x32_bf16 v[80:83], v[186:189], v[210:213], v[80:83]
	v_mfma_f32_16x16x32_bf16 v[68:71], v[148:151], v[218:221], v[68:71]
	v_mfma_f32_16x16x32_bf16 v[64:67], v[186:189], v[218:221], v[64:67]
	s_setprio 0
	s_barrier
	s_add_i32 s26, s48, s28
	v_lshl_add_u64 v[182:183], v[182:183], 0, s[8:9]
	s_mov_b32 m0, s26
	ds_read_b128 v[190:193], v179 offset:49152
	ds_read_b128 v[194:197], v179 offset:50176
	ds_read_b128 v[198:201], v179 offset:51200
	ds_read_b128 v[202:205], v179 offset:52224
	ds_read_b128 v[206:209], v179 offset:53248
	ds_read_b128 v[210:213], v179 offset:54272
	ds_read_b128 v[214:217], v179 offset:55296
	ds_read_b128 v[218:221], v179 offset:56320
	global_load_lds_dwordx4 v[182:183], off
	s_add_i32 m0, s26, 0x2000
	s_add_u32 s24, s24, 0x80080
	v_lshl_add_u64 v[182:183], v[222:223], 0, s[8:9]
	s_addc_u32 s25, s25, 0
	s_add_i32 s26, s49, s28
	global_load_lds_dwordx4 v[182:183], off
	v_lshl_add_u64 v[182:183], s[24:25], 0, v[154:155]
	s_mov_b32 m0, s26
	s_nop 0
	global_load_lds_dwordx4 v[182:183], off
	v_lshl_add_u64 v[182:183], s[24:25], 0, v[158:159]
	s_add_i32 m0, s26, 0x2000
	s_nop 0
	global_load_lds_dwordx4 v[182:183], off
	v_lshl_add_u64 v[182:183], v[224:225], 0, s[8:9]
	s_mov_b32 m0, s37
	s_nop 0
	global_load_lds_dwordx4 v[182:183], off
	v_lshl_add_u64 v[182:183], v[226:227], 0, s[8:9]
	s_mov_b32 m0, s38
	s_nop 0
	global_load_lds_dwordx4 v[182:183], off
	s_waitcnt vmcnt(8)
	s_waitcnt lgkmcnt(0)
	s_barrier
	s_setprio 1
	v_mfma_f32_16x16x32_bf16 v[60:63], v[128:131], v[190:193], v[60:63]
	v_mfma_f32_16x16x32_bf16 v[56:59], v[136:139], v[190:193], v[56:59]
	v_mfma_f32_16x16x32_bf16 v[44:47], v[128:131], v[198:201], v[44:47]
	v_mfma_f32_16x16x32_bf16 v[40:43], v[136:139], v[198:201], v[40:43]
	v_mfma_f32_16x16x32_bf16 v[28:31], v[128:131], v[206:209], v[28:31]
	v_mfma_f32_16x16x32_bf16 v[24:27], v[136:139], v[206:209], v[24:27]
	v_mfma_f32_16x16x32_bf16 v[12:15], v[128:131], v[214:217], v[12:15]
	v_mfma_f32_16x16x32_bf16 v[8:11], v[136:139], v[214:217], v[8:11]
	v_mfma_f32_16x16x32_bf16 v[60:63], v[132:135], v[194:197], v[60:63]
	v_mfma_f32_16x16x32_bf16 v[56:59], v[140:143], v[194:197], v[56:59]
	v_mfma_f32_16x16x32_bf16 v[44:47], v[132:135], v[202:205], v[44:47]
	v_mfma_f32_16x16x32_bf16 v[40:43], v[140:143], v[202:205], v[40:43]
	v_mfma_f32_16x16x32_bf16 v[28:31], v[132:135], v[210:213], v[28:31]
	v_mfma_f32_16x16x32_bf16 v[24:27], v[140:143], v[210:213], v[24:27]
	v_mfma_f32_16x16x32_bf16 v[12:15], v[132:135], v[218:221], v[12:15]
	v_mfma_f32_16x16x32_bf16 v[8:11], v[140:143], v[218:221], v[8:11]
	s_setprio 0
	s_setprio 1
	v_mfma_f32_16x16x32_bf16 v[52:55], v[144:147], v[190:193], v[52:55]
	v_mfma_f32_16x16x32_bf16 v[48:51], v[170:173], v[190:193], v[48:51]
	v_mfma_f32_16x16x32_bf16 v[36:39], v[144:147], v[198:201], v[36:39]
	v_mfma_f32_16x16x32_bf16 v[32:35], v[170:173], v[198:201], v[32:35]
	v_mfma_f32_16x16x32_bf16 v[20:23], v[144:147], v[206:209], v[20:23]
	v_mfma_f32_16x16x32_bf16 v[16:19], v[170:173], v[206:209], v[16:19]
	v_mfma_f32_16x16x32_bf16 v[4:7], v[144:147], v[214:217], v[4:7]
	v_mfma_f32_16x16x32_bf16 v[0:3], v[170:173], v[214:217], v[0:3]
	v_mfma_f32_16x16x32_bf16 v[52:55], v[148:151], v[194:197], v[52:55]
	v_mfma_f32_16x16x32_bf16 v[48:51], v[186:189], v[194:197], v[48:51]
	v_mfma_f32_16x16x32_bf16 v[36:39], v[148:151], v[202:205], v[36:39]
	v_mfma_f32_16x16x32_bf16 v[32:35], v[186:189], v[202:205], v[32:35]
	v_mfma_f32_16x16x32_bf16 v[20:23], v[148:151], v[210:213], v[20:23]
	v_mfma_f32_16x16x32_bf16 v[16:19], v[186:189], v[210:213], v[16:19]
	v_mfma_f32_16x16x32_bf16 v[4:7], v[148:151], v[218:221], v[4:7]
	v_mfma_f32_16x16x32_bf16 v[0:3], v[186:189], v[218:221], v[0:3]
	s_setprio 0
	s_barrier
	s_add_i32 s47, s47, 2
	s_add_u32 s22, s22, 0x100
	s_addc_u32 s23, s23, 0
	s_add_u32 s45, s45, 0x100
	s_addc_u32 s46, s46, 0
	s_cmp_gt_u32 s47, 29
	s_cbranch_scc0 .LBB0_1280
	s_and_b64 vcc, exec, s[10:11]
	s_cbranch_vccz .LBB0_1283
	s_barrier

.LBB0_1364:
	ds_read_b128 v[128:131], v175
	ds_read_b128 v[132:135], v175 offset:1024
	ds_read_b128 v[136:139], v175 offset:2048
	ds_read_b128 v[140:143], v175 offset:3072
	ds_read_b128 v[144:147], v176
	ds_read_b128 v[148:151], v176 offset:1024
	ds_read_b128 v[186:189], v176 offset:2048
	ds_read_b128 v[190:193], v176 offset:3072
	s_add_u32 s22, s6, 0xfff80080
	s_addc_u32 s23, s7, -1
	s_cmp_eq_u32 s49, 28
	s_cselect_b32 s25, s17, s23
	s_cselect_b32 s24, s45, s22
	s_cselect_b32 s23, s15, s48
	s_cselect_b32 s22, s46, s47
	v_lshl_add_u64 v[170:171], s[6:7], 0, v[162:163]
	s_add_i32 m0, s29, 0xc000
	ds_read_b128 v[194:197], v177
	ds_read_b128 v[198:201], v177 offset:1024
	ds_read_b128 v[202:205], v177 offset:2048
	ds_read_b128 v[206:209], v177 offset:3072
	ds_read_b128 v[210:213], v177 offset:4096
	ds_read_b128 v[214:217], v177 offset:5120
	ds_read_b128 v[218:221], v177 offset:6144
	ds_read_b128 v[222:225], v177 offset:7168
	global_load_lds_dwordx4 v[170:171], off
	v_lshl_add_u64 v[170:171], s[6:7], 0, v[164:165]
	s_add_i32 m0, s29, 0xe000
	s_nop 0
	global_load_lds_dwordx4 v[170:171], off
	s_waitcnt vmcnt(8)
	s_waitcnt lgkmcnt(0)
	s_barrier
	s_setprio 1
	v_mfma_f32_16x16x32_bf16 v[124:127], v[128:131], v[194:197], v[124:127]
	v_mfma_f32_16x16x32_bf16 v[116:119], v[136:139], v[194:197], v[116:119]
	v_mfma_f32_16x16x32_bf16 v[108:111], v[128:131], v[202:205], v[108:111]
	v_mfma_f32_16x16x32_bf16 v[100:103], v[136:139], v[202:205], v[100:103]
	v_mfma_f32_16x16x32_bf16 v[92:95], v[128:131], v[210:213], v[92:95]
	v_mfma_f32_16x16x32_bf16 v[84:87], v[136:139], v[210:213], v[84:87]
	v_mfma_f32_16x16x32_bf16 v[76:79], v[128:131], v[218:221], v[76:79]
	v_mfma_f32_16x16x32_bf16 v[68:71], v[136:139], v[218:221], v[68:71]
	v_mfma_f32_16x16x32_bf16 v[124:127], v[132:135], v[198:201], v[124:127]
	v_mfma_f32_16x16x32_bf16 v[116:119], v[140:143], v[198:201], v[116:119]
	v_mfma_f32_16x16x32_bf16 v[108:111], v[132:135], v[206:209], v[108:111]
	v_mfma_f32_16x16x32_bf16 v[100:103], v[140:143], v[206:209], v[100:103]
	v_mfma_f32_16x16x32_bf16 v[92:95], v[132:135], v[214:217], v[92:95]
	v_mfma_f32_16x16x32_bf16 v[84:87], v[140:143], v[214:217], v[84:87]
	v_mfma_f32_16x16x32_bf16 v[76:79], v[132:135], v[222:225], v[76:79]
	v_mfma_f32_16x16x32_bf16 v[68:71], v[140:143], v[222:225], v[68:71]
	s_setprio 0
	s_setprio 1
	v_mfma_f32_16x16x32_bf16 v[120:123], v[144:147], v[194:197], v[120:123]
	v_mfma_f32_16x16x32_bf16 v[112:115], v[186:189], v[194:197], v[112:115]
	v_mfma_f32_16x16x32_bf16 v[104:107], v[144:147], v[202:205], v[104:107]
	v_mfma_f32_16x16x32_bf16 v[96:99], v[186:189], v[202:205], v[96:99]
	v_mfma_f32_16x16x32_bf16 v[88:91], v[144:147], v[210:213], v[88:91]
	v_mfma_f32_16x16x32_bf16 v[80:83], v[186:189], v[210:213], v[80:83]
	v_mfma_f32_16x16x32_bf16 v[72:75], v[144:147], v[218:221], v[72:75]
	v_mfma_f32_16x16x32_bf16 v[64:67], v[186:189], v[218:221], v[64:67]
	v_mfma_f32_16x16x32_bf16 v[120:123], v[148:151], v[198:201], v[120:123]
	v_mfma_f32_16x16x32_bf16 v[112:115], v[190:193], v[198:201], v[112:115]
	v_mfma_f32_16x16x32_bf16 v[104:107], v[148:151], v[206:209], v[104:107]
	v_mfma_f32_16x16x32_bf16 v[96:99], v[190:193], v[206:209], v[96:99]
	v_mfma_f32_16x16x32_bf16 v[88:91], v[148:151], v[214:217], v[88:91]
	v_mfma_f32_16x16x32_bf16 v[80:83], v[190:193], v[214:217], v[80:83]
	v_mfma_f32_16x16x32_bf16 v[72:75], v[148:151], v[222:225], v[72:75]
	v_mfma_f32_16x16x32_bf16 v[64:67], v[190:193], v[222:225], v[64:67]
	s_setprio 0
	s_barrier
	s_add_i32 s50, s41, s26
	v_lshl_add_u64 v[170:171], s[22:23], 0, v[156:157]
	s_mov_b32 m0, s50
	ds_read_b128 v[194:197], v177 offset:16384
	ds_read_b128 v[198:201], v177 offset:17408
	ds_read_b128 v[202:205], v177 offset:18432
	ds_read_b128 v[206:209], v177 offset:19456
	ds_read_b128 v[210:213], v177 offset:20480
	ds_read_b128 v[214:217], v177 offset:21504
	ds_read_b128 v[218:221], v177 offset:22528
	ds_read_b128 v[222:225], v177 offset:23552
	global_load_lds_dwordx4 v[170:171], off
	s_add_i32 m0, s50, 0x2000
	s_add_u32 s50, s22, 0x80000
	v_lshl_add_u64 v[182:183], s[22:23], 0, v[152:153]
	s_addc_u32 s51, s23, 0
	s_add_i32 s52, s42, s26
	global_load_lds_dwordx4 v[182:183], off
	v_lshl_add_u64 v[226:227], s[50:51], 0, v[156:157]
	s_mov_b32 m0, s52
	v_lshl_add_u64 v[228:229], s[24:25], 0, v[154:155]
	global_load_lds_dwordx4 v[226:227], off
	v_lshl_add_u64 v[226:227], s[50:51], 0, v[152:153]
	s_add_i32 m0, s52, 0x2000
	s_nop 0
	global_load_lds_dwordx4 v[226:227], off
	v_lshl_add_u64 v[226:227], s[24:25], 0, v[158:159]
	s_mov_b32 m0, s29
	s_nop 0
	global_load_lds_dwordx4 v[226:227], off
	s_mov_b32 m0, s30
	s_nop 0
	global_load_lds_dwordx4 v[228:229], off
	s_waitcnt vmcnt(8)
	s_waitcnt lgkmcnt(0)
	s_barrier
	s_setprio 1
	v_mfma_f32_16x16x32_bf16 v[60:63], v[128:131], v[194:197], v[60:63]
	v_mfma_f32_16x16x32_bf16 v[52:55], v[136:139], v[194:197], v[52:55]
	v_mfma_f32_16x16x32_bf16 v[44:47], v[128:131], v[202:205], v[44:47]
	v_mfma_f32_16x16x32_bf16 v[36:39], v[136:139], v[202:205], v[36:39]
	v_mfma_f32_16x16x32_bf16 v[28:31], v[128:131], v[210:213], v[28:31]
	v_mfma_f32_16x16x32_bf16 v[20:23], v[136:139], v[210:213], v[20:23]
	v_mfma_f32_16x16x32_bf16 v[12:15], v[128:131], v[218:221], v[12:15]
	v_mfma_f32_16x16x32_bf16 v[4:7], v[136:139], v[218:221], v[4:7]
	v_mfma_f32_16x16x32_bf16 v[60:63], v[132:135], v[198:201], v[60:63]
	v_mfma_f32_16x16x32_bf16 v[52:55], v[140:143], v[198:201], v[52:55]
	v_mfma_f32_16x16x32_bf16 v[44:47], v[132:135], v[206:209], v[44:47]
	v_mfma_f32_16x16x32_bf16 v[36:39], v[140:143], v[206:209], v[36:39]
	v_mfma_f32_16x16x32_bf16 v[28:31], v[132:135], v[214:217], v[28:31]
	v_mfma_f32_16x16x32_bf16 v[20:23], v[140:143], v[214:217], v[20:23]
	v_mfma_f32_16x16x32_bf16 v[12:15], v[132:135], v[222:225], v[12:15]
	v_mfma_f32_16x16x32_bf16 v[4:7], v[140:143], v[222:225], v[4:7]
	s_setprio 0
	s_setprio 1
	v_mfma_f32_16x16x32_bf16 v[56:59], v[144:147], v[194:197], v[56:59]
	v_mfma_f32_16x16x32_bf16 v[48:51], v[186:189], v[194:197], v[48:51]
	v_mfma_f32_16x16x32_bf16 v[40:43], v[144:147], v[202:205], v[40:43]
	v_mfma_f32_16x16x32_bf16 v[32:35], v[186:189], v[202:205], v[32:35]
	v_mfma_f32_16x16x32_bf16 v[24:27], v[144:147], v[210:213], v[24:27]
	v_mfma_f32_16x16x32_bf16 v[16:19], v[186:189], v[210:213], v[16:19]
	v_mfma_f32_16x16x32_bf16 v[8:11], v[144:147], v[218:221], v[8:11]
	v_mfma_f32_16x16x32_bf16 v[0:3], v[186:189], v[218:221], v[0:3]
	v_mfma_f32_16x16x32_bf16 v[56:59], v[148:151], v[198:201], v[56:59]
	v_mfma_f32_16x16x32_bf16 v[48:51], v[190:193], v[198:201], v[48:51]
	v_mfma_f32_16x16x32_bf16 v[40:43], v[148:151], v[206:209], v[40:43]
	v_mfma_f32_16x16x32_bf16 v[32:35], v[190:193], v[206:209], v[32:35]
	v_mfma_f32_16x16x32_bf16 v[24:27], v[148:151], v[214:217], v[24:27]
	v_mfma_f32_16x16x32_bf16 v[16:19], v[190:193], v[214:217], v[16:19]
	v_mfma_f32_16x16x32_bf16 v[8:11], v[148:151], v[222:225], v[8:11]
	v_mfma_f32_16x16x32_bf16 v[0:3], v[190:193], v[222:225], v[0:3]
	s_setprio 0
	s_barrier
	s_add_i32 s50, 0, 0x18000
	s_add_i32 s51, 0, 0x1c000
	v_add_u32_e32 v140, s50, v174
	v_add_u32_e32 v160, s51, v174
	ds_read_b128 v[128:131], v140
	ds_read_b128 v[132:135], v140 offset:1024
	ds_read_b128 v[136:139], v140 offset:2048
	ds_read_b128 v[140:143], v140 offset:3072
	ds_read_b128 v[144:147], v160
	ds_read_b128 v[148:151], v160 offset:1024
	ds_read_b128 v[186:189], v160 offset:2048
	ds_read_b128 v[190:193], v160 offset:3072
	s_add_u32 s24, s24, 0x80000
	s_addc_u32 s25, s25, 0
	s_mov_b32 m0, s31
	v_lshl_add_u64 v[230:231], s[24:25], 0, v[158:159]
	ds_read_b128 v[194:197], v177 offset:32768
	ds_read_b128 v[198:201], v177 offset:33792
	ds_read_b128 v[202:205], v177 offset:34816
	ds_read_b128 v[206:209], v177 offset:35840
	ds_read_b128 v[210:213], v177 offset:36864
	ds_read_b128 v[214:217], v177 offset:37888
	ds_read_b128 v[218:221], v177 offset:38912
	ds_read_b128 v[222:225], v177 offset:39936
	global_load_lds_dwordx4 v[230:231], off
	v_lshl_add_u64 v[230:231], s[24:25], 0, v[154:155]
	s_mov_b32 m0, s33
	s_nop 0
	global_load_lds_dwordx4 v[230:231], off
	s_waitcnt vmcnt(8)
	s_waitcnt lgkmcnt(0)
	s_barrier
	s_setprio 1
	v_mfma_f32_16x16x32_bf16 v[124:127], v[128:131], v[194:197], v[124:127]
	v_mfma_f32_16x16x32_bf16 v[116:119], v[136:139], v[194:197], v[116:119]
	v_mfma_f32_16x16x32_bf16 v[108:111], v[128:131], v[202:205], v[108:111]
	v_mfma_f32_16x16x32_bf16 v[100:103], v[136:139], v[202:205], v[100:103]
	v_mfma_f32_16x16x32_bf16 v[92:95], v[128:131], v[210:213], v[92:95]
	v_mfma_f32_16x16x32_bf16 v[84:87], v[136:139], v[210:213], v[84:87]
	v_mfma_f32_16x16x32_bf16 v[76:79], v[128:131], v[218:221], v[76:79]
	v_mfma_f32_16x16x32_bf16 v[68:71], v[136:139], v[218:221], v[68:71]
	v_mfma_f32_16x16x32_bf16 v[124:127], v[132:135], v[198:201], v[124:127]
	v_mfma_f32_16x16x32_bf16 v[116:119], v[140:143], v[198:201], v[116:119]
	v_mfma_f32_16x16x32_bf16 v[108:111], v[132:135], v[206:209], v[108:111]
	v_mfma_f32_16x16x32_bf16 v[100:103], v[140:143], v[206:209], v[100:103]
	v_mfma_f32_16x16x32_bf16 v[92:95], v[132:135], v[214:217], v[92:95]
	v_mfma_f32_16x16x32_bf16 v[84:87], v[140:143], v[214:217], v[84:87]
	v_mfma_f32_16x16x32_bf16 v[76:79], v[132:135], v[222:225], v[76:79]
	v_mfma_f32_16x16x32_bf16 v[68:71], v[140:143], v[222:225], v[68:71]
	s_setprio 0
	s_setprio 1
	v_mfma_f32_16x16x32_bf16 v[120:123], v[144:147], v[194:197], v[120:123]
	v_mfma_f32_16x16x32_bf16 v[112:115], v[186:189], v[194:197], v[112:115]
	v_mfma_f32_16x16x32_bf16 v[104:107], v[144:147], v[202:205], v[104:107]
	v_mfma_f32_16x16x32_bf16 v[96:99], v[186:189], v[202:205], v[96:99]
	v_mfma_f32_16x16x32_bf16 v[88:91], v[144:147], v[210:213], v[88:91]
	v_mfma_f32_16x16x32_bf16 v[80:83], v[186:189], v[210:213], v[80:83]
	v_mfma_f32_16x16x32_bf16 v[72:75], v[144:147], v[218:221], v[72:75]
	v_mfma_f32_16x16x32_bf16 v[64:67], v[186:189], v[218:221], v[64:67]
	v_mfma_f32_16x16x32_bf16 v[120:123], v[148:151], v[198:201], v[120:123]
	v_mfma_f32_16x16x32_bf16 v[112:115], v[190:193], v[198:201], v[112:115]
	v_mfma_f32_16x16x32_bf16 v[104:107], v[148:151], v[206:209], v[104:107]
	v_mfma_f32_16x16x32_bf16 v[96:99], v[190:193], v[206:209], v[96:99]
	v_mfma_f32_16x16x32_bf16 v[88:91], v[148:151], v[214:217], v[88:91]
	v_mfma_f32_16x16x32_bf16 v[80:83], v[190:193], v[214:217], v[80:83]
	v_mfma_f32_16x16x32_bf16 v[72:75], v[148:151], v[222:225], v[72:75]
	v_mfma_f32_16x16x32_bf16 v[64:67], v[190:193], v[222:225], v[64:67]
	s_setprio 0
	s_barrier
	s_add_i32 s24, s50, s26
	v_lshl_add_u64 v[170:171], v[170:171], 0, s[10:11]
	s_mov_b32 m0, s24
	ds_read_b128 v[194:197], v177 offset:49152
	ds_read_b128 v[198:201], v177 offset:50176
	ds_read_b128 v[202:205], v177 offset:51200
	ds_read_b128 v[206:209], v177 offset:52224
	ds_read_b128 v[210:213], v177 offset:53248
	ds_read_b128 v[214:217], v177 offset:54272
	ds_read_b128 v[218:221], v177 offset:55296
	ds_read_b128 v[222:225], v177 offset:56320
	global_load_lds_dwordx4 v[170:171], off
	s_add_i32 m0, s24, 0x2000
	s_add_u32 s22, s22, 0x80080
	v_lshl_add_u64 v[170:171], v[182:183], 0, s[10:11]
	s_addc_u32 s23, s23, 0
	s_add_i32 s24, s51, s26
	global_load_lds_dwordx4 v[170:171], off
	v_lshl_add_u64 v[170:171], s[22:23], 0, v[156:157]
	s_mov_b32 m0, s24
	s_nop 0
	global_load_lds_dwordx4 v[170:171], off
	v_lshl_add_u64 v[170:171], s[22:23], 0, v[152:153]
	s_add_i32 m0, s24, 0x2000
	s_nop 0
	global_load_lds_dwordx4 v[170:171], off
	v_lshl_add_u64 v[170:171], v[226:227], 0, s[10:11]
	s_mov_b32 m0, s37
	s_nop 0
	global_load_lds_dwordx4 v[170:171], off
	v_lshl_add_u64 v[170:171], v[228:229], 0, s[10:11]
	s_mov_b32 m0, s38
	s_nop 0
	global_load_lds_dwordx4 v[170:171], off
	s_waitcnt vmcnt(8)
	s_waitcnt lgkmcnt(0)
	s_barrier
	s_setprio 1
	v_mfma_f32_16x16x32_bf16 v[60:63], v[128:131], v[194:197], v[60:63]
	v_mfma_f32_16x16x32_bf16 v[52:55], v[136:139], v[194:197], v[52:55]
	v_mfma_f32_16x16x32_bf16 v[44:47], v[128:131], v[202:205], v[44:47]
	v_mfma_f32_16x16x32_bf16 v[36:39], v[136:139], v[202:205], v[36:39]
	v_mfma_f32_16x16x32_bf16 v[28:31], v[128:131], v[210:213], v[28:31]
	v_mfma_f32_16x16x32_bf16 v[20:23], v[136:139], v[210:213], v[20:23]
	v_mfma_f32_16x16x32_bf16 v[12:15], v[128:131], v[218:221], v[12:15]
	v_mfma_f32_16x16x32_bf16 v[4:7], v[136:139], v[218:221], v[4:7]
	v_mfma_f32_16x16x32_bf16 v[60:63], v[132:135], v[198:201], v[60:63]
	v_mfma_f32_16x16x32_bf16 v[52:55], v[140:143], v[198:201], v[52:55]
	v_mfma_f32_16x16x32_bf16 v[44:47], v[132:135], v[206:209], v[44:47]
	v_mfma_f32_16x16x32_bf16 v[36:39], v[140:143], v[206:209], v[36:39]
	v_mfma_f32_16x16x32_bf16 v[28:31], v[132:135], v[214:217], v[28:31]
	v_mfma_f32_16x16x32_bf16 v[20:23], v[140:143], v[214:217], v[20:23]
	v_mfma_f32_16x16x32_bf16 v[12:15], v[132:135], v[222:225], v[12:15]
	v_mfma_f32_16x16x32_bf16 v[4:7], v[140:143], v[222:225], v[4:7]
	s_setprio 0
	s_setprio 1
	v_mfma_f32_16x16x32_bf16 v[56:59], v[144:147], v[194:197], v[56:59]
	v_mfma_f32_16x16x32_bf16 v[48:51], v[186:189], v[194:197], v[48:51]
	v_mfma_f32_16x16x32_bf16 v[40:43], v[144:147], v[202:205], v[40:43]
	v_mfma_f32_16x16x32_bf16 v[32:35], v[186:189], v[202:205], v[32:35]
	v_mfma_f32_16x16x32_bf16 v[24:27], v[144:147], v[210:213], v[24:27]
	v_mfma_f32_16x16x32_bf16 v[16:19], v[186:189], v[210:213], v[16:19]
	v_mfma_f32_16x16x32_bf16 v[8:11], v[144:147], v[218:221], v[8:11]
	v_mfma_f32_16x16x32_bf16 v[0:3], v[186:189], v[218:221], v[0:3]
	v_mfma_f32_16x16x32_bf16 v[56:59], v[148:151], v[198:201], v[56:59]
	v_mfma_f32_16x16x32_bf16 v[48:51], v[190:193], v[198:201], v[48:51]
	v_mfma_f32_16x16x32_bf16 v[40:43], v[148:151], v[206:209], v[40:43]
	v_mfma_f32_16x16x32_bf16 v[32:35], v[190:193], v[206:209], v[32:35]
	v_mfma_f32_16x16x32_bf16 v[24:27], v[148:151], v[214:217], v[24:27]
	v_mfma_f32_16x16x32_bf16 v[16:19], v[190:193], v[214:217], v[16:19]
	v_mfma_f32_16x16x32_bf16 v[8:11], v[148:151], v[222:225], v[8:11]
	v_mfma_f32_16x16x32_bf16 v[0:3], v[190:193], v[222:225], v[0:3]
	s_setprio 0
	s_barrier
	s_add_i32 s49, s49, 2
	s_add_u32 s6, s6, 0x100
	s_addc_u32 s7, s7, 0
	s_add_u32 s47, s47, 0x100
	s_addc_u32 s48, s48, 0
	s_cmp_gt_u32 s49, 29
	s_cbranch_scc0 .LBB0_1364
	s_and_b64 vcc, exec, s[12:13]
	s_cbranch_vccz .LBB0_1367
	s_barrier

.LBB0_1444:
	ds_read_b128 v[128:131], v159
	ds_read_b128 v[150:153], v159 offset:1024
	ds_read_b128 v[162:165], v159 offset:2048
	ds_read_b128 v[166:169], v159 offset:3072
	ds_read_b128 v[170:173], v160
	ds_read_b128 v[174:177], v160 offset:1024
	ds_read_b128 v[178:181], v160 offset:2048
	ds_read_b128 v[182:185], v160 offset:3072
	s_add_u32 s4, s18, 0x100
	s_addc_u32 s5, s19, 0
	s_cmpk_eq_i32 s45, 0x54
	s_cselect_b32 s23, s15, s5
	s_cselect_b32 s22, s14, s4
	s_cselect_b32 s21, s17, s44
	s_cselect_b32 s20, s16, s43
	v_lshl_add_u64 v[154:155], s[18:19], 0, v[142:143]
	s_add_i32 m0, s26, 0xc000
	ds_read_b128 v[186:189], v161
	ds_read_b128 v[190:193], v161 offset:1024
	ds_read_b128 v[194:197], v161 offset:2048
	ds_read_b128 v[198:201], v161 offset:3072
	ds_read_b128 v[202:205], v161 offset:4096
	ds_read_b128 v[206:209], v161 offset:5120
	ds_read_b128 v[210:213], v161 offset:6144
	ds_read_b128 v[214:217], v161 offset:7168
	global_load_lds_dwordx4 v[154:155], off
	v_lshl_add_u64 v[154:155], s[18:19], 0, v[144:145]
	s_add_i32 m0, s26, 0xe000
	s_nop 0
	global_load_lds_dwordx4 v[154:155], off
	s_waitcnt vmcnt(8)
	s_waitcnt lgkmcnt(0)
	s_barrier
	s_setprio 1
	v_mfma_f32_16x16x32_bf16 v[124:127], v[128:131], v[186:189], v[124:127]
	v_mfma_f32_16x16x32_bf16 v[120:123], v[162:165], v[186:189], v[120:123]
	v_mfma_f32_16x16x32_bf16 v[116:119], v[128:131], v[194:197], v[116:119]
	v_mfma_f32_16x16x32_bf16 v[112:115], v[162:165], v[194:197], v[112:115]
	v_mfma_f32_16x16x32_bf16 v[88:91], v[128:131], v[202:205], v[88:91]
	v_mfma_f32_16x16x32_bf16 v[92:95], v[162:165], v[202:205], v[92:95]
	v_mfma_f32_16x16x32_bf16 v[72:75], v[128:131], v[210:213], v[72:75]
	v_mfma_f32_16x16x32_bf16 v[76:79], v[162:165], v[210:213], v[76:79]
	v_mfma_f32_16x16x32_bf16 v[124:127], v[150:153], v[190:193], v[124:127]
	v_mfma_f32_16x16x32_bf16 v[120:123], v[166:169], v[190:193], v[120:123]
	v_mfma_f32_16x16x32_bf16 v[116:119], v[150:153], v[198:201], v[116:119]
	v_mfma_f32_16x16x32_bf16 v[112:115], v[166:169], v[198:201], v[112:115]
	v_mfma_f32_16x16x32_bf16 v[88:91], v[150:153], v[206:209], v[88:91]
	v_mfma_f32_16x16x32_bf16 v[92:95], v[166:169], v[206:209], v[92:95]
	v_mfma_f32_16x16x32_bf16 v[72:75], v[150:153], v[214:217], v[72:75]
	v_mfma_f32_16x16x32_bf16 v[76:79], v[166:169], v[214:217], v[76:79]
	s_setprio 0
	s_setprio 1
	v_mfma_f32_16x16x32_bf16 v[108:111], v[170:173], v[186:189], v[108:111]
	v_mfma_f32_16x16x32_bf16 v[104:107], v[178:181], v[186:189], v[104:107]
	v_mfma_f32_16x16x32_bf16 v[96:99], v[170:173], v[194:197], v[96:99]
	v_mfma_f32_16x16x32_bf16 v[100:103], v[178:181], v[194:197], v[100:103]
	v_mfma_f32_16x16x32_bf16 v[80:83], v[170:173], v[202:205], v[80:83]
	v_mfma_f32_16x16x32_bf16 v[84:87], v[178:181], v[202:205], v[84:87]
	v_mfma_f32_16x16x32_bf16 v[64:67], v[170:173], v[210:213], v[64:67]
	v_mfma_f32_16x16x32_bf16 v[68:71], v[178:181], v[210:213], v[68:71]
	v_mfma_f32_16x16x32_bf16 v[108:111], v[174:177], v[190:193], v[108:111]
	v_mfma_f32_16x16x32_bf16 v[104:107], v[182:185], v[190:193], v[104:107]
	v_mfma_f32_16x16x32_bf16 v[96:99], v[174:177], v[198:201], v[96:99]
	v_mfma_f32_16x16x32_bf16 v[100:103], v[182:185], v[198:201], v[100:103]
	v_mfma_f32_16x16x32_bf16 v[80:83], v[174:177], v[206:209], v[80:83]
	v_mfma_f32_16x16x32_bf16 v[84:87], v[182:185], v[206:209], v[84:87]
	v_mfma_f32_16x16x32_bf16 v[64:67], v[174:177], v[214:217], v[64:67]
	v_mfma_f32_16x16x32_bf16 v[68:71], v[182:185], v[214:217], v[68:71]
	s_setprio 0
	s_barrier
	s_add_i32 s18, s37, s25
	v_lshl_add_u64 v[154:155], s[20:21], 0, v[134:135]
	s_mov_b32 m0, s18
	ds_read_b128 v[186:189], v161 offset:16384
	ds_read_b128 v[190:193], v161 offset:17408
	ds_read_b128 v[194:197], v161 offset:18432
	ds_read_b128 v[198:201], v161 offset:19456
	ds_read_b128 v[202:205], v161 offset:20480
	ds_read_b128 v[206:209], v161 offset:21504
	ds_read_b128 v[210:213], v161 offset:22528
	ds_read_b128 v[214:217], v161 offset:23552
	global_load_lds_dwordx4 v[154:155], off
	s_add_i32 m0, s18, 0x2000
	s_add_u32 s18, s20, 0x160000
	v_lshl_add_u64 v[218:219], s[20:21], 0, v[138:139]
	s_addc_u32 s19, s21, 0
	s_add_i32 s46, s38, s25
	global_load_lds_dwordx4 v[218:219], off
	v_lshl_add_u64 v[220:221], s[18:19], 0, v[134:135]
	s_mov_b32 m0, s46
	v_lshl_add_u64 v[222:223], s[22:23], 0, v[136:137]
	global_load_lds_dwordx4 v[220:221], off
	v_lshl_add_u64 v[220:221], s[18:19], 0, v[138:139]
	s_add_i32 m0, s46, 0x2000
	s_nop 0
	global_load_lds_dwordx4 v[220:221], off
	v_lshl_add_u64 v[220:221], s[22:23], 0, v[132:133]
	s_mov_b32 m0, s26
	s_nop 0
	global_load_lds_dwordx4 v[220:221], off
	s_mov_b32 m0, s27
	s_nop 0
	global_load_lds_dwordx4 v[222:223], off
	s_waitcnt vmcnt(8)
	s_waitcnt lgkmcnt(0)
	s_barrier
	s_setprio 1
	v_mfma_f32_16x16x32_bf16 v[60:63], v[128:131], v[186:189], v[60:63]
	v_mfma_f32_16x16x32_bf16 v[56:59], v[162:165], v[186:189], v[56:59]
	v_mfma_f32_16x16x32_bf16 v[52:55], v[128:131], v[194:197], v[52:55]
	v_mfma_f32_16x16x32_bf16 v[48:51], v[162:165], v[194:197], v[48:51]
	v_mfma_f32_16x16x32_bf16 v[24:27], v[128:131], v[202:205], v[24:27]
	v_mfma_f32_16x16x32_bf16 v[28:31], v[162:165], v[202:205], v[28:31]
	v_mfma_f32_16x16x32_bf16 v[8:11], v[128:131], v[210:213], v[8:11]
	v_mfma_f32_16x16x32_bf16 v[12:15], v[162:165], v[210:213], v[12:15]
	v_mfma_f32_16x16x32_bf16 v[60:63], v[150:153], v[190:193], v[60:63]
	v_mfma_f32_16x16x32_bf16 v[56:59], v[166:169], v[190:193], v[56:59]
	v_mfma_f32_16x16x32_bf16 v[52:55], v[150:153], v[198:201], v[52:55]
	v_mfma_f32_16x16x32_bf16 v[48:51], v[166:169], v[198:201], v[48:51]
	v_mfma_f32_16x16x32_bf16 v[24:27], v[150:153], v[206:209], v[24:27]
	v_mfma_f32_16x16x32_bf16 v[28:31], v[166:169], v[206:209], v[28:31]
	v_mfma_f32_16x16x32_bf16 v[8:11], v[150:153], v[214:217], v[8:11]
	v_mfma_f32_16x16x32_bf16 v[12:15], v[166:169], v[214:217], v[12:15]
	s_setprio 0
	s_setprio 1
	v_mfma_f32_16x16x32_bf16 v[44:47], v[170:173], v[186:189], v[44:47]
	v_mfma_f32_16x16x32_bf16 v[40:43], v[178:181], v[186:189], v[40:43]
	v_mfma_f32_16x16x32_bf16 v[32:35], v[170:173], v[194:197], v[32:35]
	v_mfma_f32_16x16x32_bf16 v[36:39], v[178:181], v[194:197], v[36:39]
	v_mfma_f32_16x16x32_bf16 v[16:19], v[170:173], v[202:205], v[16:19]
	v_mfma_f32_16x16x32_bf16 v[20:23], v[178:181], v[202:205], v[20:23]
	v_mfma_f32_16x16x32_bf16 v[0:3], v[170:173], v[210:213], v[0:3]
	v_mfma_f32_16x16x32_bf16 v[4:7], v[178:181], v[210:213], v[4:7]
	v_mfma_f32_16x16x32_bf16 v[44:47], v[174:177], v[190:193], v[44:47]
	v_mfma_f32_16x16x32_bf16 v[40:43], v[182:185], v[190:193], v[40:43]
	v_mfma_f32_16x16x32_bf16 v[32:35], v[174:177], v[198:201], v[32:35]
	v_mfma_f32_16x16x32_bf16 v[36:39], v[182:185], v[198:201], v[36:39]
	v_mfma_f32_16x16x32_bf16 v[16:19], v[174:177], v[206:209], v[16:19]
	v_mfma_f32_16x16x32_bf16 v[20:23], v[182:185], v[206:209], v[20:23]
	v_mfma_f32_16x16x32_bf16 v[0:3], v[174:177], v[214:217], v[0:3]
	v_mfma_f32_16x16x32_bf16 v[4:7], v[182:185], v[214:217], v[4:7]
	s_setprio 0
	s_barrier
	s_add_i32 s46, 0, 0x18000
	v_add_u32_e32 v140, s46, v158
	s_add_i32 s47, 0, 0x1c000
	ds_read_b128 v[128:131], v140
	ds_read_b128 v[150:153], v140 offset:1024
	ds_read_b128 v[162:165], v140 offset:2048
	ds_read_b128 v[166:169], v140 offset:3072
	v_add_u32_e32 v140, s47, v158
	ds_read_b128 v[170:173], v140
	ds_read_b128 v[174:177], v140 offset:1024
	ds_read_b128 v[178:181], v140 offset:2048
	ds_read_b128 v[182:185], v140 offset:3072
	s_add_u32 s18, s22, 0x160000
	s_addc_u32 s19, s23, 0
	s_mov_b32 m0, s28
	v_lshl_add_u64 v[224:225], s[18:19], 0, v[132:133]
	ds_read_b128 v[186:189], v161 offset:32768
	ds_read_b128 v[190:193], v161 offset:33792
	ds_read_b128 v[194:197], v161 offset:34816
	ds_read_b128 v[198:201], v161 offset:35840
	ds_read_b128 v[202:205], v161 offset:36864
	ds_read_b128 v[206:209], v161 offset:37888
	ds_read_b128 v[210:213], v161 offset:38912
	ds_read_b128 v[214:217], v161 offset:39936
	global_load_lds_dwordx4 v[224:225], off
	v_lshl_add_u64 v[224:225], s[18:19], 0, v[136:137]
	s_mov_b32 m0, s29
	s_nop 0
	global_load_lds_dwordx4 v[224:225], off
	s_waitcnt vmcnt(8)
	s_waitcnt lgkmcnt(0)
	s_barrier
	s_setprio 1
	v_mfma_f32_16x16x32_bf16 v[124:127], v[128:131], v[186:189], v[124:127]
	v_mfma_f32_16x16x32_bf16 v[120:123], v[162:165], v[186:189], v[120:123]
	v_mfma_f32_16x16x32_bf16 v[116:119], v[128:131], v[194:197], v[116:119]
	v_mfma_f32_16x16x32_bf16 v[112:115], v[162:165], v[194:197], v[112:115]
	v_mfma_f32_16x16x32_bf16 v[88:91], v[128:131], v[202:205], v[88:91]
	v_mfma_f32_16x16x32_bf16 v[92:95], v[162:165], v[202:205], v[92:95]
	v_mfma_f32_16x16x32_bf16 v[72:75], v[128:131], v[210:213], v[72:75]
	v_mfma_f32_16x16x32_bf16 v[76:79], v[162:165], v[210:213], v[76:79]
	v_mfma_f32_16x16x32_bf16 v[124:127], v[150:153], v[190:193], v[124:127]
	v_mfma_f32_16x16x32_bf16 v[120:123], v[166:169], v[190:193], v[120:123]
	v_mfma_f32_16x16x32_bf16 v[116:119], v[150:153], v[198:201], v[116:119]
	v_mfma_f32_16x16x32_bf16 v[112:115], v[166:169], v[198:201], v[112:115]
	v_mfma_f32_16x16x32_bf16 v[88:91], v[150:153], v[206:209], v[88:91]
	v_mfma_f32_16x16x32_bf16 v[92:95], v[166:169], v[206:209], v[92:95]
	v_mfma_f32_16x16x32_bf16 v[72:75], v[150:153], v[214:217], v[72:75]
	v_mfma_f32_16x16x32_bf16 v[76:79], v[166:169], v[214:217], v[76:79]
	s_setprio 0
	s_setprio 1
	v_mfma_f32_16x16x32_bf16 v[108:111], v[170:173], v[186:189], v[108:111]
	v_mfma_f32_16x16x32_bf16 v[104:107], v[178:181], v[186:189], v[104:107]
	v_mfma_f32_16x16x32_bf16 v[96:99], v[170:173], v[194:197], v[96:99]
	v_mfma_f32_16x16x32_bf16 v[100:103], v[178:181], v[194:197], v[100:103]
	v_mfma_f32_16x16x32_bf16 v[80:83], v[170:173], v[202:205], v[80:83]
	v_mfma_f32_16x16x32_bf16 v[84:87], v[178:181], v[202:205], v[84:87]
	v_mfma_f32_16x16x32_bf16 v[64:67], v[170:173], v[210:213], v[64:67]
	v_mfma_f32_16x16x32_bf16 v[68:71], v[178:181], v[210:213], v[68:71]
	v_mfma_f32_16x16x32_bf16 v[108:111], v[174:177], v[190:193], v[108:111]
	v_mfma_f32_16x16x32_bf16 v[104:107], v[182:185], v[190:193], v[104:107]
	v_mfma_f32_16x16x32_bf16 v[96:99], v[174:177], v[198:201], v[96:99]
	v_mfma_f32_16x16x32_bf16 v[100:103], v[182:185], v[198:201], v[100:103]
	v_mfma_f32_16x16x32_bf16 v[80:83], v[174:177], v[206:209], v[80:83]
	v_mfma_f32_16x16x32_bf16 v[84:87], v[182:185], v[206:209], v[84:87]
	v_mfma_f32_16x16x32_bf16 v[64:67], v[174:177], v[214:217], v[64:67]
	v_mfma_f32_16x16x32_bf16 v[68:71], v[182:185], v[214:217], v[68:71]
	s_setprio 0
	s_barrier
	s_add_i32 s18, s46, s25
	v_lshl_add_u64 v[154:155], v[154:155], 0, s[8:9]
	s_mov_b32 m0, s18
	ds_read_b128 v[186:189], v161 offset:49152
	ds_read_b128 v[190:193], v161 offset:50176
	ds_read_b128 v[194:197], v161 offset:51200
	ds_read_b128 v[198:201], v161 offset:52224
	ds_read_b128 v[202:205], v161 offset:53248
	ds_read_b128 v[206:209], v161 offset:54272
	ds_read_b128 v[210:213], v161 offset:55296
	ds_read_b128 v[214:217], v161 offset:56320
	global_load_lds_dwordx4 v[154:155], off
	s_add_i32 m0, s18, 0x2000
	s_add_u32 s18, s20, 0x160080
	v_lshl_add_u64 v[154:155], v[218:219], 0, s[8:9]
	s_addc_u32 s19, s21, 0
	s_add_i32 s20, s47, s25
	global_load_lds_dwordx4 v[154:155], off
	v_lshl_add_u64 v[154:155], s[18:19], 0, v[134:135]
	s_mov_b32 m0, s20
	s_nop 0
	global_load_lds_dwordx4 v[154:155], off
	v_lshl_add_u64 v[154:155], s[18:19], 0, v[138:139]
	s_add_i32 m0, s20, 0x2000
	s_nop 0
	global_load_lds_dwordx4 v[154:155], off
	v_lshl_add_u64 v[154:155], v[220:221], 0, s[8:9]
	s_mov_b32 m0, s34
	s_nop 0
	global_load_lds_dwordx4 v[154:155], off
	v_lshl_add_u64 v[154:155], v[222:223], 0, s[8:9]
	s_mov_b32 m0, s35
	s_nop 0
	global_load_lds_dwordx4 v[154:155], off
	s_waitcnt vmcnt(8)
	s_waitcnt lgkmcnt(0)
	s_barrier
	s_setprio 1
	v_mfma_f32_16x16x32_bf16 v[60:63], v[128:131], v[186:189], v[60:63]
	v_mfma_f32_16x16x32_bf16 v[56:59], v[162:165], v[186:189], v[56:59]
	v_mfma_f32_16x16x32_bf16 v[52:55], v[128:131], v[194:197], v[52:55]
	v_mfma_f32_16x16x32_bf16 v[48:51], v[162:165], v[194:197], v[48:51]
	v_mfma_f32_16x16x32_bf16 v[24:27], v[128:131], v[202:205], v[24:27]
	v_mfma_f32_16x16x32_bf16 v[28:31], v[162:165], v[202:205], v[28:31]
	v_mfma_f32_16x16x32_bf16 v[8:11], v[128:131], v[210:213], v[8:11]
	v_mfma_f32_16x16x32_bf16 v[12:15], v[162:165], v[210:213], v[12:15]
	v_mfma_f32_16x16x32_bf16 v[60:63], v[150:153], v[190:193], v[60:63]
	v_mfma_f32_16x16x32_bf16 v[56:59], v[166:169], v[190:193], v[56:59]
	v_mfma_f32_16x16x32_bf16 v[52:55], v[150:153], v[198:201], v[52:55]
	v_mfma_f32_16x16x32_bf16 v[48:51], v[166:169], v[198:201], v[48:51]
	v_mfma_f32_16x16x32_bf16 v[24:27], v[150:153], v[206:209], v[24:27]
	v_mfma_f32_16x16x32_bf16 v[28:31], v[166:169], v[206:209], v[28:31]
	v_mfma_f32_16x16x32_bf16 v[8:11], v[150:153], v[214:217], v[8:11]
	v_mfma_f32_16x16x32_bf16 v[12:15], v[166:169], v[214:217], v[12:15]
	s_setprio 0
	s_setprio 1
	v_mfma_f32_16x16x32_bf16 v[44:47], v[170:173], v[186:189], v[44:47]
	v_mfma_f32_16x16x32_bf16 v[40:43], v[178:181], v[186:189], v[40:43]
	v_mfma_f32_16x16x32_bf16 v[32:35], v[170:173], v[194:197], v[32:35]
	v_mfma_f32_16x16x32_bf16 v[36:39], v[178:181], v[194:197], v[36:39]
	v_mfma_f32_16x16x32_bf16 v[16:19], v[170:173], v[202:205], v[16:19]
	v_mfma_f32_16x16x32_bf16 v[20:23], v[178:181], v[202:205], v[20:23]
	v_mfma_f32_16x16x32_bf16 v[0:3], v[170:173], v[210:213], v[0:3]
	v_mfma_f32_16x16x32_bf16 v[4:7], v[178:181], v[210:213], v[4:7]
	v_mfma_f32_16x16x32_bf16 v[44:47], v[174:177], v[190:193], v[44:47]
	v_mfma_f32_16x16x32_bf16 v[40:43], v[182:185], v[190:193], v[40:43]
	v_mfma_f32_16x16x32_bf16 v[32:35], v[174:177], v[198:201], v[32:35]
	v_mfma_f32_16x16x32_bf16 v[36:39], v[182:185], v[198:201], v[36:39]
	v_mfma_f32_16x16x32_bf16 v[16:19], v[174:177], v[206:209], v[16:19]
	v_mfma_f32_16x16x32_bf16 v[20:23], v[182:185], v[206:209], v[20:23]
	v_mfma_f32_16x16x32_bf16 v[0:3], v[174:177], v[214:217], v[0:3]
	v_mfma_f32_16x16x32_bf16 v[4:7], v[182:185], v[214:217], v[4:7]
	s_setprio 0
	s_barrier
	s_add_i32 s45, s45, 2
	s_add_u32 s43, s43, 0x100
	s_addc_u32 s44, s44, 0
	s_cmpk_gt_u32 s45, 0x55
	s_mov_b64 s[18:19], s[4:5]
	s_cbranch_scc0 .LBB0_1444
	s_and_b64 vcc, exec, s[10:11]
	s_cbranch_vccz .LBB0_1447
	s_barrier
